# v17: v16 + tile-boundary group alignment (leading group takes an extra barrier before its epilogue, trailing group on the loop-back edge, so both epilogues share one barrier interval)
# baseline (speedup 1.0000x reference)
; #define PG8_STAGE(bufoff, gbase, voff) do { _Pragma("unroll") for (int _i = 0; _i < 2; ++_i) \
;         __builtin_amdgcn_global_load_lds((const unsigned*)((const char*)(gbase) + (voff)[_i]), (LAS unsigned*)(lds + (bufoff) + ldsw + _i * 8192), 16, 0, 0); } while (0)
; #define PG8_WAIT_V(n) asm volatile("s_waitcnt vmcnt(" #n ")" ::: "memory")
; #define PG8_BAR __builtin_amdgcn_s_barrier()
; template <class Epi, class Ptrs>
; __device__ __forceinline__ void gemm_phase(LAS unsigned char* lds, const int K, const StaticOrder& S, const Ptrs& P, const Epi& E) {
;     ...
;     PG8_STAGE(PG8_SB(0, 0), cB, voffB); PG8_STAGE(PG8_SA(0, 0), cA, voffA); PG8_STAGE(PG8_SB(0, 1), cB + hstep, voffB); PG8_STAGE(PG8_SA(0, 1), cA + hstep, voffA);
;     if (wr == 1) PG8_BAR;
;     PG8_WAIT_V(4); PG8_BAR;
;     PG8_STAGE(PG8_SB(1, 0), cB + kstep, voffB); PG8_STAGE(PG8_SA(1, 0), cA + kstep, voffA); PG8_STAGE(PG8_SB(1, 1), cB + hstep + kstep, voffB);
;     PG8_WAIT_V(6); PG8_BAR;
;     for (;;) {
;         const bool has_next = S.next(ui + 1, nxt);
;         const char* nA = cA; const char* nB = cB; if (has_next) P.get(nxt, nA, nB);
.LBB0_120:
	s_add_u32 s4, s28, 0x35000000
	s_addc_u32 s5, s29, 0
	s_mov_b64 s[58:59], 0x80
	v_writelane_b32 v254, s4, 0
	v_lshl_add_u64 v[6:7], v[6:7], 0, s[58:59]
	s_waitcnt vmcnt(4)
	s_barrier
	v_writelane_b32 v254, s5, 1
	s_add_u32 s4, s28, 0x26000000
	s_addc_u32 s5, s29, 0
	s_add_u32 s42, s28, 0x32000000
	s_addc_u32 s43, s29, 0
	s_add_u32 s44, s28, 0x2000000
	s_addc_u32 s45, s29, 0
	s_add_u32 s48, s26, 0xc000000
	s_addc_u32 s49, s27, 0
	s_add_u32 s54, s28, 0x3e000000
	s_addc_u32 s55, s29, 0
	s_add_u32 s56, s28, 0xe000000
	s_addc_u32 s57, s29, 0
	s_lshl_b32 s1, s1, 5
	s_and_b32 s88, s1, 0x60
	s_add_i32 m0, s67, 0x18000
	v_writelane_b32 v254, s4, 2
	s_ashr_i32 s86, s3, 31
	s_ashr_i32 s87, s2, 31
	s_lshl_b32 s20, s0, 13
	s_lshl_b32 s1, s88, 7
	global_load_lds_dwordx4 v[6:7], off
	v_lshl_add_u64 v[4:5], v[4:5], 0, s[58:59]
	s_add_i32 m0, s67, 0x1a000
	s_add_i32 s89, s67, 0x8000
	s_add_i32 s90, s67, 0xa000
	v_writelane_b32 v254, s5, 3
	global_load_lds_dwordx4 v[4:5], off
	v_lshl_add_u64 v[2:3], v[2:3], 0, s[58:59]
	s_mov_b32 m0, s89
	s_add_u32 s4, s78, 0x40080
	global_load_lds_dwordx4 v[2:3], off
	v_lshl_add_u64 v[0:1], v[0:1], 0, s[58:59]
	s_mov_b32 m0, s90
	s_addc_u32 s5, s79, 0
	global_load_lds_dwordx4 v[0:1], off
	s_add_i32 m0, s67, 0x1c000
	v_lshl_add_u64 v[0:1], s[4:5], 0, v[134:135]
	global_load_lds_dwordx4 v[0:1], off
	v_lshl_add_u64 v[0:1], s[4:5], 0, v[138:139]
	s_add_i32 m0, s67, 0x1e000
	v_lshlrev_b32_e32 v2, 6, v208
	global_load_lds_dwordx4 v[0:1], off
	v_and_b32_e32 v0, 15, v208
	v_lshlrev_b32_e32 v1, 1, v130
	s_movk_i32 s4, 0x3c0
	v_lshlrev_b32_e32 v3, 2, v208
	v_and_or_b32 v2, v2, s4, v1
	v_and_b32_e32 v3, 32, v3
	v_cmp_eq_u32_e64 s[10:11], 0, v0
	v_lshl_or_b32 v129, s0, 6, v0
	v_lshl_or_b32 v0, v0, 6, v1
	v_lshlrev_b32_e32 v1, 8, v208
	v_bitop3_b32 v131, s1, v2, v3 bitop3:0xf6
	v_and_b32_e32 v1, 0x38000, v1
	v_lshlrev_b32_e32 v2, 11, v10
	v_or3_b32 v1, v8, v1, v2
	v_add_u32_e32 v142, v1, v9
	v_lshlrev_b32_e32 v1, 4, v11
	s_waitcnt vmcnt(6)
	v_and_b32_e32 v1, 0x78000, v1
	v_bitop3_b32 v0, v0, s20, v3 bitop3:0xde
	v_or3_b32 v1, v8, v1, v2
	s_add_i32 s91, 0, 0x10000
	s_add_i32 s92, 0, 0x14000
	v_or_b32_e32 v204, s88, v130
	v_mov_b32_e32 v143, v141
	v_add_u32_e32 v144, v1, v9
	v_mov_b32_e32 v145, v141
	v_mov_b64_e32 v[146:147], 0x2100
	v_mov_b64_e32 v[148:149], 0x20ff
	v_add_u32_e32 v205, s91, v131
	v_add_u32_e32 v206, 0, v0
	v_add_u32_e32 v207, s92, v131
	s_mov_b32 s60, 0xbfb8aa3b
	s_lshl_b32 s62, s0, 2
	s_mov_b32 s64, 0x3dd2d3e7
	s_mov_b32 s66, 0xc0135761
	s_mov_b32 s93, 0x600000
	s_mov_b32 s94, 0x900000
	s_mov_b32 s95, 0x1800000
	s_mov_b32 s96, 0x1b00000
	s_mov_b32 s97, 0x1e00000
	s_mov_b32 s98, 0x2100000
	s_mov_b32 s99, 0x40000
	s_mov_b32 s22, 0x48000
	s_mov_b32 s23, 0x50000
	s_nop 0
	s_nop 0
	s_nop 0
	s_nop 0
	s_nop 0
	s_nop 0
	s_nop 0
	s_nop 0
	s_nop 0
	s_nop 0
	s_nop 0
	s_nop 0
	s_nop 0
	s_nop 0
	s_nop 0
	s_nop 0
	s_nop 0
	s_nop 0
	s_nop 0
	s_nop 0
	s_nop 0
	s_nop 0
	s_nop 0
	s_nop 0
	s_nop 0
	s_nop 0
	s_nop 0
	s_nop 0
	s_nop 0
	s_nop 0
	s_nop 0
	s_nop 0
	s_nop 0
	s_nop 0
	s_nop 0
	s_nop 0
	s_nop 0
	s_nop 0
	s_nop 0
	s_nop 0
	s_nop 0
	s_nop 0
	s_nop 0
	s_nop 0
	s_nop 0
	s_nop 0
	s_nop 0
	s_nop 0
	s_nop 0
	s_nop 0
	s_nop 0
	s_nop 0
	s_mov_b32 s24, 0
	s_cmpk_lt_u32 s61, 0x100
	s_cbranch_scc1 .Lsprio_0
	s_setprio 1

; template <class Epi, class Ptrs>
; __device__ __forceinline__ void gemm_phase(LAS unsigned char* lds, const int K, const StaticOrder& S, const Ptrs& P, const Epi& E) {
;     ...
;     for (;;) {
;         const bool has_next = S.next(ui + 1, nxt);
;         const char* nA = cA; const char* nB = cB; if (has_next) P.get(nxt, nA, nB);
.LBB0_121:
	s_and_b64 vcc, exec, s[4:5]
	s_mov_b32 s74, s68
	s_mov_b32 s76, s70
	s_mov_b64 s[6:7], s[0:1]
	s_mov_b64 s[78:79], s[72:73]
	s_cbranch_vccnz .LBB0_192
	s_cmpk_lt_u32 s61, 0x100
	s_cbranch_scc1 .LBB0_122
	s_barrier

; #define PG8_STAGE(bufoff, gbase, voff) do { _Pragma("unroll") for (int _i = 0; _i < 2; ++_i) \
;         __builtin_amdgcn_global_load_lds((const unsigned*)((const char*)(gbase) + (voff)[_i]), (LAS unsigned*)(lds + (bufoff) + ldsw + _i * 8192), 16, 0, 0); } while (0)
; #define PG8_LDA(dst, b, h) do { _Pragma("unroll") for (int m = 0; m < 4; ++m) _Pragma("unroll") for (int k = 0; k < 2; ++k) dst[m][k] = *(const LAS bf16x8*)(lds + PG8_SA(b, h) + aoff + m * 2048 + k * 1024); } while (0)
; #define PG8_LDB(dst, b, h) do { _Pragma("unroll") for (int n = 0; n < 2; ++n) _Pragma("unroll") for (int k = 0; k < 2; ++k) dst[n][k] = *(const LAS bf16x8*)(lds + PG8_SB(b, h) + boff + n * 2048 + k * 1024); } while (0)
; #define PG8_MMA(ai, bj, At, Bt) do { __builtin_amdgcn_s_setprio(1); _Pragma("unroll") for (int m = 0; m < 4; ++m) _Pragma("unroll") for (int n = 0; n < 2; ++n) _Pragma("unroll") for (int k = 0; k < 2; ++k) \
;         acc[ai][bj][m][n] = __builtin_amdgcn_mfma_f32_16x16x32_bf16(Bt[n][k], At[m][k], acc[ai][bj][m][n], 0, 0, 0); __builtin_amdgcn_s_setprio(0); } while (0)
; #define PG8_WAIT_V(n) asm volatile("s_waitcnt vmcnt(" #n ")" ::: "memory")
; #define PG8_WAIT_L(n) asm volatile("s_waitcnt lgkmcnt(" #n ")" ::: "memory")
; template <class Epi, class Ptrs>
; __device__ __forceinline__ void gemm_phase(LAS unsigned char* lds, const int K, const StaticOrder& S, const Ptrs& P, const Epi& E) {
;     ...
;             PG8_LDB(B0, 0, 0); PG8_SCHED; PG8_LDA(At, 0, 0); PG8_STAGE(PG8_SA(1, 1), a1 + hstep, voffA);
;             PG8_WAIT_L(8); PG8_BAR; PG8_WAIT_L(0); PG8_MMA(0, 0, At, B0); PG8_BAR; PG8_SCHED;
;             PG8_LDB(B1, 0, 1); PG8_STAGE(PG8_SB(0, 0), b2, voffB);
;             PG8_BAR; PG8_WAIT_L(0); PG8_MMA(0, 1, At, B1); PG8_BAR;
;             PG8_LDA(At, 0, 1); PG8_STAGE(PG8_SA(0, 0), a2, voffA);
;             PG8_BAR; PG8_WAIT_L(0); PG8_MMA(1, 0, At, B0); PG8_BAR; PG8_SCHED;
;             PG8_STAGE(PG8_SB(0, 1), b2 + hstep, voffB);
;             PG8_WAIT_V(6); PG8_BAR; PG8_MMA(1, 1, At, B1); PG8_BAR;
;             PG8_LDB(B0, 1, 0); PG8_SCHED; PG8_LDA(At, 1, 0); PG8_STAGE(PG8_SA(0, 1), a2 + hstep, voffA);
;             PG8_WAIT_L(8); PG8_BAR; PG8_WAIT_L(0); PG8_MMA(0, 0, At, B0); PG8_BAR; PG8_SCHED;
;             PG8_LDB(B1, 1, 1); PG8_STAGE(PG8_SB(1, 0), b3, voffB);
;             PG8_BAR; PG8_WAIT_L(0); PG8_MMA(0, 1, At, B1); PG8_BAR;
.LBB0_127:
	ds_read_b128 v[150:153], v205
	ds_read_b128 v[154:157], v205 offset:1024
	ds_read_b128 v[158:161], v205 offset:2048
	ds_read_b128 v[162:165], v205 offset:3072
	s_add_u32 s69, s6, 0xfffc0080
	s_addc_u32 s71, s7, -1
	s_cmp_eq_u32 s63, 12
	s_cselect_b32 s81, s1, s71
	s_cselect_b32 s80, s0, s69
	s_cselect_b32 s79, s73, s25
	s_cselect_b32 s78, s72, s20
	s_add_i32 m0, s67, 0xc000
	ds_read_b128 v[166:169], v206
	ds_read_b128 v[170:173], v206 offset:1024
	ds_read_b128 v[174:177], v206 offset:2048
	ds_read_b128 v[178:181], v206 offset:3072
	ds_read_b128 v[182:185], v206 offset:4096
	ds_read_b128 v[186:189], v206 offset:5120
	ds_read_b128 v[190:193], v206 offset:6144
	ds_read_b128 v[194:197], v206 offset:7168
	global_load_lds_dwordx4 v142, s[6:7]
	s_add_i32 m0, s67, 0xe000
	s_nop 0
	global_load_lds_dwordx4 v144, s[6:7]
	s_waitcnt lgkmcnt(8)
	s_barrier
	s_waitcnt lgkmcnt(0)
	v_mfma_f32_16x16x32_bf16 v[120:123], v[150:153], v[166:169], v[120:123]
	v_mfma_f32_16x16x32_bf16 v[120:123], v[154:157], v[170:173], v[120:123]
	v_mfma_f32_16x16x32_bf16 v[116:119], v[162:165], v[170:173], v[116:119]
	v_mfma_f32_16x16x32_bf16 v[116:119], v[158:161], v[166:169], v[116:119]
	v_mfma_f32_16x16x32_bf16 v[100:103], v[158:161], v[174:177], v[100:103]
	v_mfma_f32_16x16x32_bf16 v[100:103], v[162:165], v[178:181], v[100:103]
	v_mfma_f32_16x16x32_bf16 v[104:107], v[154:157], v[178:181], v[104:107]
	v_mfma_f32_16x16x32_bf16 v[104:107], v[150:153], v[174:177], v[104:107]
	v_mfma_f32_16x16x32_bf16 v[88:91], v[150:153], v[182:185], v[88:91]
	v_mfma_f32_16x16x32_bf16 v[88:91], v[154:157], v[186:189], v[88:91]
	v_mfma_f32_16x16x32_bf16 v[84:87], v[162:165], v[186:189], v[84:87]
	v_mfma_f32_16x16x32_bf16 v[84:87], v[158:161], v[182:185], v[84:87]
	v_mfma_f32_16x16x32_bf16 v[68:71], v[158:161], v[190:193], v[68:71]
	v_mfma_f32_16x16x32_bf16 v[68:71], v[162:165], v[194:197], v[68:71]
	v_mfma_f32_16x16x32_bf16 v[72:75], v[154:157], v[194:197], v[72:75]
	v_mfma_f32_16x16x32_bf16 v[72:75], v[150:153], v[190:193], v[72:75]
	s_barrier
	s_add_i32 s69, s91, s65
	s_add_u32 s100, s78, 0x80
	s_addc_u32 s101, s79, 0
	s_mov_b32 m0, s69
	ds_read_b128 v[198:201], v207
	ds_read_b128 v[210:213], v207 offset:1024
	ds_read_b128 v[214:217], v207 offset:2048
	ds_read_b128 v[218:221], v207 offset:3072
	global_load_lds_dwordx4 v134, s[78:79]
	s_add_i32 m0, s69, 0x2000
	s_nop 0
	global_load_lds_dwordx4 v138, s[78:79]
	s_barrier
	s_waitcnt lgkmcnt(0)
	v_mfma_f32_16x16x32_bf16 v[124:127], v[198:201], v[166:169], v[124:127]
	v_mfma_f32_16x16x32_bf16 v[124:127], v[210:213], v[170:173], v[124:127]
	v_mfma_f32_16x16x32_bf16 v[112:115], v[218:221], v[170:173], v[112:115]
	v_mfma_f32_16x16x32_bf16 v[112:115], v[214:217], v[166:169], v[112:115]
	v_mfma_f32_16x16x32_bf16 v[96:99], v[214:217], v[174:177], v[96:99]
	v_mfma_f32_16x16x32_bf16 v[96:99], v[218:221], v[178:181], v[96:99]
	v_mfma_f32_16x16x32_bf16 v[108:111], v[210:213], v[178:181], v[108:111]
	v_mfma_f32_16x16x32_bf16 v[108:111], v[198:201], v[174:177], v[108:111]
	v_mfma_f32_16x16x32_bf16 v[92:95], v[198:201], v[182:185], v[92:95]
	v_mfma_f32_16x16x32_bf16 v[92:95], v[210:213], v[186:189], v[92:95]
	v_mfma_f32_16x16x32_bf16 v[80:83], v[218:221], v[186:189], v[80:83]
	v_mfma_f32_16x16x32_bf16 v[80:83], v[214:217], v[182:185], v[80:83]
	v_mfma_f32_16x16x32_bf16 v[64:67], v[214:217], v[190:193], v[64:67]
	v_mfma_f32_16x16x32_bf16 v[64:67], v[218:221], v[194:197], v[64:67]
	v_mfma_f32_16x16x32_bf16 v[76:79], v[210:213], v[194:197], v[76:79]
	v_mfma_f32_16x16x32_bf16 v[76:79], v[198:201], v[190:193], v[76:79]
	s_barrier
	s_mov_b32 m0, s67
	ds_read_b128 v[166:169], v206 offset:16384
	ds_read_b128 v[170:173], v206 offset:17408
	ds_read_b128 v[174:177], v206 offset:18432
	ds_read_b128 v[178:181], v206 offset:19456
	ds_read_b128 v[182:185], v206 offset:20480
	ds_read_b128 v[186:189], v206 offset:21504
	ds_read_b128 v[190:193], v206 offset:22528
	ds_read_b128 v[194:197], v206 offset:23552
	global_load_lds_dwordx4 v132, s[80:81]
	s_mov_b32 m0, s75
	s_nop 0
	global_load_lds_dwordx4 v136, s[80:81]
	s_barrier
	s_waitcnt lgkmcnt(0)
	v_mfma_f32_16x16x32_bf16 v[56:59], v[150:153], v[166:169], v[56:59]
	v_mfma_f32_16x16x32_bf16 v[56:59], v[154:157], v[170:173], v[56:59]
	v_mfma_f32_16x16x32_bf16 v[52:55], v[162:165], v[170:173], v[52:55]
	v_mfma_f32_16x16x32_bf16 v[52:55], v[158:161], v[166:169], v[52:55]
	v_mfma_f32_16x16x32_bf16 v[36:39], v[158:161], v[174:177], v[36:39]
	v_mfma_f32_16x16x32_bf16 v[36:39], v[162:165], v[178:181], v[36:39]
	v_mfma_f32_16x16x32_bf16 v[40:43], v[154:157], v[178:181], v[40:43]
	v_mfma_f32_16x16x32_bf16 v[40:43], v[150:153], v[174:177], v[40:43]
	v_mfma_f32_16x16x32_bf16 v[24:27], v[150:153], v[182:185], v[24:27]
	v_mfma_f32_16x16x32_bf16 v[24:27], v[154:157], v[186:189], v[24:27]
	v_mfma_f32_16x16x32_bf16 v[20:23], v[162:165], v[186:189], v[20:23]
	v_mfma_f32_16x16x32_bf16 v[20:23], v[158:161], v[182:185], v[20:23]
	v_mfma_f32_16x16x32_bf16 v[4:7], v[158:161], v[190:193], v[4:7]
	v_mfma_f32_16x16x32_bf16 v[4:7], v[162:165], v[194:197], v[4:7]
	v_mfma_f32_16x16x32_bf16 v[8:11], v[154:157], v[194:197], v[8:11]
	v_mfma_f32_16x16x32_bf16 v[8:11], v[150:153], v[190:193], v[8:11]
	s_barrier
	s_add_u32 s82, s78, 0x40000
	s_addc_u32 s83, s79, 0
	s_add_i32 s69, s92, s65
	s_mov_b32 m0, s69
	s_nop 0
	global_load_lds_dwordx4 v134, s[82:83]
	s_add_i32 m0, s69, 0x2000
	s_nop 0
	global_load_lds_dwordx4 v138, s[82:83]
	s_waitcnt vmcnt(6)
	s_barrier
; #define PG8_STAGE(bufoff, gbase, voff) do { _Pragma("unroll") for (int _i = 0; _i < 2; ++_i) \
;         __builtin_amdgcn_global_load_lds((const unsigned*)((const char*)(gbase) + (voff)[_i]), (LAS unsigned*)(lds + (bufoff) + ldsw + _i * 8192), 16, 0, 0); } while (0)
; #define PG8_LDA(dst, b, h) do { _Pragma("unroll") for (int m = 0; m < 4; ++m) _Pragma("unroll") for (int k = 0; k < 2; ++k) dst[m][k] = *(const LAS bf16x8*)(lds + PG8_SA(b, h) + aoff + m * 2048 + k * 1024); } while (0)
; #define PG8_LDB(dst, b, h) do { _Pragma("unroll") for (int n = 0; n < 2; ++n) _Pragma("unroll") for (int k = 0; k < 2; ++k) dst[n][k] = *(const LAS bf16x8*)(lds + PG8_SB(b, h) + boff + n * 2048 + k * 1024); } while (0)
; #define PG8_MMA(ai, bj, At, Bt) do { __builtin_amdgcn_s_setprio(1); _Pragma("unroll") for (int m = 0; m < 4; ++m) _Pragma("unroll") for (int n = 0; n < 2; ++n) _Pragma("unroll") for (int k = 0; k < 2; ++k) \
;         acc[ai][bj][m][n] = __builtin_amdgcn_mfma_f32_16x16x32_bf16(Bt[n][k], At[m][k], acc[ai][bj][m][n], 0, 0, 0); __builtin_amdgcn_s_setprio(0); } while (0)
; #define PG8_WAIT_V(n) asm volatile("s_waitcnt vmcnt(" #n ")" ::: "memory")
; #define PG8_WAIT_L(n) asm volatile("s_waitcnt lgkmcnt(" #n ")" ::: "memory")
; #define PG8_BAR __builtin_amdgcn_s_barrier()
; #define PG8_SCHED __builtin_amdgcn_sched_barrier(0)
; template <class Epi, class Ptrs>
; __device__ __forceinline__ void gemm_phase(LAS unsigned char* lds, const int K, const StaticOrder& S, const Ptrs& P, const Epi& E) {
;     ...
;             PG8_WAIT_V(6); PG8_BAR; PG8_MMA(1, 1, At, B1); PG8_BAR;
;             PG8_LDB(B0, 1, 0); PG8_SCHED; PG8_LDA(At, 1, 0); PG8_STAGE(PG8_SA(0, 1), a2 + hstep, voffA);
;             PG8_WAIT_L(8); PG8_BAR; PG8_WAIT_L(0); PG8_MMA(0, 0, At, B0); PG8_BAR; PG8_SCHED;
;             PG8_LDB(B1, 1, 1); PG8_STAGE(PG8_SB(1, 0), b3, voffB);
;             PG8_BAR; PG8_WAIT_L(0); PG8_MMA(0, 1, At, B1); PG8_BAR;
;             PG8_LDA(At, 1, 1); PG8_STAGE(PG8_SA(1, 0), a3, voffA);
;             PG8_BAR; PG8_WAIT_L(0); PG8_MMA(1, 0, At, B0); PG8_BAR; PG8_SCHED;
;             PG8_STAGE(PG8_SB(1, 1), b3 + hstep, voffB);
;             PG8_WAIT_V(6); PG8_BAR; PG8_MMA(1, 1, At, B1); PG8_BAR;
	v_mfma_f32_16x16x32_bf16 v[60:63], v[198:201], v[166:169], v[60:63]
	v_mfma_f32_16x16x32_bf16 v[60:63], v[210:213], v[170:173], v[60:63]
	v_mfma_f32_16x16x32_bf16 v[48:51], v[218:221], v[170:173], v[48:51]
	v_mfma_f32_16x16x32_bf16 v[48:51], v[214:217], v[166:169], v[48:51]
	v_mfma_f32_16x16x32_bf16 v[32:35], v[214:217], v[174:177], v[32:35]
	v_mfma_f32_16x16x32_bf16 v[32:35], v[218:221], v[178:181], v[32:35]
	v_mfma_f32_16x16x32_bf16 v[44:47], v[210:213], v[178:181], v[44:47]
	v_mfma_f32_16x16x32_bf16 v[44:47], v[198:201], v[174:177], v[44:47]
	v_mfma_f32_16x16x32_bf16 v[28:31], v[198:201], v[182:185], v[28:31]
	v_mfma_f32_16x16x32_bf16 v[28:31], v[210:213], v[186:189], v[28:31]
	v_mfma_f32_16x16x32_bf16 v[16:19], v[218:221], v[186:189], v[16:19]
	v_mfma_f32_16x16x32_bf16 v[16:19], v[214:217], v[182:185], v[16:19]
	v_mfma_f32_16x16x32_bf16 v[0:3], v[214:217], v[190:193], v[0:3]
	v_mfma_f32_16x16x32_bf16 v[0:3], v[218:221], v[194:197], v[0:3]
	v_mfma_f32_16x16x32_bf16 v[12:15], v[210:213], v[194:197], v[12:15]
	v_mfma_f32_16x16x32_bf16 v[12:15], v[198:201], v[190:193], v[12:15]
	s_barrier
	s_add_i32 s69, 0, 0x18000
	ds_read_b128 v[150:153], v252
	ds_read_b128 v[154:157], v252 offset:1024
	ds_read_b128 v[158:161], v252 offset:2048
	ds_read_b128 v[162:165], v252 offset:3072
	s_add_u32 s80, s80, 0x40000
	s_addc_u32 s81, s81, 0
	s_mov_b32 m0, s77
	ds_read_b128 v[166:169], v206 offset:32768
	ds_read_b128 v[170:173], v206 offset:33792
	ds_read_b128 v[174:177], v206 offset:34816
	ds_read_b128 v[178:181], v206 offset:35840
	ds_read_b128 v[182:185], v206 offset:36864
	ds_read_b128 v[186:189], v206 offset:37888
	ds_read_b128 v[190:193], v206 offset:38912
	ds_read_b128 v[194:197], v206 offset:39936
	global_load_lds_dwordx4 v132, s[80:81]
	s_mov_b32 m0, s85
	s_nop 0
	global_load_lds_dwordx4 v136, s[80:81]
	s_waitcnt lgkmcnt(8)
	s_barrier
	s_waitcnt lgkmcnt(0)
	v_mfma_f32_16x16x32_bf16 v[120:123], v[150:153], v[166:169], v[120:123]
	v_mfma_f32_16x16x32_bf16 v[120:123], v[154:157], v[170:173], v[120:123]
	v_mfma_f32_16x16x32_bf16 v[116:119], v[162:165], v[170:173], v[116:119]
	v_mfma_f32_16x16x32_bf16 v[116:119], v[158:161], v[166:169], v[116:119]
	v_mfma_f32_16x16x32_bf16 v[100:103], v[158:161], v[174:177], v[100:103]
	v_mfma_f32_16x16x32_bf16 v[100:103], v[162:165], v[178:181], v[100:103]
	v_mfma_f32_16x16x32_bf16 v[104:107], v[154:157], v[178:181], v[104:107]
	v_mfma_f32_16x16x32_bf16 v[104:107], v[150:153], v[174:177], v[104:107]
	v_mfma_f32_16x16x32_bf16 v[88:91], v[150:153], v[182:185], v[88:91]
	v_mfma_f32_16x16x32_bf16 v[88:91], v[154:157], v[186:189], v[88:91]
	v_mfma_f32_16x16x32_bf16 v[84:87], v[162:165], v[186:189], v[84:87]
	v_mfma_f32_16x16x32_bf16 v[84:87], v[158:161], v[182:185], v[84:87]
	v_mfma_f32_16x16x32_bf16 v[68:71], v[158:161], v[190:193], v[68:71]
	v_mfma_f32_16x16x32_bf16 v[68:71], v[162:165], v[194:197], v[68:71]
	v_mfma_f32_16x16x32_bf16 v[72:75], v[154:157], v[194:197], v[72:75]
	v_mfma_f32_16x16x32_bf16 v[72:75], v[150:153], v[190:193], v[72:75]
	s_barrier
	s_add_i32 s71, 0, 0x1c000
	s_add_i32 s69, s69, s65
	s_mov_b32 m0, s69
	ds_read_b128 v[198:201], v253
	ds_read_b128 v[210:213], v253 offset:1024
	ds_read_b128 v[214:217], v253 offset:2048
	ds_read_b128 v[218:221], v253 offset:3072
	global_load_lds_dwordx4 v134, s[100:101]
	s_add_i32 m0, s69, 0x2000
	s_nop 0
	global_load_lds_dwordx4 v138, s[100:101]
	s_barrier
	s_waitcnt lgkmcnt(0)
	v_mfma_f32_16x16x32_bf16 v[124:127], v[198:201], v[166:169], v[124:127]
	v_mfma_f32_16x16x32_bf16 v[124:127], v[210:213], v[170:173], v[124:127]
	v_mfma_f32_16x16x32_bf16 v[112:115], v[218:221], v[170:173], v[112:115]
	v_mfma_f32_16x16x32_bf16 v[112:115], v[214:217], v[166:169], v[112:115]
	v_mfma_f32_16x16x32_bf16 v[96:99], v[214:217], v[174:177], v[96:99]
	v_mfma_f32_16x16x32_bf16 v[96:99], v[218:221], v[178:181], v[96:99]
	v_mfma_f32_16x16x32_bf16 v[108:111], v[210:213], v[178:181], v[108:111]
	v_mfma_f32_16x16x32_bf16 v[108:111], v[198:201], v[174:177], v[108:111]
	v_mfma_f32_16x16x32_bf16 v[92:95], v[198:201], v[182:185], v[92:95]
	v_mfma_f32_16x16x32_bf16 v[92:95], v[210:213], v[186:189], v[92:95]
	v_mfma_f32_16x16x32_bf16 v[80:83], v[218:221], v[186:189], v[80:83]
	v_mfma_f32_16x16x32_bf16 v[80:83], v[214:217], v[182:185], v[80:83]
	v_mfma_f32_16x16x32_bf16 v[64:67], v[214:217], v[190:193], v[64:67]
	v_mfma_f32_16x16x32_bf16 v[64:67], v[218:221], v[194:197], v[64:67]
	v_mfma_f32_16x16x32_bf16 v[76:79], v[210:213], v[194:197], v[76:79]
	v_mfma_f32_16x16x32_bf16 v[76:79], v[198:201], v[190:193], v[76:79]
	s_barrier
; #define PG8_WAIT_V(n) asm volatile("s_waitcnt vmcnt(" #n ")" ::: "memory")
; template <class Epi, class Ptrs>
; __device__ __forceinline__ void gemm_phase(LAS unsigned char* lds, const int K, const StaticOrder& S, const Ptrs& P, const Epi& E) {
;     ...
;             PG8_LDA(At, 1, 1); PG8_STAGE(PG8_SA(1, 0), a3, voffA);
;             PG8_BAR; PG8_WAIT_L(0); PG8_MMA(1, 0, At, B0); PG8_BAR; PG8_SCHED;
;             PG8_STAGE(PG8_SB(1, 1), b3 + hstep, voffB);
;             PG8_WAIT_V(6); PG8_BAR; PG8_MMA(1, 1, At, B1); PG8_BAR;
;         }
;         E(acc, cur, ui, wr, wc, fr, fq);
;     __device__ __forceinline__ void operator()(const f32x4 (&acc)[2][2][4][2], const Unit& u, int ui, int wr, int wc, int fr, int fq) const {
;         const int pn = u.pn;
;         if (pn < 8) {
;             bf16_t* base = (bf16_t*)(ws + WS_U) + (size_t)(u.pm * 256 + wr * 64 + fr) * DM + pn * 128 + wc * 32 + 8 * fq;
; #pragma unroll
;             for (int ai = 0; ai < 2; ++ai)
; #pragma unroll
;                 for (int m = 0; m < 4; ++m) {
;                     const f32x4 g0 = g1_4(acc[ai][0][m][0], acc[ai][1][m][0]), g1 = g1_4(acc[ai][0][m][1], acc[ai][1][m][1]);
;                     *(u32x4*)(base + (size_t)(ai * 128 + m * 16) * DM) = pack8(g0, g1); }
;             return; }
;         if (pn >= 17 && pn < 21) {
;             bf16_t* base = (bf16_t*)(dout + DO_GVT) + (size_t)((pn - 17) * 256 + wr * 64 + fr) * MTOK + u.pm * 256 + wc * 32 + 8 * fq;
;             float* pp = (float*)(ws + WS_PART) + (size_t)(u.pm * 256 + wc * 32 + 8 * fq) * 8 + (pn - 17) * 2 + wr;
; #pragma unroll
;             for (int bj = 0; bj < 2; ++bj) { f32x4 sq0 = {0.f, 0.f, 0.f, 0.f}, sq1 = {0.f, 0.f, 0.f, 0.f};
; #pragma unroll
;                 for (int ai = 0; ai < 2; ++ai)
; #pragma unroll
;                     for (int m = 0; m < 4; ++m) { const f32x4 g0 = gelu4(acc[ai][bj][m][0]), g1 = gelu4(acc[ai][bj][m][1]);
;                         sq0 += g0 * g0; sq1 += g1 * g1;
;                         *(u32x4*)(base + (size_t)(ai * 128 + m * 16) * MTOK + bj * 128) = pack8(g0, g1); }
; #pragma unroll
;                 for (int j = 0; j < 4; ++j) { const float t0 = row16_sum(sq0[j]), t1 = row16_sum(sq1[j]); if (fr == 0) { pp[(size_t)(bj * 128 + j) * 8] = t0; pp[(size_t)(bj * 128 + 4 + j) * 8] = t1; } } }
;             return; }
;         bf16_t* base; size_t ld; int row0, col0, act;
	s_mov_b32 m0, s89
	s_add_u32 s100, s80, 0xfffc0080
	s_addc_u32 s101, s81, -1
	ds_read_b128 v[166:169], v206 offset:49152
	ds_read_b128 v[170:173], v206 offset:50176
	ds_read_b128 v[174:177], v206 offset:51200
	ds_read_b128 v[178:181], v206 offset:52224
	ds_read_b128 v[182:185], v206 offset:53248
	ds_read_b128 v[186:189], v206 offset:54272
	ds_read_b128 v[190:193], v206 offset:55296
	ds_read_b128 v[194:197], v206 offset:56320
	global_load_lds_dwordx4 v132, s[100:101]
	s_mov_b32 m0, s90
	s_nop 0
	global_load_lds_dwordx4 v136, s[100:101]
	s_barrier
	s_waitcnt lgkmcnt(0)
	v_mfma_f32_16x16x32_bf16 v[56:59], v[150:153], v[166:169], v[56:59]
	v_mfma_f32_16x16x32_bf16 v[56:59], v[154:157], v[170:173], v[56:59]
	v_mfma_f32_16x16x32_bf16 v[52:55], v[162:165], v[170:173], v[52:55]
	v_mfma_f32_16x16x32_bf16 v[52:55], v[158:161], v[166:169], v[52:55]
	v_mfma_f32_16x16x32_bf16 v[36:39], v[158:161], v[174:177], v[36:39]
	v_mfma_f32_16x16x32_bf16 v[36:39], v[162:165], v[178:181], v[36:39]
	v_mfma_f32_16x16x32_bf16 v[40:43], v[154:157], v[178:181], v[40:43]
	v_mfma_f32_16x16x32_bf16 v[40:43], v[150:153], v[174:177], v[40:43]
	v_mfma_f32_16x16x32_bf16 v[24:27], v[150:153], v[182:185], v[24:27]
	v_mfma_f32_16x16x32_bf16 v[24:27], v[154:157], v[186:189], v[24:27]
	v_mfma_f32_16x16x32_bf16 v[20:23], v[162:165], v[186:189], v[20:23]
	v_mfma_f32_16x16x32_bf16 v[20:23], v[158:161], v[182:185], v[20:23]
	v_mfma_f32_16x16x32_bf16 v[4:7], v[158:161], v[190:193], v[4:7]
	v_mfma_f32_16x16x32_bf16 v[4:7], v[162:165], v[194:197], v[4:7]
	v_mfma_f32_16x16x32_bf16 v[8:11], v[154:157], v[194:197], v[8:11]
	v_mfma_f32_16x16x32_bf16 v[8:11], v[150:153], v[190:193], v[8:11]
	s_barrier
	s_add_u32 s78, s78, 0x40080
	s_addc_u32 s79, s79, 0
	s_add_i32 s69, s71, s65
	s_mov_b32 m0, s69
	s_nop 0
	global_load_lds_dwordx4 v134, s[78:79]
	s_add_i32 m0, s69, 0x2000
	s_nop 0
	global_load_lds_dwordx4 v138, s[78:79]
	s_waitcnt vmcnt(6)
	s_barrier
	v_mfma_f32_16x16x32_bf16 v[60:63], v[198:201], v[166:169], v[60:63]
	v_mfma_f32_16x16x32_bf16 v[60:63], v[210:213], v[170:173], v[60:63]
	v_mfma_f32_16x16x32_bf16 v[48:51], v[218:221], v[170:173], v[48:51]
	v_mfma_f32_16x16x32_bf16 v[48:51], v[214:217], v[166:169], v[48:51]
	v_mfma_f32_16x16x32_bf16 v[32:35], v[214:217], v[174:177], v[32:35]
	v_mfma_f32_16x16x32_bf16 v[32:35], v[218:221], v[178:181], v[32:35]
	v_mfma_f32_16x16x32_bf16 v[44:47], v[210:213], v[178:181], v[44:47]
	v_mfma_f32_16x16x32_bf16 v[44:47], v[198:201], v[174:177], v[44:47]
	v_mfma_f32_16x16x32_bf16 v[28:31], v[198:201], v[182:185], v[28:31]
	v_mfma_f32_16x16x32_bf16 v[28:31], v[210:213], v[186:189], v[28:31]
	v_mfma_f32_16x16x32_bf16 v[16:19], v[218:221], v[186:189], v[16:19]
	v_mfma_f32_16x16x32_bf16 v[16:19], v[214:217], v[182:185], v[16:19]
	v_mfma_f32_16x16x32_bf16 v[0:3], v[214:217], v[190:193], v[0:3]
	v_mfma_f32_16x16x32_bf16 v[0:3], v[218:221], v[194:197], v[0:3]
	v_mfma_f32_16x16x32_bf16 v[12:15], v[210:213], v[194:197], v[12:15]
	v_mfma_f32_16x16x32_bf16 v[12:15], v[198:201], v[190:193], v[12:15]
	s_barrier
	s_add_i32 s63, s63, 2
	s_add_u32 s6, s6, 0x100
	s_addc_u32 s7, s7, 0
	s_add_u32 s20, s20, 0x100
	s_addc_u32 s25, s25, 0
	s_cmp_gt_u32 s63, 13
	s_cbranch_scc0 .LBB0_127
	s_cmpk_lt_u32 s61, 0x100
	s_cbranch_scc0 .Ltsync_a0
	s_barrier
.Ltsync_a0:
	s_cmp_gt_i32 s74, 7
	s_mov_b64 s[6:7], -1
	s_cbranch_scc0 .LBB0_188
	s_sub_i32 s25, s74, 17
	s_cmp_gt_u32 s25, 3
	s_cbranch_scc0 .LBB0_170
	s_lshl_b32 s69, s76, 8
	s_cmp_gt_u32 s74, 11
	s_cbranch_scc0 .LBB0_135
	s_cmp_eq_u32 s74, 12
	s_mov_b64 s[6:7], 0
	s_cbranch_scc1 .LBB0_134
	s_cmp_gt_u32 s74, 16
	s_cbranch_scc1 .LBB0_191
	s_lshl_b32 s20, s74, 8
	v_readlane_b32 s80, v254, 2
	s_addk_i32 s20, 0xf300
	s_mov_b64 s[78:79], 0x400
	s_mov_b64 s[82:83], -1
	s_mov_b32 s63, s69
	v_readlane_b32 s81, v254, 3
	s_andn2_b64 vcc, exec, s[6:7]
	s_cbranch_vccz .LBB0_136
	s_branch .LBB0_137

; #define PG8_WAIT_V(n) asm volatile("s_waitcnt vmcnt(" #n ")" ::: "memory")
; #define PG8_BAR __builtin_amdgcn_s_barrier()
; __device__ __forceinline__ unsigned xb_add(unsigned* p, unsigned v) { return __hip_atomic_fetch_add(p, v, __ATOMIC_RELAXED, __HIP_MEMORY_SCOPE_AGENT); }
; template <class Epi, class Ptrs>
; __device__ __forceinline__ void gemm_phase(LAS unsigned char* lds, const int K, const StaticOrder& S, const Ptrs& P, const Epi& E) {
;     ...
;     PG8_WAIT_V(0);
;     if (wr == 0) PG8_BAR;
;     PG8_BAR;
; __device__ __forceinline__ void xcd_barrier(const XcdBarrier& b) {
;     asm volatile("s_waitcnt vmcnt(0)" ::: "memory");
;     __syncthreads();
;     if (threadIdx.x == 0) {
;         unsigned* bar = b.bar;
;         __builtin_amdgcn_s_waitcnt(0);
;         unsigned nloc = b.st[0], nx = b.st[1];
;         if (nloc == 0u) { xcd_barrier_complete(bar, b.x, nloc, nx); b.st[0] = nloc; b.st[1] = nx; }
;         const unsigned old = xb_add(&bar[XB_XSUB(b.x)], 1u);
.LBB0_192:
	s_waitcnt vmcnt(0)
	s_setprio 0
	s_cmpk_gt_u32 s61, 0xff
	s_cbranch_scc1 .LBB0_194
.LBB0_194:
	s_barrier
.LBB0_195:
	s_nop 0
	s_nop 0
	s_nop 0
	s_nop 0
	s_nop 0
	s_nop 0
	s_nop 0
	s_nop 0
	s_nop 0
	s_nop 0
	s_nop 0
	s_nop 0
	s_nop 0
	s_nop 0
	s_nop 0
	s_nop 0
	s_nop 0
	s_nop 0
	s_nop 0
	s_nop 0
	s_nop 0
	s_nop 0
	s_nop 0
	s_nop 0
	s_nop 0
	s_nop 0
	s_nop 0
	s_nop 0
	s_nop 0
	s_nop 0
	s_nop 0
	s_nop 0
	s_nop 0
	s_nop 0
	s_nop 0
	s_nop 0
	s_nop 0
	s_nop 0
	s_nop 0
	s_nop 0
	s_nop 0
	s_nop 0
	s_nop 0
	s_nop 0
	s_nop 0
	s_nop 0
	s_nop 0
	s_cmp_gt_i32 s31, 2
	s_cselect_b64 s[0:1], -1, 0
	s_and_b64 s[4:5], s[18:19], s[0:1]
	s_andn2_b64 vcc, exec, s[4:5]
	s_cbranch_vccnz .LBB0_245
	s_waitcnt vmcnt(0)
	s_waitcnt vmcnt(0) lgkmcnt(0)
	s_barrier
	s_and_saveexec_b64 s[4:5], s[8:9]
	s_cbranch_execz .LBB0_244
	s_add_i32 s6, 0, 0x25ff0
	v_mov_b32_e32 v0, s6
	s_waitcnt vmcnt(0) expcnt(0) lgkmcnt(0)
	ds_read_b32 v2, v0
	s_add_i32 s6, 0, 0x25ff4
	v_mov_b32_e32 v0, s6
	ds_read_b32 v0, v0
	s_waitcnt lgkmcnt(1)
	v_cmp_ne_u32_e32 vcc, 0, v2
	s_cbranch_vccnz .LBB0_212
	s_load_dwordx2 s[18:19], s[52:53], 0x4
	s_add_u32 s6, s28, 0x3e800200
	s_addc_u32 s7, s29, 0
	s_add_u32 s10, s28, 0x3e800400
	s_addc_u32 s11, s29, 0
	s_waitcnt lgkmcnt(0)
	s_mul_i32 s76, s18, s3
	s_add_u32 s18, s28, 0x3e800500
	s_mul_i32 s76, s76, s19
	s_addc_u32 s19, s29, 0
	s_add_u32 s20, s28, 0x3e800600
	s_addc_u32 s21, s29, 0
	s_add_u32 s22, s28, 0x3e800700
	s_addc_u32 s23, s29, 0
	s_add_u32 s24, s28, 0x3e800800
	s_addc_u32 s25, s29, 0
	s_add_u32 s42, s28, 0x3e800900
	s_addc_u32 s43, s29, 0
	s_add_u32 s44, s28, 0x3e800a00
	s_addc_u32 s45, s29, 0
	s_add_u32 s48, s28, 0x3e800b00
	s_addc_u32 s49, s29, 0
	s_add_u32 s54, s28, 0x3e800c00
	s_addc_u32 s55, s29, 0
	s_add_u32 s56, s28, 0x3e800d00
	s_addc_u32 s57, s29, 0
	s_add_u32 s58, s28, 0x3e800e00
	s_addc_u32 s59, s29, 0
	s_add_u32 s60, s28, 0x3e800f00
	s_addc_u32 s61, s29, 0
	s_add_u32 s62, s28, 0x3e801000
	s_addc_u32 s63, s29, 0
	s_add_u32 s64, s28, 0x3e801100
	s_addc_u32 s65, s29, 0
	s_add_u32 s66, s28, 0x3e801200
	s_addc_u32 s67, s29, 0
	s_add_u32 s68, s28, 0x3e801300
	s_addc_u32 s69, s29, 0
	s_mov_b32 s77, 1
	v_mov_b32_e32 v16, 0
	s_branch .LBB0_200

; #define PG8_STAGE(bufoff, gbase, voff) do { _Pragma("unroll") for (int _i = 0; _i < 2; ++_i) \
;         __builtin_amdgcn_global_load_lds((const unsigned*)((const char*)(gbase) + (voff)[_i]), (LAS unsigned*)(lds + (bufoff) + ldsw + _i * 8192), 16, 0, 0); } while (0)
; #define PG8_WAIT_V(n) asm volatile("s_waitcnt vmcnt(" #n ")" ::: "memory")
; #define PG8_BAR __builtin_amdgcn_s_barrier()
; template <class Epi, class Ptrs>
; __device__ __forceinline__ void gemm_phase(LAS unsigned char* lds, const int K, const StaticOrder& S, const Ptrs& P, const Epi& E) {
;     ...
;     PG8_STAGE(PG8_SB(0, 0), cB, voffB); PG8_STAGE(PG8_SA(0, 0), cA, voffA); PG8_STAGE(PG8_SB(0, 1), cB + hstep, voffB); PG8_STAGE(PG8_SA(0, 1), cA + hstep, voffA);
;     if (wr == 1) PG8_BAR;
;     PG8_WAIT_V(4); PG8_BAR;
;     PG8_STAGE(PG8_SB(1, 0), cB + kstep, voffB); PG8_STAGE(PG8_SA(1, 0), cA + kstep, voffA); PG8_STAGE(PG8_SB(1, 1), cB + hstep + kstep, voffB);
;     PG8_WAIT_V(6); PG8_BAR;
;     for (;;) {
;         const bool has_next = S.next(ui + 1, nxt);
;         const char* nA = cA; const char* nB = cB; if (has_next) P.get(nxt, nA, nB);
.LBB0_346:
	s_add_u32 s14, s28, 0x2000000
	s_addc_u32 s15, s29, 0
	s_add_u32 s16, s28, 0x3e000000
	s_addc_u32 s17, s29, 0
	s_ashr_i32 s58, s3, 31
	s_ashr_i32 s59, s2, 31
	s_add_u32 s60, s38, 0xf8000000
	s_mov_b64 s[18:19], 0x80
	s_addc_u32 s61, s39, -1
	s_and_b32 s62, s1, 3
	s_add_i32 m0, s54, 0x18000
	v_lshl_add_u64 v[6:7], v[6:7], 0, s[18:19]
	s_lshl_b32 s1, s0, 13
	s_lshl_b32 s20, s62, 12
	s_waitcnt vmcnt(4)
	s_barrier
	global_load_lds_dwordx4 v[6:7], off
	v_lshl_add_u64 v[4:5], v[4:5], 0, s[18:19]
	s_add_i32 m0, s54, 0x1a000
	s_add_i32 s63, s54, 0x8000
	s_add_i32 s64, s54, 0xa000
	global_load_lds_dwordx4 v[4:5], off
	v_lshl_add_u64 v[2:3], v[2:3], 0, s[18:19]
	s_mov_b32 m0, s63
	s_add_u32 s4, s42, 0x40080
	global_load_lds_dwordx4 v[2:3], off
	v_lshl_add_u64 v[0:1], v[0:1], 0, s[18:19]
	s_mov_b32 m0, s64
	s_addc_u32 s5, s43, 0
	global_load_lds_dwordx4 v[0:1], off
	s_add_i32 m0, s54, 0x1c000
	v_lshl_add_u64 v[0:1], s[4:5], 0, v[178:179]
	global_load_lds_dwordx4 v[0:1], off
	v_lshl_add_u64 v[0:1], s[4:5], 0, v[182:183]
	s_add_i32 m0, s54, 0x1e000
	v_lshlrev_b32_e32 v4, 6, v208
	global_load_lds_dwordx4 v[0:1], off
	v_bfe_u32 v1, v208, 4, 2
	v_lshlrev_b32_e32 v2, 3, v1
	v_lshlrev_b32_e32 v3, 4, v1
	v_cmp_eq_u32_e64 s[6:7], 0, v1
	v_lshlrev_b32_e32 v1, 8, v208
	v_lshl_or_b32 v206, s62, 5, v2
	v_and_b32_e32 v1, 0x38000, v1
	v_lshlrev_b32_e32 v2, 11, v10
	v_or3_b32 v1, v8, v1, v2
	v_and_b32_e32 v0, 15, v208
	s_movk_i32 s4, 0x3c0
	v_lshlrev_b32_e32 v5, 2, v208
	v_add_u32_e32 v184, v1, v9
	v_lshlrev_b32_e32 v1, 4, v11
	v_and_or_b32 v4, v4, s4, v3
	v_and_b32_e32 v5, 32, v5
	v_lshl_or_b32 v204, s0, 6, v0
	v_lshl_or_b32 v0, v0, 6, v3
	s_waitcnt vmcnt(6)
	v_and_b32_e32 v1, 0x78000, v1
	v_bitop3_b32 v0, v0, s1, v5 bitop3:0xde
	v_bitop3_b32 v205, s20, v4, v5 bitop3:0xf6
	v_or3_b32 v1, v8, v1, v2
	s_add_i32 s66, 0, 0x10000
	s_add_i32 s67, 0, 0x14000
	v_mov_b32_e32 v185, v179
	v_add_u32_e32 v186, v1, v9
	v_mov_b32_e32 v187, v179
	v_mov_b64_e32 v[188:189], 0x600
	v_mov_b64_e32 v[190:191], 0x5ff
	s_movk_i32 s65, 0xc1
	v_add_u32_e32 v207, s66, v205
	v_add_u32_e32 v209, 0, v0
	v_add_u32_e32 v210, s67, v205
	s_nop 0
	s_nop 0
	s_nop 0
	s_nop 0
	s_nop 0
	s_nop 0
	s_nop 0
	s_nop 0
	s_nop 0
	s_nop 0
	s_nop 0
	s_nop 0
	s_nop 0
	s_nop 0
	s_nop 0
	s_nop 0
	s_nop 0
	s_nop 0
	s_nop 0
	s_nop 0
	s_nop 0
	s_nop 0
	s_nop 0
	s_nop 0
	s_nop 0
	s_nop 0
	s_nop 0
	s_nop 0
	s_nop 0
	s_nop 0
	s_nop 0
	s_nop 0
	s_nop 0
	s_nop 0
	s_nop 0
	s_nop 0
	s_nop 0
	s_nop 0
	s_nop 0
	s_nop 0
	s_nop 0
	s_nop 0
	s_nop 0
	s_nop 0
	s_nop 0
	s_nop 0
	s_nop 0
	s_nop 0
	s_nop 0
	s_nop 0
	s_nop 0
	s_nop 0
	s_mov_b32 s68, 0
	s_cmpk_lt_u32 s46, 0x100
	s_cbranch_scc1 .Lsprio_1
	s_setprio 1

; template <class Epi, class Ptrs>
; __device__ __forceinline__ void gemm_phase(LAS unsigned char* lds, const int K, const StaticOrder& S, const Ptrs& P, const Epi& E) {
;     ...
;     for (;;) {
;         const bool has_next = S.next(ui + 1, nxt);
;         const char* nA = cA; const char* nB = cB; if (has_next) P.get(nxt, nA, nB);
.LBB0_347:
	s_or_b64 exec, exec, s[40:41]
	s_and_b64 vcc, exec, s[4:5]
	s_mov_b32 s12, s20
	s_mov_b32 s40, s22
	s_mov_b64 s[44:45], s[0:1]
	s_mov_b64 s[42:43], s[24:25]
	s_cbranch_vccnz .LBB0_370
	s_cmpk_lt_u32 s46, 0x100
	s_cbranch_scc1 .LBB0_348
	s_barrier

; #define PG8_STAGE(bufoff, gbase, voff) do { _Pragma("unroll") for (int _i = 0; _i < 2; ++_i) \
;         __builtin_amdgcn_global_load_lds((const unsigned*)((const char*)(gbase) + (voff)[_i]), (LAS unsigned*)(lds + (bufoff) + ldsw + _i * 8192), 16, 0, 0); } while (0)
; #define PG8_LDA(dst, b, h) do { _Pragma("unroll") for (int m = 0; m < 4; ++m) _Pragma("unroll") for (int k = 0; k < 2; ++k) dst[m][k] = *(const LAS bf16x8*)(lds + PG8_SA(b, h) + aoff + m * 2048 + k * 1024); } while (0)
; #define PG8_LDB(dst, b, h) do { _Pragma("unroll") for (int n = 0; n < 2; ++n) _Pragma("unroll") for (int k = 0; k < 2; ++k) dst[n][k] = *(const LAS bf16x8*)(lds + PG8_SB(b, h) + boff + n * 2048 + k * 1024); } while (0)
; #define PG8_MMA(ai, bj, At, Bt) do { __builtin_amdgcn_s_setprio(1); _Pragma("unroll") for (int m = 0; m < 4; ++m) _Pragma("unroll") for (int n = 0; n < 2; ++n) _Pragma("unroll") for (int k = 0; k < 2; ++k) \
;         acc[ai][bj][m][n] = __builtin_amdgcn_mfma_f32_16x16x32_bf16(Bt[n][k], At[m][k], acc[ai][bj][m][n], 0, 0, 0); __builtin_amdgcn_s_setprio(0); } while (0)
; #define PG8_WAIT_V(n) asm volatile("s_waitcnt vmcnt(" #n ")" ::: "memory")
; #define PG8_WAIT_L(n) asm volatile("s_waitcnt lgkmcnt(" #n ")" ::: "memory")
; template <class Epi, class Ptrs>
; __device__ __forceinline__ void gemm_phase(LAS unsigned char* lds, const int K, const StaticOrder& S, const Ptrs& P, const Epi& E) {
;     ...
;             PG8_LDB(B0, 0, 0); PG8_SCHED; PG8_LDA(At, 0, 0); PG8_STAGE(PG8_SA(1, 1), a1 + hstep, voffA);
;             PG8_WAIT_L(8); PG8_BAR; PG8_WAIT_L(0); PG8_MMA(0, 0, At, B0); PG8_BAR; PG8_SCHED;
;             PG8_LDB(B1, 0, 1); PG8_STAGE(PG8_SB(0, 0), b2, voffB);
;             PG8_BAR; PG8_WAIT_L(0); PG8_MMA(0, 1, At, B1); PG8_BAR;
;             PG8_LDA(At, 0, 1); PG8_STAGE(PG8_SA(0, 0), a2, voffA);
;             PG8_BAR; PG8_WAIT_L(0); PG8_MMA(1, 0, At, B0); PG8_BAR; PG8_SCHED;
;             PG8_STAGE(PG8_SB(0, 1), b2 + hstep, voffB);
;             PG8_WAIT_V(6); PG8_BAR; PG8_MMA(1, 1, At, B1); PG8_BAR;
;             PG8_LDB(B0, 1, 0); PG8_SCHED; PG8_LDA(At, 1, 0); PG8_STAGE(PG8_SA(0, 1), a2 + hstep, voffA);
;             PG8_WAIT_L(8); PG8_BAR; PG8_WAIT_L(0); PG8_MMA(0, 0, At, B0); PG8_BAR; PG8_SCHED;
;             PG8_LDB(B1, 1, 1); PG8_STAGE(PG8_SB(1, 0), b3, voffB);
;             PG8_BAR; PG8_WAIT_L(0); PG8_MMA(0, 1, At, B1); PG8_BAR;
.LBB0_353:
	ds_read_b128 v[128:131], v207
	ds_read_b128 v[132:135], v207 offset:1024
	ds_read_b128 v[136:139], v207 offset:2048
	ds_read_b128 v[140:143], v207 offset:3072
	s_add_u32 s42, s38, 0xfffc0080
	s_addc_u32 s43, s39, -1
	s_cmp_eq_u32 s41, 12
	s_cselect_b32 s45, s1, s43
	s_cselect_b32 s44, s0, s42
	s_cselect_b32 s43, s25, s23
	s_cselect_b32 s42, s24, s21
	s_add_i32 m0, s54, 0xc000
	ds_read_b128 v[144:147], v209
	ds_read_b128 v[148:151], v209 offset:1024
	ds_read_b128 v[152:155], v209 offset:2048
	ds_read_b128 v[156:159], v209 offset:3072
	ds_read_b128 v[160:163], v209 offset:4096
	ds_read_b128 v[164:167], v209 offset:5120
	ds_read_b128 v[168:171], v209 offset:6144
	ds_read_b128 v[172:175], v209 offset:7168
	global_load_lds_dwordx4 v184, s[38:39]
	s_add_i32 m0, s54, 0xe000
	s_nop 0
	global_load_lds_dwordx4 v186, s[38:39]
	s_waitcnt lgkmcnt(8)
	s_barrier
	s_waitcnt lgkmcnt(0)
	v_mfma_f32_16x16x32_bf16 v[124:127], v[128:131], v[144:147], v[124:127]
	v_mfma_f32_16x16x32_bf16 v[124:127], v[132:135], v[148:151], v[124:127]
	v_mfma_f32_16x16x32_bf16 v[120:123], v[140:143], v[148:151], v[120:123]
	v_mfma_f32_16x16x32_bf16 v[120:123], v[136:139], v[144:147], v[120:123]
	v_mfma_f32_16x16x32_bf16 v[104:107], v[136:139], v[152:155], v[104:107]
	v_mfma_f32_16x16x32_bf16 v[104:107], v[140:143], v[156:159], v[104:107]
	v_mfma_f32_16x16x32_bf16 v[108:111], v[132:135], v[156:159], v[108:111]
	v_mfma_f32_16x16x32_bf16 v[108:111], v[128:131], v[152:155], v[108:111]
	v_mfma_f32_16x16x32_bf16 v[92:95], v[128:131], v[160:163], v[92:95]
	v_mfma_f32_16x16x32_bf16 v[92:95], v[132:135], v[164:167], v[92:95]
	v_mfma_f32_16x16x32_bf16 v[88:91], v[140:143], v[164:167], v[88:91]
	v_mfma_f32_16x16x32_bf16 v[88:91], v[136:139], v[160:163], v[88:91]
	v_mfma_f32_16x16x32_bf16 v[72:75], v[136:139], v[168:171], v[72:75]
	v_mfma_f32_16x16x32_bf16 v[72:75], v[140:143], v[172:175], v[72:75]
	v_mfma_f32_16x16x32_bf16 v[76:79], v[132:135], v[172:175], v[76:79]
	v_mfma_f32_16x16x32_bf16 v[76:79], v[128:131], v[168:171], v[76:79]
	s_barrier
	s_add_i32 s69, s66, s51
	s_add_u32 s90, s42, 0x80
	s_addc_u32 s91, s43, 0
	s_mov_b32 m0, s69
	ds_read_b128 v[192:195], v210
	ds_read_b128 v[196:199], v210 offset:1024
	ds_read_b128 v[200:203], v210 offset:2048
	ds_read_b128 v[212:215], v210 offset:3072
	global_load_lds_dwordx4 v178, s[42:43]
	s_add_i32 m0, s69, 0x2000
	s_nop 0
	global_load_lds_dwordx4 v182, s[42:43]
	s_barrier
	s_waitcnt lgkmcnt(0)
	v_mfma_f32_16x16x32_bf16 v[116:119], v[192:195], v[144:147], v[116:119]
	v_mfma_f32_16x16x32_bf16 v[116:119], v[196:199], v[148:151], v[116:119]
	v_mfma_f32_16x16x32_bf16 v[112:115], v[212:215], v[148:151], v[112:115]
	v_mfma_f32_16x16x32_bf16 v[112:115], v[200:203], v[144:147], v[112:115]
	v_mfma_f32_16x16x32_bf16 v[96:99], v[200:203], v[152:155], v[96:99]
	v_mfma_f32_16x16x32_bf16 v[96:99], v[212:215], v[156:159], v[96:99]
	v_mfma_f32_16x16x32_bf16 v[100:103], v[196:199], v[156:159], v[100:103]
	v_mfma_f32_16x16x32_bf16 v[100:103], v[192:195], v[152:155], v[100:103]
	v_mfma_f32_16x16x32_bf16 v[84:87], v[192:195], v[160:163], v[84:87]
	v_mfma_f32_16x16x32_bf16 v[84:87], v[196:199], v[164:167], v[84:87]
	v_mfma_f32_16x16x32_bf16 v[80:83], v[212:215], v[164:167], v[80:83]
	v_mfma_f32_16x16x32_bf16 v[80:83], v[200:203], v[160:163], v[80:83]
	v_mfma_f32_16x16x32_bf16 v[64:67], v[200:203], v[168:171], v[64:67]
	v_mfma_f32_16x16x32_bf16 v[64:67], v[212:215], v[172:175], v[64:67]
	v_mfma_f32_16x16x32_bf16 v[68:71], v[196:199], v[172:175], v[68:71]
	v_mfma_f32_16x16x32_bf16 v[68:71], v[192:195], v[168:171], v[68:71]
	s_barrier
	s_mov_b32 m0, s54
	s_add_u32 s92, s44, 0x80
	s_addc_u32 s93, s45, 0
	ds_read_b128 v[144:147], v209 offset:16384
	ds_read_b128 v[148:151], v209 offset:17408
	ds_read_b128 v[152:155], v209 offset:18432
	ds_read_b128 v[156:159], v209 offset:19456
	ds_read_b128 v[160:163], v209 offset:20480
	ds_read_b128 v[164:167], v209 offset:21504
	ds_read_b128 v[168:171], v209 offset:22528
	ds_read_b128 v[172:175], v209 offset:23552
	global_load_lds_dwordx4 v176, s[44:45]
	s_mov_b32 m0, s55
	s_nop 0
	global_load_lds_dwordx4 v180, s[44:45]
	s_barrier
	s_waitcnt lgkmcnt(0)
	v_mfma_f32_16x16x32_bf16 v[60:63], v[128:131], v[144:147], v[60:63]
	v_mfma_f32_16x16x32_bf16 v[60:63], v[132:135], v[148:151], v[60:63]
	v_mfma_f32_16x16x32_bf16 v[56:59], v[140:143], v[148:151], v[56:59]
	v_mfma_f32_16x16x32_bf16 v[56:59], v[136:139], v[144:147], v[56:59]
	v_mfma_f32_16x16x32_bf16 v[40:43], v[136:139], v[152:155], v[40:43]
	v_mfma_f32_16x16x32_bf16 v[40:43], v[140:143], v[156:159], v[40:43]
	v_mfma_f32_16x16x32_bf16 v[44:47], v[132:135], v[156:159], v[44:47]
	v_mfma_f32_16x16x32_bf16 v[44:47], v[128:131], v[152:155], v[44:47]
	v_mfma_f32_16x16x32_bf16 v[28:31], v[128:131], v[160:163], v[28:31]
	v_mfma_f32_16x16x32_bf16 v[28:31], v[132:135], v[164:167], v[28:31]
	v_mfma_f32_16x16x32_bf16 v[24:27], v[140:143], v[164:167], v[24:27]
	v_mfma_f32_16x16x32_bf16 v[24:27], v[136:139], v[160:163], v[24:27]
	v_mfma_f32_16x16x32_bf16 v[8:11], v[136:139], v[168:171], v[8:11]
	v_mfma_f32_16x16x32_bf16 v[8:11], v[140:143], v[172:175], v[8:11]
	v_mfma_f32_16x16x32_bf16 v[12:15], v[132:135], v[172:175], v[12:15]
	v_mfma_f32_16x16x32_bf16 v[12:15], v[128:131], v[168:171], v[12:15]
	s_barrier
	s_add_u32 s70, s42, 0x40000
	s_addc_u32 s71, s43, 0
	s_add_i32 s69, s67, s51
	s_mov_b32 m0, s69
	s_nop 0
	global_load_lds_dwordx4 v178, s[70:71]
	s_add_i32 m0, s69, 0x2000
	s_nop 0
	global_load_lds_dwordx4 v182, s[70:71]
	s_waitcnt vmcnt(6)
	s_barrier
; #define PG8_STAGE(bufoff, gbase, voff) do { _Pragma("unroll") for (int _i = 0; _i < 2; ++_i) \
;         __builtin_amdgcn_global_load_lds((const unsigned*)((const char*)(gbase) + (voff)[_i]), (LAS unsigned*)(lds + (bufoff) + ldsw + _i * 8192), 16, 0, 0); } while (0)
; #define PG8_LDA(dst, b, h) do { _Pragma("unroll") for (int m = 0; m < 4; ++m) _Pragma("unroll") for (int k = 0; k < 2; ++k) dst[m][k] = *(const LAS bf16x8*)(lds + PG8_SA(b, h) + aoff + m * 2048 + k * 1024); } while (0)
; #define PG8_LDB(dst, b, h) do { _Pragma("unroll") for (int n = 0; n < 2; ++n) _Pragma("unroll") for (int k = 0; k < 2; ++k) dst[n][k] = *(const LAS bf16x8*)(lds + PG8_SB(b, h) + boff + n * 2048 + k * 1024); } while (0)
; #define PG8_MMA(ai, bj, At, Bt) do { __builtin_amdgcn_s_setprio(1); _Pragma("unroll") for (int m = 0; m < 4; ++m) _Pragma("unroll") for (int n = 0; n < 2; ++n) _Pragma("unroll") for (int k = 0; k < 2; ++k) \
;         acc[ai][bj][m][n] = __builtin_amdgcn_mfma_f32_16x16x32_bf16(Bt[n][k], At[m][k], acc[ai][bj][m][n], 0, 0, 0); __builtin_amdgcn_s_setprio(0); } while (0)
; #define PG8_WAIT_V(n) asm volatile("s_waitcnt vmcnt(" #n ")" ::: "memory")
; #define PG8_WAIT_L(n) asm volatile("s_waitcnt lgkmcnt(" #n ")" ::: "memory")
; #define PG8_BAR __builtin_amdgcn_s_barrier()
; #define PG8_SCHED __builtin_amdgcn_sched_barrier(0)
; template <class Epi, class Ptrs>
; __device__ __forceinline__ void gemm_phase(LAS unsigned char* lds, const int K, const StaticOrder& S, const Ptrs& P, const Epi& E) {
;     ...
;             PG8_WAIT_V(6); PG8_BAR; PG8_MMA(1, 1, At, B1); PG8_BAR;
;             PG8_LDB(B0, 1, 0); PG8_SCHED; PG8_LDA(At, 1, 0); PG8_STAGE(PG8_SA(0, 1), a2 + hstep, voffA);
;             PG8_WAIT_L(8); PG8_BAR; PG8_WAIT_L(0); PG8_MMA(0, 0, At, B0); PG8_BAR; PG8_SCHED;
;             PG8_LDB(B1, 1, 1); PG8_STAGE(PG8_SB(1, 0), b3, voffB);
;             PG8_BAR; PG8_WAIT_L(0); PG8_MMA(0, 1, At, B1); PG8_BAR;
;             PG8_LDA(At, 1, 1); PG8_STAGE(PG8_SA(1, 0), a3, voffA);
;             PG8_BAR; PG8_WAIT_L(0); PG8_MMA(1, 0, At, B0); PG8_BAR; PG8_SCHED;
;             PG8_STAGE(PG8_SB(1, 1), b3 + hstep, voffB);
	v_mfma_f32_16x16x32_bf16 v[52:55], v[192:195], v[144:147], v[52:55]
	v_mfma_f32_16x16x32_bf16 v[52:55], v[196:199], v[148:151], v[52:55]
	v_mfma_f32_16x16x32_bf16 v[48:51], v[212:215], v[148:151], v[48:51]
	v_mfma_f32_16x16x32_bf16 v[48:51], v[200:203], v[144:147], v[48:51]
	v_mfma_f32_16x16x32_bf16 v[32:35], v[200:203], v[152:155], v[32:35]
	v_mfma_f32_16x16x32_bf16 v[32:35], v[212:215], v[156:159], v[32:35]
	v_mfma_f32_16x16x32_bf16 v[36:39], v[196:199], v[156:159], v[36:39]
	v_mfma_f32_16x16x32_bf16 v[36:39], v[192:195], v[152:155], v[36:39]
	v_mfma_f32_16x16x32_bf16 v[20:23], v[192:195], v[160:163], v[20:23]
	v_mfma_f32_16x16x32_bf16 v[20:23], v[196:199], v[164:167], v[20:23]
	v_mfma_f32_16x16x32_bf16 v[16:19], v[212:215], v[164:167], v[16:19]
	v_mfma_f32_16x16x32_bf16 v[16:19], v[200:203], v[160:163], v[16:19]
	v_mfma_f32_16x16x32_bf16 v[0:3], v[200:203], v[168:171], v[0:3]
	v_mfma_f32_16x16x32_bf16 v[0:3], v[212:215], v[172:175], v[0:3]
	v_mfma_f32_16x16x32_bf16 v[4:7], v[196:199], v[172:175], v[4:7]
	v_mfma_f32_16x16x32_bf16 v[4:7], v[192:195], v[168:171], v[4:7]
	s_barrier
	s_add_i32 s69, 0, 0x18000
	ds_read_b128 v[128:131], v252
	ds_read_b128 v[132:135], v252 offset:1024
	ds_read_b128 v[136:139], v252 offset:2048
	ds_read_b128 v[140:143], v252 offset:3072
	s_add_u32 s44, s44, 0x40000
	s_addc_u32 s45, s45, 0
	s_mov_b32 m0, s56
	ds_read_b128 v[144:147], v209 offset:32768
	ds_read_b128 v[148:151], v209 offset:33792
	ds_read_b128 v[152:155], v209 offset:34816
	ds_read_b128 v[156:159], v209 offset:35840
	ds_read_b128 v[160:163], v209 offset:36864
	ds_read_b128 v[164:167], v209 offset:37888
	ds_read_b128 v[168:171], v209 offset:38912
	ds_read_b128 v[172:175], v209 offset:39936
	global_load_lds_dwordx4 v176, s[44:45]
	s_mov_b32 m0, s57
	s_nop 0
	global_load_lds_dwordx4 v180, s[44:45]
	s_waitcnt lgkmcnt(8)
	s_barrier
	s_waitcnt lgkmcnt(0)
	v_mfma_f32_16x16x32_bf16 v[124:127], v[128:131], v[144:147], v[124:127]
	v_mfma_f32_16x16x32_bf16 v[124:127], v[132:135], v[148:151], v[124:127]
	v_mfma_f32_16x16x32_bf16 v[120:123], v[140:143], v[148:151], v[120:123]
	v_mfma_f32_16x16x32_bf16 v[120:123], v[136:139], v[144:147], v[120:123]
	v_mfma_f32_16x16x32_bf16 v[104:107], v[136:139], v[152:155], v[104:107]
	v_mfma_f32_16x16x32_bf16 v[104:107], v[140:143], v[156:159], v[104:107]
	v_mfma_f32_16x16x32_bf16 v[108:111], v[132:135], v[156:159], v[108:111]
	v_mfma_f32_16x16x32_bf16 v[108:111], v[128:131], v[152:155], v[108:111]
	v_mfma_f32_16x16x32_bf16 v[92:95], v[128:131], v[160:163], v[92:95]
	v_mfma_f32_16x16x32_bf16 v[92:95], v[132:135], v[164:167], v[92:95]
	v_mfma_f32_16x16x32_bf16 v[88:91], v[140:143], v[164:167], v[88:91]
	v_mfma_f32_16x16x32_bf16 v[88:91], v[136:139], v[160:163], v[88:91]
	v_mfma_f32_16x16x32_bf16 v[72:75], v[136:139], v[168:171], v[72:75]
	v_mfma_f32_16x16x32_bf16 v[72:75], v[140:143], v[172:175], v[72:75]
	v_mfma_f32_16x16x32_bf16 v[76:79], v[132:135], v[172:175], v[76:79]
	v_mfma_f32_16x16x32_bf16 v[76:79], v[128:131], v[168:171], v[76:79]
	s_barrier
	s_add_i32 s44, 0, 0x1c000
	s_add_i32 s45, s69, s51
	s_mov_b32 m0, s45
	ds_read_b128 v[192:195], v253
	ds_read_b128 v[196:199], v253 offset:1024
	ds_read_b128 v[200:203], v253 offset:2048
	ds_read_b128 v[212:215], v253 offset:3072
	global_load_lds_dwordx4 v178, s[90:91]
	s_add_i32 m0, s45, 0x2000
	s_nop 0
	global_load_lds_dwordx4 v182, s[90:91]
	s_barrier
	s_waitcnt lgkmcnt(0)
	v_mfma_f32_16x16x32_bf16 v[116:119], v[192:195], v[144:147], v[116:119]
	v_mfma_f32_16x16x32_bf16 v[116:119], v[196:199], v[148:151], v[116:119]
	v_mfma_f32_16x16x32_bf16 v[112:115], v[212:215], v[148:151], v[112:115]
	v_mfma_f32_16x16x32_bf16 v[112:115], v[200:203], v[144:147], v[112:115]
	v_mfma_f32_16x16x32_bf16 v[96:99], v[200:203], v[152:155], v[96:99]
	v_mfma_f32_16x16x32_bf16 v[96:99], v[212:215], v[156:159], v[96:99]
	v_mfma_f32_16x16x32_bf16 v[100:103], v[196:199], v[156:159], v[100:103]
	v_mfma_f32_16x16x32_bf16 v[100:103], v[192:195], v[152:155], v[100:103]
	v_mfma_f32_16x16x32_bf16 v[84:87], v[192:195], v[160:163], v[84:87]
	v_mfma_f32_16x16x32_bf16 v[84:87], v[196:199], v[164:167], v[84:87]
	v_mfma_f32_16x16x32_bf16 v[80:83], v[212:215], v[164:167], v[80:83]
	v_mfma_f32_16x16x32_bf16 v[80:83], v[200:203], v[160:163], v[80:83]
	v_mfma_f32_16x16x32_bf16 v[64:67], v[200:203], v[168:171], v[64:67]
	v_mfma_f32_16x16x32_bf16 v[64:67], v[212:215], v[172:175], v[64:67]
	v_mfma_f32_16x16x32_bf16 v[68:71], v[196:199], v[172:175], v[68:71]
	v_mfma_f32_16x16x32_bf16 v[68:71], v[192:195], v[168:171], v[68:71]
	s_barrier
	s_mov_b32 m0, s63
	ds_read_b128 v[144:147], v209 offset:49152
	ds_read_b128 v[148:151], v209 offset:50176
	ds_read_b128 v[152:155], v209 offset:51200
	ds_read_b128 v[156:159], v209 offset:52224
	ds_read_b128 v[160:163], v209 offset:53248
	ds_read_b128 v[164:167], v209 offset:54272
	ds_read_b128 v[168:171], v209 offset:55296
	ds_read_b128 v[172:175], v209 offset:56320
	global_load_lds_dwordx4 v176, s[92:93]
	s_mov_b32 m0, s64
	s_nop 0
	global_load_lds_dwordx4 v180, s[92:93]
	s_barrier
	s_waitcnt lgkmcnt(0)
	v_mfma_f32_16x16x32_bf16 v[60:63], v[128:131], v[144:147], v[60:63]
	v_mfma_f32_16x16x32_bf16 v[60:63], v[132:135], v[148:151], v[60:63]
	v_mfma_f32_16x16x32_bf16 v[56:59], v[140:143], v[148:151], v[56:59]
	v_mfma_f32_16x16x32_bf16 v[56:59], v[136:139], v[144:147], v[56:59]
	v_mfma_f32_16x16x32_bf16 v[40:43], v[136:139], v[152:155], v[40:43]
	v_mfma_f32_16x16x32_bf16 v[40:43], v[140:143], v[156:159], v[40:43]
	v_mfma_f32_16x16x32_bf16 v[44:47], v[132:135], v[156:159], v[44:47]
	v_mfma_f32_16x16x32_bf16 v[44:47], v[128:131], v[152:155], v[44:47]
	v_mfma_f32_16x16x32_bf16 v[28:31], v[128:131], v[160:163], v[28:31]
	v_mfma_f32_16x16x32_bf16 v[28:31], v[132:135], v[164:167], v[28:31]
	v_mfma_f32_16x16x32_bf16 v[24:27], v[140:143], v[164:167], v[24:27]
	v_mfma_f32_16x16x32_bf16 v[24:27], v[136:139], v[160:163], v[24:27]
	v_mfma_f32_16x16x32_bf16 v[8:11], v[136:139], v[168:171], v[8:11]
	v_mfma_f32_16x16x32_bf16 v[8:11], v[140:143], v[172:175], v[8:11]
	v_mfma_f32_16x16x32_bf16 v[12:15], v[132:135], v[172:175], v[12:15]
	v_mfma_f32_16x16x32_bf16 v[12:15], v[128:131], v[168:171], v[12:15]
	s_barrier
; __device__ __forceinline__ unsigned cvt_pk_bf16(float lo, float hi) { unsigned r; asm volatile("v_cvt_pk_bf16_f32 %0, %1, %2" : "=v"(r) : "v"(lo), "v"(hi)); return r; }
; __device__ __forceinline__ float x16_sum(float x) { auto s = __builtin_amdgcn_permlane16_swap(__float_as_uint(x), __float_as_uint(x), false, false); return __uint_as_float(s[0]) + __uint_as_float(s[1]); }
; #define PG8_WAIT_V(n) asm volatile("s_waitcnt vmcnt(" #n ")" ::: "memory")
; #define PG8_BAR __builtin_amdgcn_s_barrier()
; template <class Epi, class Ptrs>
; __device__ __forceinline__ void gemm_phase(LAS unsigned char* lds, const int K, const StaticOrder& S, const Ptrs& P, const Epi& E) {
;     ...
;             PG8_STAGE(PG8_SB(1, 1), b3 + hstep, voffB);
;             PG8_WAIT_V(6); PG8_BAR; PG8_MMA(1, 1, At, B1); PG8_BAR;
;     __device__ __forceinline__ void operator()(const f32x4 (&acc)[2][2][4][2], const Unit& u, int ui, int wr, int wc, int fr, int fq) const {
;         const int row0 = u.pm * 256 + wr * 64 + fr, col0 = u.pn * 256 + wc * 32 + 8 * fq;
;         const float* xb0 = (u.pm * 256 < MP) ? xp : xs - (size_t)MP * DM;
; #pragma unroll
;         for (int ai = 0; ai < 2; ++ai) {
;             f32x4 xv[4][2][2];
; #pragma unroll
;             for (int m = 0; m < 4; ++m)
; #pragma unroll
;                 for (int bj = 0; bj < 2; ++bj) { const float* p = xb0 + (size_t)(row0 + ai * 128 + m * 16) * DM + col0 + bj * 128; xv[m][bj][0] = *(const f32x4*)p; xv[m][bj][1] = *(const f32x4*)(p + 4); }
; #pragma unroll
;             for (int m = 0; m < 4; ++m) { const int row = row0 + ai * 128 + m * 16; const size_t off = (size_t)row * DM + col0; float ss = 0.f;
; #pragma unroll
;                 for (int bj = 0; bj < 2; ++bj) {
;                     const f32x4 v0 = acc[ai][bj][m][0] + xv[m][bj][0], v1 = acc[ai][bj][m][1] + xv[m][bj][1];
;                     u32x4 w; w.x = cvt_pk_bf16(v0[0], v0[1]); w.y = cvt_pk_bf16(v0[2], v0[3]); w.z = cvt_pk_bf16(v1[0], v1[1]); w.w = cvt_pk_bf16(v1[2], v1[3]);
;                     *(u32x4*)(xb + off + bj * 128) = w;
;                     ss += (v0[0] * v0[0] + v0[1] * v0[1]) + (v0[2] * v0[2] + v0[3] * v0[3]) + (v1[0] * v1[0] + v1[1] * v1[1]) + (v1[2] * v1[2] + v1[3] * v1[3]); }
;                 ss = x32_sum(x16_sum(ss));
;                 if (fq == 0) part[(size_t)row * 16 + u.pn * 4 + wc] = ss; }
	s_add_u32 s42, s42, 0x40080
	s_addc_u32 s43, s43, 0
	s_add_i32 s44, s44, s51
	s_mov_b32 m0, s44
	s_nop 0
	global_load_lds_dwordx4 v178, s[42:43]
	s_add_i32 m0, s44, 0x2000
	s_nop 0
	global_load_lds_dwordx4 v182, s[42:43]
	s_waitcnt vmcnt(6)
	s_barrier
	v_mfma_f32_16x16x32_bf16 v[52:55], v[192:195], v[144:147], v[52:55]
	v_mfma_f32_16x16x32_bf16 v[52:55], v[196:199], v[148:151], v[52:55]
	v_mfma_f32_16x16x32_bf16 v[48:51], v[212:215], v[148:151], v[48:51]
	v_mfma_f32_16x16x32_bf16 v[48:51], v[200:203], v[144:147], v[48:51]
	v_mfma_f32_16x16x32_bf16 v[32:35], v[200:203], v[152:155], v[32:35]
	v_mfma_f32_16x16x32_bf16 v[32:35], v[212:215], v[156:159], v[32:35]
	v_mfma_f32_16x16x32_bf16 v[36:39], v[196:199], v[156:159], v[36:39]
	v_mfma_f32_16x16x32_bf16 v[36:39], v[192:195], v[152:155], v[36:39]
	v_mfma_f32_16x16x32_bf16 v[20:23], v[192:195], v[160:163], v[20:23]
	v_mfma_f32_16x16x32_bf16 v[20:23], v[196:199], v[164:167], v[20:23]
	v_mfma_f32_16x16x32_bf16 v[16:19], v[212:215], v[164:167], v[16:19]
	v_mfma_f32_16x16x32_bf16 v[16:19], v[200:203], v[160:163], v[16:19]
	v_mfma_f32_16x16x32_bf16 v[0:3], v[200:203], v[168:171], v[0:3]
	v_mfma_f32_16x16x32_bf16 v[0:3], v[212:215], v[172:175], v[0:3]
	v_mfma_f32_16x16x32_bf16 v[4:7], v[196:199], v[172:175], v[4:7]
	v_mfma_f32_16x16x32_bf16 v[4:7], v[192:195], v[168:171], v[4:7]
	s_barrier
	s_add_i32 s41, s41, 2
	s_add_u32 s38, s38, 0x100
	s_addc_u32 s39, s39, 0
	s_add_u32 s21, s21, 0x100
	s_addc_u32 s23, s23, 0
	s_cmp_gt_u32 s41, 13
	s_cbranch_scc0 .LBB0_353
	s_cmpk_lt_u32 s46, 0x100
	s_cbranch_scc0 .Ltsync_a1
	s_barrier
.Ltsync_a1:
	s_cmpk_lt_i32 s40, 0x80
	v_lshl_add_u32 v194, s40, 8, v204
	v_lshl_or_b32 v192, s12, 8, v206
	s_cselect_b32 s21, s37, s61
	s_cselect_b32 s23, s36, s60
	v_mov_b32_e32 v128, s23
	v_mov_b32_e32 v129, s21
	v_ashrrev_i32_e32 v193, 31, v192
	v_ashrrev_i32_e32 v195, 31, v194
	v_lshl_add_u64 v[196:197], v[192:193], 2, v[128:129]
	v_lshlrev_b64 v[128:129], 12, v[194:195]
	v_or_b32_e32 v202, 16, v194
	v_or_b32_e32 v200, 32, v194
	v_or_b32_e32 v198, 48, v194
	v_lshl_add_u64 v[128:129], v[196:197], 0, v[128:129]
	v_ashrrev_i32_e32 v203, 31, v202
	v_ashrrev_i32_e32 v201, 31, v200
	v_ashrrev_i32_e32 v199, 31, v198
	global_load_dwordx4 v[212:215], v[128:129], off
	global_load_dwordx4 v[216:219], v[128:129], off offset:16
	global_load_dwordx4 v[220:223], v[128:129], off offset:512
	global_load_dwordx4 v[224:227], v[128:129], off offset:528
	v_lshlrev_b64 v[128:129], 12, v[202:203]
	v_lshlrev_b64 v[130:131], 12, v[200:201]
	v_lshlrev_b64 v[132:133], 12, v[198:199]
	v_lshl_add_u64 v[128:129], v[196:197], 0, v[128:129]
	v_lshl_add_u64 v[130:131], v[196:197], 0, v[130:131]
	v_lshl_add_u64 v[132:133], v[196:197], 0, v[132:133]
	global_load_dwordx4 v[168:171], v[128:129], off offset:16
	global_load_dwordx4 v[172:175], v[128:129], off
	global_load_dwordx4 v[160:163], v[128:129], off offset:528
	global_load_dwordx4 v[164:167], v[128:129], off offset:512
	global_load_dwordx4 v[152:155], v[130:131], off offset:16
	global_load_dwordx4 v[156:159], v[130:131], off
	global_load_dwordx4 v[144:147], v[130:131], off offset:528
	global_load_dwordx4 v[148:151], v[130:131], off offset:512
	global_load_dwordx4 v[136:139], v[132:133], off offset:16
	global_load_dwordx4 v[140:143], v[132:133], off
	s_nop 0
	global_load_dwordx4 v[128:131], v[132:133], off offset:528
	s_nop 0
	global_load_dwordx4 v[132:135], v[132:133], off offset:512
	v_lshlrev_b64 v[228:229], 11, v[194:195]
	v_lshl_add_u64 v[228:229], s[14:15], 0, v[228:229]
	v_lshl_add_u64 v[228:229], v[192:193], 1, v[228:229]
	s_lshl_b32 s38, s12, 2
	s_ashr_i32 s39, s38, 31
	s_waitcnt vmcnt(0)
	v_pk_add_f32 v[126:127], v[126:127], v[214:215]
	v_pk_add_f32 v[124:125], v[124:125], v[212:213]
	v_pk_add_f32 v[118:119], v[118:119], v[222:223]
	v_pk_add_f32 v[116:117], v[116:117], v[220:221]
	v_pk_add_f32 v[120:121], v[120:121], v[216:217]
	v_pk_add_f32 v[214:215], v[112:113], v[224:225]
	v_cvt_pk_bf16_f32 v112, v124, v125
	v_cvt_pk_bf16_f32 v113, v126, v127
	v_mul_f32_e32 v125, v125, v125
	v_mul_f32_e32 v127, v127, v127
	v_mul_f32_e32 v211, v117, v117
	v_mul_f32_e32 v216, v119, v119
	v_pk_add_f32 v[122:123], v[122:123], v[218:219]
	v_pk_add_f32 v[212:213], v[114:115], v[226:227]
	v_cvt_pk_bf16_f32 v114, v120, v121
	v_cvt_pk_bf16_f32 v115, v122, v123
	v_mul_f32_e32 v121, v121, v121
	v_mul_f32_e32 v217, v215, v215
	global_store_dwordx4 v[228:229], v[112:115], off
	v_fmac_f32_e32 v125, v124, v124
	v_fmac_f32_e32 v127, v126, v126
	v_cvt_pk_bf16_f32 v112, v116, v117
	v_fmac_f32_e32 v211, v116, v116
	v_fmac_f32_e32 v216, v118, v118
	v_mul_f32_e32 v123, v123, v123
	v_mul_f32_e32 v218, v213, v213
	v_fmac_f32_e32 v121, v120, v120
	v_cvt_pk_bf16_f32 v113, v118, v119
	v_cvt_pk_bf16_f32 v114, v214, v215
	v_cvt_pk_bf16_f32 v115, v212, v213
	v_fmac_f32_e32 v217, v214, v214
	v_add_f32_e32 v116, v125, v127
	global_store_dwordx4 v[228:229], v[112:115], off offset:256
	v_fmac_f32_e32 v123, v122, v122
	v_fmac_f32_e32 v218, v212, v212
	v_add_f32_e32 v112, v211, v216
	v_add_f32_e32 v113, v116, v121
	v_add_f32_e32 v112, v112, v217
	v_add_f32_e32 v113, v123, v113
	v_add_f32_e32 v112, v218, v112
	v_add_f32_e32 v112, v113, v112
	v_mov_b32_e32 v113, v112
	s_nop 1
	v_permlane16_swap_b32_e32 v112, v113
	v_add_f32_e32 v112, v112, v113
	v_mov_b32_e32 v113, v112
	s_nop 1
	v_permlane32_swap_b32_e32 v112, v113
	s_and_saveexec_b64 s[40:41], s[6:7]
	s_cbranch_execz .LBB0_356
	v_lshlrev_b64 v[114:115], 6, v[194:195]
	v_lshl_add_u64 v[114:115], s[16:17], 0, v[114:115]
	v_lshl_add_u64 v[114:115], s[38:39], 2, v[114:115]
	s_lshl_b32 s12, s62, 2
	v_lshl_add_u64 v[114:115], v[114:115], 0, s[12:13]
	v_add_f32_e32 v112, v112, v113
	global_store_dword v[114:115], v112, off

; #define PG8_WAIT_V(n) asm volatile("s_waitcnt vmcnt(" #n ")" ::: "memory")
; #define PG8_BAR __builtin_amdgcn_s_barrier()
; template <class Epi, class Ptrs>
; __device__ __forceinline__ void gemm_phase(LAS unsigned char* lds, const int K, const StaticOrder& S, const Ptrs& P, const Epi& E) {
;     ...
;     PG8_WAIT_V(0);
;     if (wr == 0) PG8_BAR;
;     PG8_BAR;
; __device__ __forceinline__ void xcd_barrier(const XcdBarrier& b) {
;     asm volatile("s_waitcnt vmcnt(0)" ::: "memory");
;     __syncthreads();
;     if (threadIdx.x == 0) {
;         unsigned* bar = b.bar;
;         __builtin_amdgcn_s_waitcnt(0);
;         unsigned nloc = b.st[0], nx = b.st[1];
;         if (nloc == 0u) { xcd_barrier_complete(bar, b.x, nloc, nx); b.st[0] = nloc; b.st[1] = nx; }
.LBB0_370:
	s_waitcnt vmcnt(0)
	s_setprio 0
	s_cmpk_gt_u32 s46, 0xff
	s_cbranch_scc1 .LBB0_372
.LBB0_372:
	s_barrier
.LBB0_373:
	s_nop 0
	s_nop 0
	s_nop 0
	s_nop 0
	s_nop 0
	s_nop 0
	s_nop 0
	s_nop 0
	s_nop 0
	s_nop 0
	s_nop 0
	s_nop 0
	s_nop 0
	s_nop 0
	s_nop 0
	s_nop 0
	s_nop 0
	s_nop 0
	s_nop 0
	s_nop 0
	s_nop 0
	s_nop 0
	s_nop 0
	s_nop 0
	s_nop 0
	s_nop 0
	s_nop 0
	s_nop 0
	s_nop 0
	s_nop 0
	s_nop 0
	s_nop 0
	s_nop 0
	s_nop 0
	s_nop 0
	s_nop 0
	s_nop 0
	s_nop 0
	s_nop 0
	s_nop 0
	s_nop 0
	s_nop 0
	s_nop 0
	s_nop 0
	s_nop 0
	s_nop 0
	s_nop 0
	s_cmp_gt_i32 s31, 4
	s_cselect_b64 s[0:1], -1, 0
	s_and_b64 s[4:5], s[10:11], s[0:1]
	s_andn2_b64 vcc, exec, s[4:5]
	s_cbranch_vccnz .LBB0_423
	s_waitcnt vmcnt(0)
	s_waitcnt vmcnt(0) lgkmcnt(0)
	s_barrier
	s_and_saveexec_b64 s[4:5], s[8:9]
	s_cbranch_execz .LBB0_422
	s_add_i32 s6, 0, 0x25ff0
	v_mov_b32_e32 v0, s6
	s_waitcnt vmcnt(0) expcnt(0) lgkmcnt(0)
	ds_read_b32 v2, v0
	s_add_i32 s6, 0, 0x25ff4
	v_mov_b32_e32 v0, s6
	ds_read_b32 v0, v0
	s_waitcnt lgkmcnt(1)
	v_cmp_ne_u32_e32 vcc, 0, v2
	s_cbranch_vccnz .LBB0_390
	s_load_dwordx2 s[12:13], s[52:53], 0x4
	s_add_u32 s6, s28, 0x3e800200
	s_addc_u32 s7, s29, 0
	s_add_u32 s10, s28, 0x3e800400
	s_addc_u32 s11, s29, 0
	s_waitcnt lgkmcnt(0)
	s_mul_i32 s60, s12, s3
	s_add_u32 s12, s28, 0x3e800500
	s_mul_i32 s60, s60, s13
	s_addc_u32 s13, s29, 0
	s_add_u32 s14, s28, 0x3e800600
	s_addc_u32 s15, s29, 0
	s_add_u32 s16, s28, 0x3e800700
	s_addc_u32 s17, s29, 0
	s_add_u32 s18, s28, 0x3e800800
	s_addc_u32 s19, s29, 0
	s_add_u32 s20, s28, 0x3e800900
	s_addc_u32 s21, s29, 0
	s_add_u32 s22, s28, 0x3e800a00
	s_addc_u32 s23, s29, 0
	s_add_u32 s24, s28, 0x3e800b00
	s_addc_u32 s25, s29, 0
	s_add_u32 s36, s28, 0x3e800c00
	s_addc_u32 s37, s29, 0
	s_add_u32 s38, s28, 0x3e800d00
	s_addc_u32 s39, s29, 0
	s_add_u32 s40, s28, 0x3e800e00
	s_addc_u32 s41, s29, 0
	s_add_u32 s42, s28, 0x3e800f00
	s_addc_u32 s43, s29, 0
	s_add_u32 s44, s28, 0x3e801000
	s_addc_u32 s45, s29, 0
	s_add_u32 s46, s28, 0x3e801100
	s_addc_u32 s47, s29, 0
	s_add_u32 s48, s28, 0x3e801200
	s_addc_u32 s49, s29, 0
	s_add_u32 s50, s28, 0x3e801300
	s_addc_u32 s51, s29, 0
	s_mov_b32 s61, 1
	v_mov_b32_e32 v16, 0
	s_branch .LBB0_378

; #define PG8_STAGE(bufoff, gbase, voff) do { _Pragma("unroll") for (int _i = 0; _i < 2; ++_i) \
;         __builtin_amdgcn_global_load_lds((const unsigned*)((const char*)(gbase) + (voff)[_i]), (LAS unsigned*)(lds + (bufoff) + ldsw + _i * 8192), 16, 0, 0); } while (0)
; #define PG8_LDA(dst, b, h) do { _Pragma("unroll") for (int m = 0; m < 4; ++m) _Pragma("unroll") for (int k = 0; k < 2; ++k) dst[m][k] = *(const LAS bf16x8*)(lds + PG8_SA(b, h) + aoff + m * 2048 + k * 1024); } while (0)
; #define PG8_LDB(dst, b, h) do { _Pragma("unroll") for (int n = 0; n < 2; ++n) _Pragma("unroll") for (int k = 0; k < 2; ++k) dst[n][k] = *(const LAS bf16x8*)(lds + PG8_SB(b, h) + boff + n * 2048 + k * 1024); } while (0)
; #define PG8_MMA(ai, bj, At, Bt) do { __builtin_amdgcn_s_setprio(1); _Pragma("unroll") for (int m = 0; m < 4; ++m) _Pragma("unroll") for (int n = 0; n < 2; ++n) _Pragma("unroll") for (int k = 0; k < 2; ++k) \
;         acc[ai][bj][m][n] = __builtin_amdgcn_mfma_f32_16x16x32_bf16(Bt[n][k], At[m][k], acc[ai][bj][m][n], 0, 0, 0); __builtin_amdgcn_s_setprio(0); } while (0)
; #define PG8_WAIT_V(n) asm volatile("s_waitcnt vmcnt(" #n ")" ::: "memory")
; #define PG8_WAIT_L(n) asm volatile("s_waitcnt lgkmcnt(" #n ")" ::: "memory")
; #define PG8_BAR __builtin_amdgcn_s_barrier()
; #define PG8_SCHED __builtin_amdgcn_sched_barrier(0)
; template <class Epi, class Ptrs>
; __device__ __forceinline__ void gemm_phase(LAS unsigned char* lds, const int K, const StaticOrder& S, const Ptrs& P, const Epi& E) {
;     ...
;             const char* a1 = cA + (size_t)(t + 1) * kstep;
;             const char* a2 = last ? nA : cA + (size_t)(t + 2) * kstep; const char* b2 = last ? nB : cB + (size_t)(t + 2) * kstep;
;             const char* a3 = a2 + kstep; const char* b3 = b2 + kstep;
;             PG8_LDB(B0, 0, 0); PG8_SCHED; PG8_LDA(At, 0, 0); PG8_STAGE(PG8_SA(1, 1), a1 + hstep, voffA);
;             PG8_WAIT_L(8); PG8_BAR; PG8_WAIT_L(0); PG8_MMA(0, 0, At, B0); PG8_BAR; PG8_SCHED;
;             PG8_LDB(B1, 0, 1); PG8_STAGE(PG8_SB(0, 0), b2, voffB);
;             PG8_BAR; PG8_WAIT_L(0); PG8_MMA(0, 1, At, B1); PG8_BAR;
;             PG8_LDA(At, 0, 1); PG8_STAGE(PG8_SA(0, 0), a2, voffA);
;             PG8_BAR; PG8_WAIT_L(0); PG8_MMA(1, 0, At, B0); PG8_BAR; PG8_SCHED;
;             PG8_STAGE(PG8_SB(0, 1), b2 + hstep, voffB);
;             PG8_WAIT_V(6); PG8_BAR; PG8_MMA(1, 1, At, B1); PG8_BAR;
.LBB0_433:
	ds_read_b128 v[152:155], v149
	ds_read_b128 v[156:159], v149 offset:1024
	ds_read_b128 v[160:163], v149 offset:2048
	ds_read_b128 v[164:167], v149 offset:3072
	s_add_u32 s42, s40, 0xfffc0080
	s_addc_u32 s43, s41, -1
	s_cmp_eq_u32 s70, 12
	s_cselect_b32 s45, s1, s43
	s_cselect_b32 s44, s0, s42
	s_cselect_b32 s43, s37, s25
	s_cselect_b32 s42, s36, s23
	s_add_i32 m0, s39, 0xc000
	ds_read_b128 v[168:171], v150
	ds_read_b128 v[172:175], v150 offset:1024
	ds_read_b128 v[176:179], v150 offset:2048
	ds_read_b128 v[180:183], v150 offset:3072
	ds_read_b128 v[184:187], v150 offset:4096
	ds_read_b128 v[188:191], v150 offset:5120
	ds_read_b128 v[192:195], v150 offset:6144
	ds_read_b128 v[196:199], v150 offset:7168
	global_load_lds_dwordx4 v136, s[40:41]
	s_add_i32 m0, s39, 0xe000
	s_nop 0
	global_load_lds_dwordx4 v138, s[40:41]
	s_waitcnt lgkmcnt(8)
	s_barrier
	s_waitcnt lgkmcnt(0)
	v_mfma_f32_16x16x32_bf16 v[124:127], v[152:155], v[168:171], v[124:127]
	v_mfma_f32_16x16x32_bf16 v[124:127], v[156:159], v[172:175], v[124:127]
	v_mfma_f32_16x16x32_bf16 v[120:123], v[164:167], v[172:175], v[120:123]
	v_mfma_f32_16x16x32_bf16 v[120:123], v[160:163], v[168:171], v[120:123]
	v_mfma_f32_16x16x32_bf16 v[104:107], v[160:163], v[176:179], v[104:107]
	v_mfma_f32_16x16x32_bf16 v[104:107], v[164:167], v[180:183], v[104:107]
	v_mfma_f32_16x16x32_bf16 v[108:111], v[156:159], v[180:183], v[108:111]
	v_mfma_f32_16x16x32_bf16 v[108:111], v[152:155], v[176:179], v[108:111]
	v_mfma_f32_16x16x32_bf16 v[92:95], v[152:155], v[184:187], v[92:95]
	v_mfma_f32_16x16x32_bf16 v[92:95], v[156:159], v[188:191], v[92:95]
	v_mfma_f32_16x16x32_bf16 v[88:91], v[164:167], v[188:191], v[88:91]
	v_mfma_f32_16x16x32_bf16 v[88:91], v[160:163], v[184:187], v[88:91]
	v_mfma_f32_16x16x32_bf16 v[72:75], v[160:163], v[192:195], v[72:75]
	v_mfma_f32_16x16x32_bf16 v[72:75], v[164:167], v[196:199], v[72:75]
	v_mfma_f32_16x16x32_bf16 v[76:79], v[156:159], v[196:199], v[76:79]
	v_mfma_f32_16x16x32_bf16 v[76:79], v[152:155], v[192:195], v[76:79]
	s_barrier
	s_add_i32 s71, s63, s51
	s_add_u32 s76, s42, 0x80
	s_addc_u32 s77, s43, 0
	s_mov_b32 m0, s71
	ds_read_b128 v[200:203], v151
	ds_read_b128 v[204:207], v151 offset:1024
	ds_read_b128 v[210:213], v151 offset:2048
	ds_read_b128 v[214:217], v151 offset:3072
	global_load_lds_dwordx4 v130, s[42:43]
	s_add_i32 m0, s71, 0x2000
	s_nop 0
	global_load_lds_dwordx4 v134, s[42:43]
	s_barrier
	s_waitcnt lgkmcnt(0)
	v_mfma_f32_16x16x32_bf16 v[116:119], v[200:203], v[168:171], v[116:119]
	v_mfma_f32_16x16x32_bf16 v[116:119], v[204:207], v[172:175], v[116:119]
	v_mfma_f32_16x16x32_bf16 v[112:115], v[214:217], v[172:175], v[112:115]
	v_mfma_f32_16x16x32_bf16 v[112:115], v[210:213], v[168:171], v[112:115]
	v_mfma_f32_16x16x32_bf16 v[96:99], v[210:213], v[176:179], v[96:99]
	v_mfma_f32_16x16x32_bf16 v[96:99], v[214:217], v[180:183], v[96:99]
	v_mfma_f32_16x16x32_bf16 v[100:103], v[204:207], v[180:183], v[100:103]
	v_mfma_f32_16x16x32_bf16 v[100:103], v[200:203], v[176:179], v[100:103]
	v_mfma_f32_16x16x32_bf16 v[84:87], v[200:203], v[184:187], v[84:87]
	v_mfma_f32_16x16x32_bf16 v[84:87], v[204:207], v[188:191], v[84:87]
	v_mfma_f32_16x16x32_bf16 v[80:83], v[214:217], v[188:191], v[80:83]
	v_mfma_f32_16x16x32_bf16 v[80:83], v[210:213], v[184:187], v[80:83]
	v_mfma_f32_16x16x32_bf16 v[64:67], v[210:213], v[192:195], v[64:67]
	v_mfma_f32_16x16x32_bf16 v[64:67], v[214:217], v[196:199], v[64:67]
	v_mfma_f32_16x16x32_bf16 v[68:71], v[204:207], v[196:199], v[68:71]
	v_mfma_f32_16x16x32_bf16 v[68:71], v[200:203], v[192:195], v[68:71]
	s_barrier
	s_mov_b32 m0, s39
	s_add_u32 s78, s44, 0x80
	s_addc_u32 s79, s45, 0
	ds_read_b128 v[168:171], v150 offset:16384
	ds_read_b128 v[172:175], v150 offset:17408
	ds_read_b128 v[176:179], v150 offset:18432
	ds_read_b128 v[180:183], v150 offset:19456
	ds_read_b128 v[184:187], v150 offset:20480
	ds_read_b128 v[188:191], v150 offset:21504
	ds_read_b128 v[192:195], v150 offset:22528
	ds_read_b128 v[196:199], v150 offset:23552
	global_load_lds_dwordx4 v128, s[44:45]
	s_mov_b32 m0, s56
	s_nop 0
	global_load_lds_dwordx4 v132, s[44:45]
	s_barrier
	s_waitcnt lgkmcnt(0)
	v_mfma_f32_16x16x32_bf16 v[60:63], v[152:155], v[168:171], v[60:63]
	v_mfma_f32_16x16x32_bf16 v[60:63], v[156:159], v[172:175], v[60:63]
	v_mfma_f32_16x16x32_bf16 v[56:59], v[164:167], v[172:175], v[56:59]
	v_mfma_f32_16x16x32_bf16 v[56:59], v[160:163], v[168:171], v[56:59]
	v_mfma_f32_16x16x32_bf16 v[40:43], v[160:163], v[176:179], v[40:43]
	v_mfma_f32_16x16x32_bf16 v[40:43], v[164:167], v[180:183], v[40:43]
	v_mfma_f32_16x16x32_bf16 v[44:47], v[156:159], v[180:183], v[44:47]
	v_mfma_f32_16x16x32_bf16 v[44:47], v[152:155], v[176:179], v[44:47]
	v_mfma_f32_16x16x32_bf16 v[28:31], v[152:155], v[184:187], v[28:31]
	v_mfma_f32_16x16x32_bf16 v[28:31], v[156:159], v[188:191], v[28:31]
	v_mfma_f32_16x16x32_bf16 v[24:27], v[164:167], v[188:191], v[24:27]
	v_mfma_f32_16x16x32_bf16 v[24:27], v[160:163], v[184:187], v[24:27]
	v_mfma_f32_16x16x32_bf16 v[8:11], v[160:163], v[192:195], v[8:11]
	v_mfma_f32_16x16x32_bf16 v[8:11], v[164:167], v[196:199], v[8:11]
	v_mfma_f32_16x16x32_bf16 v[12:15], v[156:159], v[196:199], v[12:15]
	v_mfma_f32_16x16x32_bf16 v[12:15], v[152:155], v[192:195], v[12:15]
	s_barrier
	s_add_u32 s72, s42, 0x40000
	s_addc_u32 s73, s43, 0
	s_add_i32 s71, s64, s51
	s_mov_b32 m0, s71
	s_nop 0
	global_load_lds_dwordx4 v130, s[72:73]
	s_add_i32 m0, s71, 0x2000
	s_nop 0
	global_load_lds_dwordx4 v134, s[72:73]
	s_waitcnt vmcnt(6)
	s_barrier
; #define PG8_STAGE(bufoff, gbase, voff) do { _Pragma("unroll") for (int _i = 0; _i < 2; ++_i) \
;         __builtin_amdgcn_global_load_lds((const unsigned*)((const char*)(gbase) + (voff)[_i]), (LAS unsigned*)(lds + (bufoff) + ldsw + _i * 8192), 16, 0, 0); } while (0)
; #define PG8_LDA(dst, b, h) do { _Pragma("unroll") for (int m = 0; m < 4; ++m) _Pragma("unroll") for (int k = 0; k < 2; ++k) dst[m][k] = *(const LAS bf16x8*)(lds + PG8_SA(b, h) + aoff + m * 2048 + k * 1024); } while (0)
; #define PG8_LDB(dst, b, h) do { _Pragma("unroll") for (int n = 0; n < 2; ++n) _Pragma("unroll") for (int k = 0; k < 2; ++k) dst[n][k] = *(const LAS bf16x8*)(lds + PG8_SB(b, h) + boff + n * 2048 + k * 1024); } while (0)
; #define PG8_MMA(ai, bj, At, Bt) do { __builtin_amdgcn_s_setprio(1); _Pragma("unroll") for (int m = 0; m < 4; ++m) _Pragma("unroll") for (int n = 0; n < 2; ++n) _Pragma("unroll") for (int k = 0; k < 2; ++k) \
;         acc[ai][bj][m][n] = __builtin_amdgcn_mfma_f32_16x16x32_bf16(Bt[n][k], At[m][k], acc[ai][bj][m][n], 0, 0, 0); __builtin_amdgcn_s_setprio(0); } while (0)
; #define PG8_WAIT_V(n) asm volatile("s_waitcnt vmcnt(" #n ")" ::: "memory")
; #define PG8_WAIT_L(n) asm volatile("s_waitcnt lgkmcnt(" #n ")" ::: "memory")
; #define PG8_BAR __builtin_amdgcn_s_barrier()
; #define PG8_SCHED __builtin_amdgcn_sched_barrier(0)
; template <class Epi, class Ptrs>
; __device__ __forceinline__ void gemm_phase(LAS unsigned char* lds, const int K, const StaticOrder& S, const Ptrs& P, const Epi& E) {
;     ...
;             PG8_WAIT_V(6); PG8_BAR; PG8_MMA(1, 1, At, B1); PG8_BAR;
;             PG8_LDB(B0, 1, 0); PG8_SCHED; PG8_LDA(At, 1, 0); PG8_STAGE(PG8_SA(0, 1), a2 + hstep, voffA);
;             PG8_WAIT_L(8); PG8_BAR; PG8_WAIT_L(0); PG8_MMA(0, 0, At, B0); PG8_BAR; PG8_SCHED;
;             PG8_LDB(B1, 1, 1); PG8_STAGE(PG8_SB(1, 0), b3, voffB);
;             PG8_BAR; PG8_WAIT_L(0); PG8_MMA(0, 1, At, B1); PG8_BAR;
;             PG8_LDA(At, 1, 1); PG8_STAGE(PG8_SA(1, 0), a3, voffA);
;             PG8_BAR; PG8_WAIT_L(0); PG8_MMA(1, 0, At, B0); PG8_BAR; PG8_SCHED;
;             PG8_STAGE(PG8_SB(1, 1), b3 + hstep, voffB);
	v_mfma_f32_16x16x32_bf16 v[52:55], v[200:203], v[168:171], v[52:55]
	v_mfma_f32_16x16x32_bf16 v[52:55], v[204:207], v[172:175], v[52:55]
	v_mfma_f32_16x16x32_bf16 v[48:51], v[214:217], v[172:175], v[48:51]
	v_mfma_f32_16x16x32_bf16 v[48:51], v[210:213], v[168:171], v[48:51]
	v_mfma_f32_16x16x32_bf16 v[32:35], v[210:213], v[176:179], v[32:35]
	v_mfma_f32_16x16x32_bf16 v[32:35], v[214:217], v[180:183], v[32:35]
	v_mfma_f32_16x16x32_bf16 v[36:39], v[204:207], v[180:183], v[36:39]
	v_mfma_f32_16x16x32_bf16 v[36:39], v[200:203], v[176:179], v[36:39]
	v_mfma_f32_16x16x32_bf16 v[20:23], v[200:203], v[184:187], v[20:23]
	v_mfma_f32_16x16x32_bf16 v[20:23], v[204:207], v[188:191], v[20:23]
	v_mfma_f32_16x16x32_bf16 v[16:19], v[214:217], v[188:191], v[16:19]
	v_mfma_f32_16x16x32_bf16 v[16:19], v[210:213], v[184:187], v[16:19]
	v_mfma_f32_16x16x32_bf16 v[0:3], v[210:213], v[192:195], v[0:3]
	v_mfma_f32_16x16x32_bf16 v[0:3], v[214:217], v[196:199], v[0:3]
	v_mfma_f32_16x16x32_bf16 v[4:7], v[204:207], v[196:199], v[4:7]
	v_mfma_f32_16x16x32_bf16 v[4:7], v[200:203], v[192:195], v[4:7]
	s_barrier
	s_add_i32 s71, 0, 0x18000
	ds_read_b128 v[152:155], v252
	ds_read_b128 v[156:159], v252 offset:1024
	ds_read_b128 v[160:163], v252 offset:2048
	ds_read_b128 v[164:167], v252 offset:3072
	s_add_u32 s44, s44, 0x40000
	s_addc_u32 s45, s45, 0
	s_mov_b32 m0, s57
	ds_read_b128 v[168:171], v150 offset:32768
	ds_read_b128 v[172:175], v150 offset:33792
	ds_read_b128 v[176:179], v150 offset:34816
	ds_read_b128 v[180:183], v150 offset:35840
	ds_read_b128 v[184:187], v150 offset:36864
	ds_read_b128 v[188:191], v150 offset:37888
	ds_read_b128 v[192:195], v150 offset:38912
	ds_read_b128 v[196:199], v150 offset:39936
	global_load_lds_dwordx4 v128, s[44:45]
	s_mov_b32 m0, s58
	s_nop 0
	global_load_lds_dwordx4 v132, s[44:45]
	s_waitcnt lgkmcnt(8)
	s_barrier
	s_waitcnt lgkmcnt(0)
	v_mfma_f32_16x16x32_bf16 v[124:127], v[152:155], v[168:171], v[124:127]
	v_mfma_f32_16x16x32_bf16 v[124:127], v[156:159], v[172:175], v[124:127]
	v_mfma_f32_16x16x32_bf16 v[120:123], v[164:167], v[172:175], v[120:123]
	v_mfma_f32_16x16x32_bf16 v[120:123], v[160:163], v[168:171], v[120:123]
	v_mfma_f32_16x16x32_bf16 v[104:107], v[160:163], v[176:179], v[104:107]
	v_mfma_f32_16x16x32_bf16 v[104:107], v[164:167], v[180:183], v[104:107]
	v_mfma_f32_16x16x32_bf16 v[108:111], v[156:159], v[180:183], v[108:111]
	v_mfma_f32_16x16x32_bf16 v[108:111], v[152:155], v[176:179], v[108:111]
	v_mfma_f32_16x16x32_bf16 v[92:95], v[152:155], v[184:187], v[92:95]
	v_mfma_f32_16x16x32_bf16 v[92:95], v[156:159], v[188:191], v[92:95]
	v_mfma_f32_16x16x32_bf16 v[88:91], v[164:167], v[188:191], v[88:91]
	v_mfma_f32_16x16x32_bf16 v[88:91], v[160:163], v[184:187], v[88:91]
	v_mfma_f32_16x16x32_bf16 v[72:75], v[160:163], v[192:195], v[72:75]
	v_mfma_f32_16x16x32_bf16 v[72:75], v[164:167], v[196:199], v[72:75]
	v_mfma_f32_16x16x32_bf16 v[76:79], v[156:159], v[196:199], v[76:79]
	v_mfma_f32_16x16x32_bf16 v[76:79], v[152:155], v[192:195], v[76:79]
	s_barrier
	s_add_i32 s44, 0, 0x1c000
	s_add_i32 s45, s71, s51
	s_mov_b32 m0, s45
	ds_read_b128 v[200:203], v253
	ds_read_b128 v[204:207], v253 offset:1024
	ds_read_b128 v[210:213], v253 offset:2048
	ds_read_b128 v[214:217], v253 offset:3072
	global_load_lds_dwordx4 v130, s[76:77]
	s_add_i32 m0, s45, 0x2000
	s_nop 0
	global_load_lds_dwordx4 v134, s[76:77]
	s_barrier
	s_waitcnt lgkmcnt(0)
	v_mfma_f32_16x16x32_bf16 v[116:119], v[200:203], v[168:171], v[116:119]
	v_mfma_f32_16x16x32_bf16 v[116:119], v[204:207], v[172:175], v[116:119]
	v_mfma_f32_16x16x32_bf16 v[112:115], v[214:217], v[172:175], v[112:115]
	v_mfma_f32_16x16x32_bf16 v[112:115], v[210:213], v[168:171], v[112:115]
	v_mfma_f32_16x16x32_bf16 v[96:99], v[210:213], v[176:179], v[96:99]
	v_mfma_f32_16x16x32_bf16 v[96:99], v[214:217], v[180:183], v[96:99]
	v_mfma_f32_16x16x32_bf16 v[100:103], v[204:207], v[180:183], v[100:103]
	v_mfma_f32_16x16x32_bf16 v[100:103], v[200:203], v[176:179], v[100:103]
	v_mfma_f32_16x16x32_bf16 v[84:87], v[200:203], v[184:187], v[84:87]
	v_mfma_f32_16x16x32_bf16 v[84:87], v[204:207], v[188:191], v[84:87]
	v_mfma_f32_16x16x32_bf16 v[80:83], v[214:217], v[188:191], v[80:83]
	v_mfma_f32_16x16x32_bf16 v[80:83], v[210:213], v[184:187], v[80:83]
	v_mfma_f32_16x16x32_bf16 v[64:67], v[210:213], v[192:195], v[64:67]
	v_mfma_f32_16x16x32_bf16 v[64:67], v[214:217], v[196:199], v[64:67]
	v_mfma_f32_16x16x32_bf16 v[68:71], v[204:207], v[196:199], v[68:71]
	v_mfma_f32_16x16x32_bf16 v[68:71], v[200:203], v[192:195], v[68:71]
	s_barrier
	s_mov_b32 m0, s61
	ds_read_b128 v[168:171], v150 offset:49152
	ds_read_b128 v[172:175], v150 offset:50176
	ds_read_b128 v[176:179], v150 offset:51200
	ds_read_b128 v[180:183], v150 offset:52224
	ds_read_b128 v[184:187], v150 offset:53248
	ds_read_b128 v[188:191], v150 offset:54272
	ds_read_b128 v[192:195], v150 offset:55296
	ds_read_b128 v[196:199], v150 offset:56320
	global_load_lds_dwordx4 v128, s[78:79]
	s_mov_b32 m0, s62
	s_nop 0
	global_load_lds_dwordx4 v132, s[78:79]
	s_barrier
	s_waitcnt lgkmcnt(0)
	v_mfma_f32_16x16x32_bf16 v[60:63], v[152:155], v[168:171], v[60:63]
	v_mfma_f32_16x16x32_bf16 v[60:63], v[156:159], v[172:175], v[60:63]
	v_mfma_f32_16x16x32_bf16 v[56:59], v[164:167], v[172:175], v[56:59]
	v_mfma_f32_16x16x32_bf16 v[56:59], v[160:163], v[168:171], v[56:59]
	v_mfma_f32_16x16x32_bf16 v[40:43], v[160:163], v[176:179], v[40:43]
	v_mfma_f32_16x16x32_bf16 v[40:43], v[164:167], v[180:183], v[40:43]
	v_mfma_f32_16x16x32_bf16 v[44:47], v[156:159], v[180:183], v[44:47]
	v_mfma_f32_16x16x32_bf16 v[44:47], v[152:155], v[176:179], v[44:47]
	v_mfma_f32_16x16x32_bf16 v[28:31], v[152:155], v[184:187], v[28:31]
	v_mfma_f32_16x16x32_bf16 v[28:31], v[156:159], v[188:191], v[28:31]
	v_mfma_f32_16x16x32_bf16 v[24:27], v[164:167], v[188:191], v[24:27]
	v_mfma_f32_16x16x32_bf16 v[24:27], v[160:163], v[184:187], v[24:27]
	v_mfma_f32_16x16x32_bf16 v[8:11], v[160:163], v[192:195], v[8:11]
	v_mfma_f32_16x16x32_bf16 v[8:11], v[164:167], v[196:199], v[8:11]
	v_mfma_f32_16x16x32_bf16 v[12:15], v[156:159], v[196:199], v[12:15]
	v_mfma_f32_16x16x32_bf16 v[12:15], v[152:155], v[192:195], v[12:15]
	s_barrier
; __device__ __forceinline__ unsigned cvt_pk_bf16(float lo, float hi) { unsigned r; asm volatile("v_cvt_pk_bf16_f32 %0, %1, %2" : "=v"(r) : "v"(lo), "v"(hi)); return r; }
; #define PG8_STAGE(bufoff, gbase, voff) do { _Pragma("unroll") for (int _i = 0; _i < 2; ++_i) \
;         __builtin_amdgcn_global_load_lds((const unsigned*)((const char*)(gbase) + (voff)[_i]), (LAS unsigned*)(lds + (bufoff) + ldsw + _i * 8192), 16, 0, 0); } while (0)
; #define PG8_MMA(ai, bj, At, Bt) do { __builtin_amdgcn_s_setprio(1); _Pragma("unroll") for (int m = 0; m < 4; ++m) _Pragma("unroll") for (int n = 0; n < 2; ++n) _Pragma("unroll") for (int k = 0; k < 2; ++k) \
;         acc[ai][bj][m][n] = __builtin_amdgcn_mfma_f32_16x16x32_bf16(Bt[n][k], At[m][k], acc[ai][bj][m][n], 0, 0, 0); __builtin_amdgcn_s_setprio(0); } while (0)
; #define PG8_WAIT_V(n) asm volatile("s_waitcnt vmcnt(" #n ")" ::: "memory")
; #define PG8_BAR __builtin_amdgcn_s_barrier()
; template <class Epi, class Ptrs>
; __device__ __forceinline__ void gemm_phase(LAS unsigned char* lds, const int K, const StaticOrder& S, const Ptrs& P, const Epi& E) {
;     ...
;             PG8_STAGE(PG8_SB(1, 1), b3 + hstep, voffB);
;             PG8_WAIT_V(6); PG8_BAR; PG8_MMA(1, 1, At, B1); PG8_BAR;
;     __device__ __forceinline__ void operator()(const f32x4 (&acc)[2][2][4][2], const Unit& u, int ui, int wr, int wc, int fr, int fq) const {
;         const int row0 = u.pm * 256 + wr * 64 + fr, col0 = u.pn * 256 + wc * 32 + 8 * fq;
; #pragma unroll
;         for (int ai = 0; ai < 2; ++ai)
; #pragma unroll
;             for (int m = 0; m < 4; ++m) { bf16_t* rowp = hid + (size_t)(row0 + ai * 128 + m * 16) * DFF + col0;
; #pragma unroll
;                 for (int bj = 0; bj < 2; ++bj) { f32x4 v0 = acc[ai][bj][m][0], v1 = acc[ai][bj][m][1];
; #pragma unroll
;                     for (int j = 0; j < 4; ++j) { const float a = fmaxf(v0[j], 0.f), b = fmaxf(v1[j], 0.f); v0[j] = a * a; v1[j] = b * b; }
;                     u32x4 w; w.x = cvt_pk_bf16(v0[0], v0[1]); w.y = cvt_pk_bf16(v0[2], v0[3]); w.z = cvt_pk_bf16(v1[0], v1[1]); w.w = cvt_pk_bf16(v1[2], v1[3]);
;                     *(u32x4*)(rowp + bj * 128) = w; } }
	s_add_u32 s42, s42, 0x40080
	s_addc_u32 s43, s43, 0
	s_add_i32 s44, s44, s51
	s_mov_b32 m0, s44
	s_nop 0
	global_load_lds_dwordx4 v130, s[42:43]
	s_add_i32 m0, s44, 0x2000
	s_nop 0
	global_load_lds_dwordx4 v134, s[42:43]
	s_waitcnt vmcnt(6)
	s_barrier
	v_mfma_f32_16x16x32_bf16 v[52:55], v[200:203], v[168:171], v[52:55]
	v_mfma_f32_16x16x32_bf16 v[52:55], v[204:207], v[172:175], v[52:55]
	v_mfma_f32_16x16x32_bf16 v[48:51], v[214:217], v[172:175], v[48:51]
	v_mfma_f32_16x16x32_bf16 v[48:51], v[210:213], v[168:171], v[48:51]
	v_mfma_f32_16x16x32_bf16 v[32:35], v[210:213], v[176:179], v[32:35]
	v_mfma_f32_16x16x32_bf16 v[32:35], v[214:217], v[180:183], v[32:35]
	v_mfma_f32_16x16x32_bf16 v[36:39], v[204:207], v[180:183], v[36:39]
	v_mfma_f32_16x16x32_bf16 v[36:39], v[200:203], v[176:179], v[36:39]
	v_mfma_f32_16x16x32_bf16 v[20:23], v[200:203], v[184:187], v[20:23]
	v_mfma_f32_16x16x32_bf16 v[20:23], v[204:207], v[188:191], v[20:23]
	v_mfma_f32_16x16x32_bf16 v[16:19], v[214:217], v[188:191], v[16:19]
	v_mfma_f32_16x16x32_bf16 v[16:19], v[210:213], v[184:187], v[16:19]
	v_mfma_f32_16x16x32_bf16 v[0:3], v[210:213], v[192:195], v[0:3]
	v_mfma_f32_16x16x32_bf16 v[0:3], v[214:217], v[196:199], v[0:3]
	v_mfma_f32_16x16x32_bf16 v[4:7], v[204:207], v[196:199], v[4:7]
	v_mfma_f32_16x16x32_bf16 v[4:7], v[200:203], v[192:195], v[4:7]
	s_barrier
	s_add_i32 s70, s70, 2
	s_add_u32 s40, s40, 0x100
	s_addc_u32 s41, s41, 0
	s_add_u32 s23, s23, 0x100
	s_addc_u32 s25, s25, 0
	s_cmp_gt_u32 s70, 13
	s_cbranch_scc0 .LBB0_433
	s_cmpk_lt_u32 s46, 0x100
	s_cbranch_scc0 .Ltsync_a2
	s_barrier
.Ltsync_a2:
	v_lshl_add_u32 v152, s38, 8, v146
	v_max_f32_e32 v120, 0, v120
	v_ashrrev_i32_e32 v153, 31, v152
	v_max_f32_e32 v121, 0, v121
	v_max_f32_e32 v122, 0, v122
	v_lshl_or_b32 v144, s69, 8, v148
	v_lshlrev_b64 v[154:155], 13, v[152:153]
	v_mul_f32_e32 v153, v120, v120
	v_max_f32_e32 v120, 0, v125
	v_ashrrev_i32_e32 v145, 31, v144
	v_max_f32_e32 v124, 0, v124
	v_mul_f32_e32 v125, v121, v121
	v_max_f32_e32 v121, 0, v126
	v_mul_f32_e32 v126, v122, v122
	v_max_f32_e32 v122, 0, v127
	v_max_f32_e32 v123, 0, v123
	v_lshl_add_u64 v[154:155], s[10:11], 0, v[154:155]
	v_lshlrev_b64 v[156:157], 1, v[144:145]
	v_mul_f32_e32 v120, v120, v120
	v_max_f32_e32 v112, 0, v112
	v_lshl_add_u64 v[144:145], v[154:155], 0, v[156:157]
	v_mul_f32_e32 v124, v124, v124
	v_mul_f32_e32 v121, v121, v121
	v_mul_f32_e32 v122, v122, v122
	v_mul_f32_e32 v123, v123, v123
	v_cvt_pk_bf16_f32 v120, v124, v120
	v_max_f32_e32 v113, 0, v113
	v_max_f32_e32 v114, 0, v114
	v_cvt_pk_bf16_f32 v121, v121, v122
	v_cvt_pk_bf16_f32 v122, v153, v125
	v_cvt_pk_bf16_f32 v123, v126, v123
	global_store_dwordx4 v[144:145], v[120:123], off
	s_nop 1
	v_mul_f32_e32 v120, v112, v112
	v_max_f32_e32 v112, 0, v117
	v_max_f32_e32 v116, 0, v116
	v_mul_f32_e32 v117, v113, v113
	v_max_f32_e32 v113, 0, v118
	v_mul_f32_e32 v118, v114, v114
	v_max_f32_e32 v114, 0, v119
	v_max_f32_e32 v115, 0, v115
	v_mul_f32_e32 v112, v112, v112
	v_mul_f32_e32 v116, v116, v116
	v_mul_f32_e32 v113, v113, v113
	v_mul_f32_e32 v114, v114, v114
	v_mul_f32_e32 v115, v115, v115
	v_cvt_pk_bf16_f32 v112, v116, v112
	v_max_f32_e32 v104, 0, v104
	v_cvt_pk_bf16_f32 v113, v113, v114
	v_cvt_pk_bf16_f32 v114, v120, v117
	v_cvt_pk_bf16_f32 v115, v118, v115
	global_store_dwordx4 v[144:145], v[112:115], off offset:256
	s_nop 0
	v_max_f32_e32 v105, 0, v105
	v_or_b32_e32 v112, 16, v152
	v_max_f32_e32 v106, 0, v106
	v_ashrrev_i32_e32 v113, 31, v112
	v_mul_f32_e32 v114, v104, v104
	v_max_f32_e32 v104, 0, v109
	v_lshlrev_b64 v[112:113], 13, v[112:113]
	v_max_f32_e32 v108, 0, v108
	v_mul_f32_e32 v109, v105, v105
	v_max_f32_e32 v105, 0, v110
	v_mul_f32_e32 v110, v106, v106
	v_max_f32_e32 v106, 0, v111
	v_max_f32_e32 v107, 0, v107
	v_lshl_add_u64 v[112:113], s[10:11], 0, v[112:113]
	v_mul_f32_e32 v104, v104, v104
	v_max_f32_e32 v96, 0, v96
	v_lshl_add_u64 v[112:113], v[112:113], 0, v[156:157]
	v_mul_f32_e32 v108, v108, v108
	v_mul_f32_e32 v105, v105, v105
	v_mul_f32_e32 v106, v106, v106
	v_mul_f32_e32 v107, v107, v107
	v_cvt_pk_bf16_f32 v104, v108, v104
	v_max_f32_e32 v97, 0, v97
	v_max_f32_e32 v98, 0, v98
	v_cvt_pk_bf16_f32 v105, v105, v106
	v_cvt_pk_bf16_f32 v106, v114, v109
	v_cvt_pk_bf16_f32 v107, v110, v107
	global_store_dwordx4 v[112:113], v[104:107], off
	s_nop 1
	v_mul_f32_e32 v104, v96, v96
	v_max_f32_e32 v96, 0, v101
	v_max_f32_e32 v100, 0, v100
	v_mul_f32_e32 v101, v97, v97
	v_max_f32_e32 v97, 0, v102
	v_mul_f32_e32 v102, v98, v98
	v_max_f32_e32 v98, 0, v103
	v_max_f32_e32 v99, 0, v99
	v_mul_f32_e32 v96, v96, v96
	v_mul_f32_e32 v100, v100, v100
	v_mul_f32_e32 v97, v97, v97
	v_mul_f32_e32 v98, v98, v98
	v_mul_f32_e32 v99, v99, v99
	v_cvt_pk_bf16_f32 v96, v100, v96
	v_max_f32_e32 v88, 0, v88
	v_cvt_pk_bf16_f32 v97, v97, v98
	v_cvt_pk_bf16_f32 v98, v104, v101
	v_cvt_pk_bf16_f32 v99, v102, v99
	global_store_dwordx4 v[112:113], v[96:99], off offset:256
	s_nop 0
	v_max_f32_e32 v89, 0, v89
	v_or_b32_e32 v96, 32, v152
	v_max_f32_e32 v90, 0, v90
	v_ashrrev_i32_e32 v97, 31, v96
	v_mul_f32_e32 v98, v88, v88
	v_max_f32_e32 v88, 0, v93
	v_lshlrev_b64 v[96:97], 13, v[96:97]
	v_max_f32_e32 v92, 0, v92
	v_mul_f32_e32 v93, v89, v89
	v_max_f32_e32 v89, 0, v94
	v_mul_f32_e32 v94, v90, v90
	v_max_f32_e32 v90, 0, v95
	v_max_f32_e32 v91, 0, v91
	v_lshl_add_u64 v[96:97], s[10:11], 0, v[96:97]
	v_mul_f32_e32 v88, v88, v88
	v_max_f32_e32 v80, 0, v80
	v_lshl_add_u64 v[96:97], v[96:97], 0, v[156:157]
	v_mul_f32_e32 v92, v92, v92
	v_mul_f32_e32 v89, v89, v89
	v_mul_f32_e32 v90, v90, v90
	v_mul_f32_e32 v91, v91, v91
	v_cvt_pk_bf16_f32 v88, v92, v88
	v_max_f32_e32 v81, 0, v81
	v_max_f32_e32 v82, 0, v82
; __device__ __forceinline__ unsigned cvt_pk_bf16(float lo, float hi) { unsigned r; asm volatile("v_cvt_pk_bf16_f32 %0, %1, %2" : "=v"(r) : "v"(lo), "v"(hi)); return r; }
;     __device__ __forceinline__ void operator()(const f32x4 (&acc)[2][2][4][2], const Unit& u, int ui, int wr, int wc, int fr, int fq) const {
;     ...
;         for (int ai = 0; ai < 2; ++ai)
; #pragma unroll
;             for (int m = 0; m < 4; ++m) { bf16_t* rowp = hid + (size_t)(row0 + ai * 128 + m * 16) * DFF + col0;
; #pragma unroll
;                 for (int bj = 0; bj < 2; ++bj) { f32x4 v0 = acc[ai][bj][m][0], v1 = acc[ai][bj][m][1];
; #pragma unroll
;                     for (int j = 0; j < 4; ++j) { const float a = fmaxf(v0[j], 0.f), b = fmaxf(v1[j], 0.f); v0[j] = a * a; v1[j] = b * b; }
;                     u32x4 w; w.x = cvt_pk_bf16(v0[0], v0[1]); w.y = cvt_pk_bf16(v0[2], v0[3]); w.z = cvt_pk_bf16(v1[0], v1[1]); w.w = cvt_pk_bf16(v1[2], v1[3]);
;                     *(u32x4*)(rowp + bj * 128) = w; } }
	v_cvt_pk_bf16_f32 v89, v89, v90
	v_cvt_pk_bf16_f32 v90, v98, v93
	v_cvt_pk_bf16_f32 v91, v94, v91
	global_store_dwordx4 v[96:97], v[88:91], off
	s_nop 1
	v_mul_f32_e32 v88, v80, v80
	v_max_f32_e32 v80, 0, v85
	v_max_f32_e32 v84, 0, v84
	v_mul_f32_e32 v85, v81, v81
	v_max_f32_e32 v81, 0, v86
	v_mul_f32_e32 v86, v82, v82
	v_max_f32_e32 v82, 0, v87
	v_max_f32_e32 v83, 0, v83
	v_mul_f32_e32 v80, v80, v80
	v_mul_f32_e32 v84, v84, v84
	v_mul_f32_e32 v81, v81, v81
	v_mul_f32_e32 v82, v82, v82
	v_mul_f32_e32 v83, v83, v83
	v_cvt_pk_bf16_f32 v80, v84, v80
	v_max_f32_e32 v72, 0, v72
	v_cvt_pk_bf16_f32 v81, v81, v82
	v_cvt_pk_bf16_f32 v82, v88, v85
	v_cvt_pk_bf16_f32 v83, v86, v83
	global_store_dwordx4 v[96:97], v[80:83], off offset:256
	s_nop 0
	v_max_f32_e32 v73, 0, v73
	v_or_b32_e32 v80, 48, v152
	v_max_f32_e32 v74, 0, v74
	v_ashrrev_i32_e32 v81, 31, v80
	v_mul_f32_e32 v82, v72, v72
	v_max_f32_e32 v72, 0, v77
	v_lshlrev_b64 v[80:81], 13, v[80:81]
	v_max_f32_e32 v76, 0, v76
	v_mul_f32_e32 v77, v73, v73
	v_max_f32_e32 v73, 0, v78
	v_mul_f32_e32 v78, v74, v74
	v_max_f32_e32 v74, 0, v79
	v_max_f32_e32 v75, 0, v75
	v_lshl_add_u64 v[80:81], s[10:11], 0, v[80:81]
	v_mul_f32_e32 v72, v72, v72
	v_max_f32_e32 v64, 0, v64
	v_max_f32_e32 v65, 0, v65
	v_max_f32_e32 v66, 0, v66
	v_lshl_add_u64 v[80:81], v[80:81], 0, v[156:157]
	v_mul_f32_e32 v76, v76, v76
	v_mul_f32_e32 v73, v73, v73
	v_mul_f32_e32 v74, v74, v74
	v_mul_f32_e32 v75, v75, v75
	v_cvt_pk_bf16_f32 v72, v76, v72
	v_cvt_pk_bf16_f32 v73, v73, v74
	v_cvt_pk_bf16_f32 v74, v82, v77
	v_cvt_pk_bf16_f32 v75, v78, v75
	global_store_dwordx4 v[80:81], v[72:75], off
	v_max_f32_e32 v68, 0, v68
	v_max_f32_e32 v67, 0, v67
	v_mul_f32_e32 v72, v64, v64
	v_max_f32_e32 v64, 0, v69
	v_mul_f32_e32 v69, v65, v65
	v_max_f32_e32 v65, 0, v70
	v_mul_f32_e32 v70, v66, v66
	v_max_f32_e32 v66, 0, v71
	v_mul_f32_e32 v64, v64, v64
	v_mul_f32_e32 v65, v65, v65
	v_mul_f32_e32 v66, v66, v66
	v_max_f32_e32 v56, 0, v56
	v_mul_f32_e32 v68, v68, v68
	v_mul_f32_e32 v67, v67, v67
	v_cvt_pk_bf16_f32 v64, v68, v64
	v_cvt_pk_bf16_f32 v65, v65, v66
	v_cvt_pk_bf16_f32 v66, v72, v69
	v_max_f32_e32 v57, 0, v57
	v_max_f32_e32 v58, 0, v58
	v_cvt_pk_bf16_f32 v67, v70, v67
	global_store_dwordx4 v[80:81], v[64:67], off offset:256
	s_nop 0
	v_max_f32_e32 v60, 0, v60
	v_mul_f32_e32 v66, v56, v56
	v_max_f32_e32 v56, 0, v61
	v_mul_f32_e32 v61, v57, v57
	v_max_f32_e32 v57, 0, v62
	v_mul_f32_e32 v62, v58, v58
	v_max_f32_e32 v58, 0, v63
	v_mul_f32_e32 v60, v60, v60
	v_mul_f32_e32 v56, v56, v56
	v_max_f32_e32 v59, 0, v59
	v_mul_f32_e32 v57, v57, v57
	v_mul_f32_e32 v58, v58, v58
	v_cvt_pk_bf16_f32 v56, v60, v56
	v_add_co_u32_e32 v60, vcc, s65, v144
	v_max_f32_e32 v48, 0, v48
	v_max_f32_e32 v49, 0, v49
	v_max_f32_e32 v50, 0, v50
	v_mul_f32_e32 v59, v59, v59
	v_cvt_pk_bf16_f32 v57, v57, v58
	v_cvt_pk_bf16_f32 v58, v66, v61
	v_addc_co_u32_e32 v61, vcc, 0, v145, vcc
	v_cvt_pk_bf16_f32 v59, v62, v59
	global_store_dwordx4 v[60:61], v[56:59], off
	v_max_f32_e32 v52, 0, v52
	v_max_f32_e32 v51, 0, v51
	v_mul_f32_e32 v56, v48, v48
	v_max_f32_e32 v48, 0, v53
	v_mul_f32_e32 v53, v49, v49
	v_max_f32_e32 v49, 0, v54
	v_mul_f32_e32 v54, v50, v50
	v_max_f32_e32 v50, 0, v55
	v_mul_f32_e32 v48, v48, v48
	v_mul_f32_e32 v49, v49, v49
	v_mul_f32_e32 v50, v50, v50
	v_max_f32_e32 v40, 0, v40
	v_lshl_add_u64 v[64:65], v[144:145], 0, s[14:15]
	v_mul_f32_e32 v52, v52, v52
	v_mul_f32_e32 v51, v51, v51
	v_cvt_pk_bf16_f32 v48, v52, v48
	v_cvt_pk_bf16_f32 v49, v49, v50
	v_cvt_pk_bf16_f32 v50, v56, v53
	v_max_f32_e32 v41, 0, v41
	v_max_f32_e32 v42, 0, v42
	v_cvt_pk_bf16_f32 v51, v54, v51
	global_store_dwordx4 v[64:65], v[48:51], off offset:256
	s_nop 0
	v_max_f32_e32 v44, 0, v44
	v_mul_f32_e32 v50, v40, v40
	v_max_f32_e32 v40, 0, v45
	v_mul_f32_e32 v45, v41, v41
	v_max_f32_e32 v41, 0, v46
	v_mul_f32_e32 v46, v42, v42
	v_max_f32_e32 v42, 0, v47
	v_mul_f32_e32 v44, v44, v44
	v_mul_f32_e32 v40, v40, v40
	v_max_f32_e32 v43, 0, v43
	v_mul_f32_e32 v41, v41, v41
	v_mul_f32_e32 v42, v42, v42
	v_cvt_pk_bf16_f32 v40, v44, v40
	v_add_co_u32_e32 v44, vcc, s66, v144
	v_max_f32_e32 v32, 0, v32
	v_max_f32_e32 v33, 0, v33
	v_max_f32_e32 v34, 0, v34
	v_mul_f32_e32 v43, v43, v43
	v_cvt_pk_bf16_f32 v41, v41, v42
	v_cvt_pk_bf16_f32 v42, v50, v45
	v_addc_co_u32_e32 v45, vcc, 0, v145, vcc
	v_cvt_pk_bf16_f32 v43, v46, v43
	global_store_dwordx4 v[44:45], v[40:43], off
	v_max_f32_e32 v36, 0, v36
	v_max_f32_e32 v35, 0, v35
	v_mul_f32_e32 v40, v32, v32
	v_max_f32_e32 v32, 0, v37
	v_mul_f32_e32 v37, v33, v33
	v_max_f32_e32 v33, 0, v38
	v_mul_f32_e32 v38, v34, v34
	v_max_f32_e32 v34, 0, v39
	v_mul_f32_e32 v32, v32, v32
	v_mul_f32_e32 v33, v33, v33
	v_mul_f32_e32 v34, v34, v34
	v_max_f32_e32 v24, 0, v24
	v_lshl_add_u64 v[48:49], v[144:145], 0, s[16:17]
	v_mul_f32_e32 v36, v36, v36
	v_mul_f32_e32 v35, v35, v35
	v_cvt_pk_bf16_f32 v32, v36, v32
	v_cvt_pk_bf16_f32 v33, v33, v34
	v_cvt_pk_bf16_f32 v34, v40, v37
	v_max_f32_e32 v25, 0, v25
	v_max_f32_e32 v26, 0, v26
	v_cvt_pk_bf16_f32 v35, v38, v35
; __device__ __forceinline__ unsigned cvt_pk_bf16(float lo, float hi) { unsigned r; asm volatile("v_cvt_pk_bf16_f32 %0, %1, %2" : "=v"(r) : "v"(lo), "v"(hi)); return r; }
;     __device__ __forceinline__ void operator()(const f32x4 (&acc)[2][2][4][2], const Unit& u, int ui, int wr, int wc, int fr, int fq) const {
;     ...
;         for (int ai = 0; ai < 2; ++ai)
; #pragma unroll
;             for (int m = 0; m < 4; ++m) { bf16_t* rowp = hid + (size_t)(row0 + ai * 128 + m * 16) * DFF + col0;
; #pragma unroll
;                 for (int bj = 0; bj < 2; ++bj) { f32x4 v0 = acc[ai][bj][m][0], v1 = acc[ai][bj][m][1];
; #pragma unroll
;                     for (int j = 0; j < 4; ++j) { const float a = fmaxf(v0[j], 0.f), b = fmaxf(v1[j], 0.f); v0[j] = a * a; v1[j] = b * b; }
;                     u32x4 w; w.x = cvt_pk_bf16(v0[0], v0[1]); w.y = cvt_pk_bf16(v0[2], v0[3]); w.z = cvt_pk_bf16(v1[0], v1[1]); w.w = cvt_pk_bf16(v1[2], v1[3]);
;                     *(u32x4*)(rowp + bj * 128) = w; } }
; __device__ __forceinline__ void xcd_barrier(const XcdBarrier& b) {
;     asm volatile("s_waitcnt vmcnt(0)" ::: "memory");
;     __syncthreads();
;     if (threadIdx.x == 0) {
;         unsigned* bar = b.bar;
;         __builtin_amdgcn_s_waitcnt(0);
;         unsigned nloc = b.st[0], nx = b.st[1];
;         if (nloc == 0u) { xcd_barrier_complete(bar, b.x, nloc, nx); b.st[0] = nloc; b.st[1] = nx; }
	global_store_dwordx4 v[48:49], v[32:35], off offset:256
	s_nop 0
	v_max_f32_e32 v28, 0, v28
	v_mul_f32_e32 v34, v24, v24
	v_max_f32_e32 v24, 0, v29
	v_mul_f32_e32 v29, v25, v25
	v_max_f32_e32 v25, 0, v30
	v_mul_f32_e32 v30, v26, v26
	v_max_f32_e32 v26, 0, v31
	v_mul_f32_e32 v28, v28, v28
	v_mul_f32_e32 v24, v24, v24
	v_max_f32_e32 v27, 0, v27
	v_mul_f32_e32 v25, v25, v25
	v_mul_f32_e32 v26, v26, v26
	v_cvt_pk_bf16_f32 v24, v28, v24
	v_add_co_u32_e32 v28, vcc, s67, v144
	v_max_f32_e32 v16, 0, v16
	v_max_f32_e32 v17, 0, v17
	v_max_f32_e32 v18, 0, v18
	v_mul_f32_e32 v27, v27, v27
	v_cvt_pk_bf16_f32 v25, v25, v26
	v_cvt_pk_bf16_f32 v26, v34, v29
	v_addc_co_u32_e32 v29, vcc, 0, v145, vcc
	v_cvt_pk_bf16_f32 v27, v30, v27
	global_store_dwordx4 v[28:29], v[24:27], off
	v_max_f32_e32 v20, 0, v20
	v_max_f32_e32 v19, 0, v19
	v_mul_f32_e32 v24, v16, v16
	v_max_f32_e32 v16, 0, v21
	v_mul_f32_e32 v21, v17, v17
	v_max_f32_e32 v17, 0, v22
	v_mul_f32_e32 v22, v18, v18
	v_max_f32_e32 v18, 0, v23
	v_mul_f32_e32 v16, v16, v16
	v_mul_f32_e32 v17, v17, v17
	v_mul_f32_e32 v18, v18, v18
	v_max_f32_e32 v8, 0, v8
	v_lshl_add_u64 v[32:33], v[144:145], 0, s[18:19]
	v_mul_f32_e32 v20, v20, v20
	v_mul_f32_e32 v19, v19, v19
	v_cvt_pk_bf16_f32 v16, v20, v16
	v_cvt_pk_bf16_f32 v17, v17, v18
	v_cvt_pk_bf16_f32 v18, v24, v21
	v_max_f32_e32 v9, 0, v9
	v_max_f32_e32 v10, 0, v10
	v_cvt_pk_bf16_f32 v19, v22, v19
	global_store_dwordx4 v[32:33], v[16:19], off offset:256
	s_nop 0
	v_max_f32_e32 v12, 0, v12
	v_mul_f32_e32 v18, v8, v8
	v_max_f32_e32 v8, 0, v13
	v_mul_f32_e32 v13, v9, v9
	v_max_f32_e32 v9, 0, v14
	v_mul_f32_e32 v14, v10, v10
	v_max_f32_e32 v10, 0, v15
	v_mul_f32_e32 v12, v12, v12
	v_mul_f32_e32 v8, v8, v8
	v_max_f32_e32 v11, 0, v11
	v_mul_f32_e32 v9, v9, v9
	v_mul_f32_e32 v10, v10, v10
	v_cvt_pk_bf16_f32 v8, v12, v8
	v_add_co_u32_e32 v12, vcc, s68, v144
	v_max_f32_e32 v0, 0, v0
	v_max_f32_e32 v1, 0, v1
	v_max_f32_e32 v2, 0, v2
	v_mul_f32_e32 v11, v11, v11
	v_cvt_pk_bf16_f32 v9, v9, v10
	v_cvt_pk_bf16_f32 v10, v18, v13
	v_addc_co_u32_e32 v13, vcc, 0, v145, vcc
	v_cvt_pk_bf16_f32 v11, v14, v11
	global_store_dwordx4 v[12:13], v[8:11], off
	v_max_f32_e32 v3, 0, v3
	v_max_f32_e32 v4, 0, v4
	v_mul_f32_e32 v8, v0, v0
	v_max_f32_e32 v0, 0, v5
	v_mul_f32_e32 v5, v1, v1
	v_max_f32_e32 v1, 0, v6
	v_mul_f32_e32 v6, v2, v2
	v_max_f32_e32 v2, 0, v7
	v_lshl_add_u64 v[16:17], v[144:145], 0, s[20:21]
	v_mul_f32_e32 v0, v0, v0
	v_mul_f32_e32 v1, v1, v1
	v_mul_f32_e32 v2, v2, v2
	v_mul_f32_e32 v3, v3, v3
	s_and_b64 vcc, exec, s[4:5]
	s_mov_b32 s69, s22
	s_mov_b32 s38, s24
	s_mov_b64 s[40:41], s[0:1]
	s_mov_b64 s[42:43], s[36:37]
	v_mul_f32_e32 v4, v4, v4
	v_cvt_pk_bf16_f32 v0, v4, v0
	v_cvt_pk_bf16_f32 v1, v1, v2
	v_cvt_pk_bf16_f32 v2, v8, v5
	v_cvt_pk_bf16_f32 v3, v6, v3
	global_store_dwordx4 v[16:17], v[0:3], off offset:256
	s_cbranch_vccnz .Ltsync_x2
	s_cmpk_lt_u32 s46, 0x100
	s_cbranch_scc1 .LBB0_428
	s_barrier
	s_branch .LBB0_428
.Ltsync_x2:
	s_waitcnt vmcnt(0)
	s_setprio 0
	s_cmpk_gt_u32 s46, 0xff
	s_cbranch_scc1 .LBB0_437
.LBB0_437:
	s_barrier
.LBB0_438:
	s_nop 0
	s_nop 0
	s_nop 0
	s_nop 0
	s_nop 0
	s_nop 0
	s_nop 0
	s_nop 0
	s_nop 0
	s_nop 0
	s_nop 0
	s_nop 0
	s_nop 0
	s_nop 0
	s_nop 0
	s_nop 0
	s_nop 0
	s_nop 0
	s_nop 0
	s_nop 0
	s_nop 0
	s_nop 0
	s_nop 0
	s_nop 0
	s_nop 0
	s_nop 0
	s_nop 0
	s_nop 0
	s_nop 0
	s_nop 0
	s_nop 0
	s_nop 0
	s_nop 0
	s_cmp_gt_i32 s31, 5
	s_cselect_b64 s[0:1], -1, 0
	s_and_b64 s[4:5], s[6:7], s[0:1]
	s_andn2_b64 vcc, exec, s[4:5]
	s_cbranch_vccnz .LBB0_488
	s_waitcnt vmcnt(0)
	s_waitcnt vmcnt(0) lgkmcnt(0)
	s_barrier
	s_and_saveexec_b64 s[4:5], s[8:9]
	s_cbranch_execz .LBB0_487
	s_add_i32 s6, 0, 0x25ff0
	v_mov_b32_e32 v0, s6
	s_waitcnt vmcnt(0) expcnt(0) lgkmcnt(0)
	ds_read_b32 v2, v0
	s_add_i32 s6, 0, 0x25ff4
	v_mov_b32_e32 v0, s6
	ds_read_b32 v0, v0
	s_waitcnt lgkmcnt(1)
	v_cmp_ne_u32_e32 vcc, 0, v2
	s_cbranch_vccnz .LBB0_455
	s_load_dwordx2 s[10:11], s[52:53], 0x4
	s_add_u32 s6, s28, 0x3e800200
	s_addc_u32 s7, s29, 0
	s_add_u32 s8, s28, 0x3e800400
	s_addc_u32 s9, s29, 0
	s_waitcnt lgkmcnt(0)
	s_mul_i32 s31, s10, s3
	s_add_u32 s10, s28, 0x3e800500
	s_mul_i32 s31, s31, s11
	s_addc_u32 s11, s29, 0
	s_add_u32 s12, s28, 0x3e800600
	s_addc_u32 s13, s29, 0
	s_add_u32 s14, s28, 0x3e800700
	s_addc_u32 s15, s29, 0
	s_add_u32 s16, s28, 0x3e800800
	s_addc_u32 s17, s29, 0
	s_add_u32 s18, s28, 0x3e800900
	s_addc_u32 s19, s29, 0
	s_add_u32 s20, s28, 0x3e800a00
	s_addc_u32 s21, s29, 0
	s_add_u32 s22, s28, 0x3e800b00
	s_addc_u32 s23, s29, 0
	s_add_u32 s24, s28, 0x3e800c00
	s_addc_u32 s25, s29, 0
	s_add_u32 s36, s28, 0x3e800d00
	s_addc_u32 s37, s29, 0
	s_add_u32 s38, s28, 0x3e800e00
	s_addc_u32 s39, s29, 0
	s_add_u32 s40, s28, 0x3e800f00
	s_addc_u32 s41, s29, 0
	s_add_u32 s42, s28, 0x3e801000
	s_addc_u32 s43, s29, 0
	s_add_u32 s44, s28, 0x3e801100
	s_addc_u32 s45, s29, 0
	s_add_u32 s46, s28, 0x3e801200
	s_addc_u32 s47, s29, 0
	s_add_u32 s48, s28, 0x3e801300
	s_addc_u32 s49, s29, 0
	s_mov_b32 s56, 1
	v_mov_b32_e32 v16, 0
	s_branch .LBB0_443

; #define PG8_STAGE(bufoff, gbase, voff) do { _Pragma("unroll") for (int _i = 0; _i < 2; ++_i) \
;         __builtin_amdgcn_global_load_lds((const unsigned*)((const char*)(gbase) + (voff)[_i]), (LAS unsigned*)(lds + (bufoff) + ldsw + _i * 8192), 16, 0, 0); } while (0)
; #define PG8_LDA(dst, b, h) do { _Pragma("unroll") for (int m = 0; m < 4; ++m) _Pragma("unroll") for (int k = 0; k < 2; ++k) dst[m][k] = *(const LAS bf16x8*)(lds + PG8_SA(b, h) + aoff + m * 2048 + k * 1024); } while (0)
; #define PG8_LDB(dst, b, h) do { _Pragma("unroll") for (int n = 0; n < 2; ++n) _Pragma("unroll") for (int k = 0; k < 2; ++k) dst[n][k] = *(const LAS bf16x8*)(lds + PG8_SB(b, h) + boff + n * 2048 + k * 1024); } while (0)
; #define PG8_MMA(ai, bj, At, Bt) do { __builtin_amdgcn_s_setprio(1); _Pragma("unroll") for (int m = 0; m < 4; ++m) _Pragma("unroll") for (int n = 0; n < 2; ++n) _Pragma("unroll") for (int k = 0; k < 2; ++k) \
;         acc[ai][bj][m][n] = __builtin_amdgcn_mfma_f32_16x16x32_bf16(Bt[n][k], At[m][k], acc[ai][bj][m][n], 0, 0, 0); __builtin_amdgcn_s_setprio(0); } while (0)
; #define PG8_WAIT_V(n) asm volatile("s_waitcnt vmcnt(" #n ")" ::: "memory")
; #define PG8_WAIT_L(n) asm volatile("s_waitcnt lgkmcnt(" #n ")" ::: "memory")
; #define PG8_BAR __builtin_amdgcn_s_barrier()
; #define PG8_SCHED __builtin_amdgcn_sched_barrier(0)
; template <class Epi, class Ptrs>
; __device__ __forceinline__ void gemm_phase(LAS unsigned char* lds, const int K, const StaticOrder& S, const Ptrs& P, const Epi& E) {
;     ...
;             const char* a1 = cA + (size_t)(t + 1) * kstep;
;             const char* a2 = last ? nA : cA + (size_t)(t + 2) * kstep; const char* b2 = last ? nB : cB + (size_t)(t + 2) * kstep;
;             const char* a3 = a2 + kstep; const char* b3 = b2 + kstep;
;             PG8_LDB(B0, 0, 0); PG8_SCHED; PG8_LDA(At, 0, 0); PG8_STAGE(PG8_SA(1, 1), a1 + hstep, voffA);
;             PG8_WAIT_L(8); PG8_BAR; PG8_WAIT_L(0); PG8_MMA(0, 0, At, B0); PG8_BAR; PG8_SCHED;
;             PG8_LDB(B1, 0, 1); PG8_STAGE(PG8_SB(0, 0), b2, voffB);
;             PG8_BAR; PG8_WAIT_L(0); PG8_MMA(0, 1, At, B1); PG8_BAR;
;             PG8_LDA(At, 0, 1); PG8_STAGE(PG8_SA(0, 0), a2, voffA);
;             PG8_BAR; PG8_WAIT_L(0); PG8_MMA(1, 0, At, B0); PG8_BAR; PG8_SCHED;
;             PG8_STAGE(PG8_SB(0, 1), b2 + hstep, voffB);
;             PG8_WAIT_V(6); PG8_BAR; PG8_MMA(1, 1, At, B1); PG8_BAR;
.LBB0_522:
	ds_read_b128 v[128:131], v193
	ds_read_b128 v[132:135], v193 offset:1024
	ds_read_b128 v[136:139], v193 offset:2048
	ds_read_b128 v[140:143], v193 offset:3072
	s_add_u32 s22, s20, 0xfff00080
	s_addc_u32 s23, s21, -1
	s_cmp_eq_u32 s46, 60
	s_cselect_b32 s25, s5, s23
	s_cselect_b32 s24, s4, s22
	s_cselect_b32 s23, s15, s13
	s_cselect_b32 s22, s14, s11
	s_add_i32 m0, s17, 0xc000
	ds_read_b128 v[144:147], v194
	ds_read_b128 v[148:151], v194 offset:1024
	ds_read_b128 v[152:155], v194 offset:2048
	ds_read_b128 v[156:159], v194 offset:3072
	ds_read_b128 v[176:179], v194 offset:4096
	ds_read_b128 v[180:183], v194 offset:5120
	ds_read_b128 v[196:199], v194 offset:6144
	ds_read_b128 v[200:203], v194 offset:7168
	global_load_lds_dwordx4 v168, s[20:21]
	s_add_i32 m0, s17, 0xe000
	s_nop 0
	global_load_lds_dwordx4 v170, s[20:21]
	s_waitcnt lgkmcnt(8)
	s_barrier
	s_waitcnt lgkmcnt(0)
	v_mfma_f32_16x16x32_bf16 v[124:127], v[128:131], v[144:147], v[124:127]
	v_mfma_f32_16x16x32_bf16 v[124:127], v[132:135], v[148:151], v[124:127]
	v_mfma_f32_16x16x32_bf16 v[120:123], v[140:143], v[148:151], v[120:123]
	v_mfma_f32_16x16x32_bf16 v[120:123], v[136:139], v[144:147], v[120:123]
	v_mfma_f32_16x16x32_bf16 v[104:107], v[136:139], v[152:155], v[104:107]
	v_mfma_f32_16x16x32_bf16 v[104:107], v[140:143], v[156:159], v[104:107]
	v_mfma_f32_16x16x32_bf16 v[112:115], v[132:135], v[156:159], v[112:115]
	v_mfma_f32_16x16x32_bf16 v[112:115], v[128:131], v[152:155], v[112:115]
	v_mfma_f32_16x16x32_bf16 v[92:95], v[128:131], v[176:179], v[92:95]
	v_mfma_f32_16x16x32_bf16 v[92:95], v[132:135], v[180:183], v[92:95]
	v_mfma_f32_16x16x32_bf16 v[88:91], v[140:143], v[180:183], v[88:91]
	v_mfma_f32_16x16x32_bf16 v[88:91], v[136:139], v[176:179], v[88:91]
	v_mfma_f32_16x16x32_bf16 v[72:75], v[136:139], v[196:199], v[72:75]
	v_mfma_f32_16x16x32_bf16 v[72:75], v[140:143], v[200:203], v[72:75]
	v_mfma_f32_16x16x32_bf16 v[76:79], v[132:135], v[200:203], v[76:79]
	v_mfma_f32_16x16x32_bf16 v[76:79], v[128:131], v[196:199], v[76:79]
	s_barrier
	s_add_i32 s47, s42, s34
	s_add_u32 s90, s22, 0x80
	s_addc_u32 s91, s23, 0
	s_mov_b32 m0, s47
	ds_read_b128 v[204:207], v195
	ds_read_b128 v[208:211], v195 offset:1024
	ds_read_b128 v[212:215], v195 offset:2048
	ds_read_b128 v[216:219], v195 offset:3072
	global_load_lds_dwordx4 v162, s[22:23]
	s_add_i32 m0, s47, 0x2000
	s_nop 0
	global_load_lds_dwordx4 v166, s[22:23]
	s_barrier
	s_waitcnt lgkmcnt(0)
	v_mfma_f32_16x16x32_bf16 v[116:119], v[204:207], v[144:147], v[116:119]
	v_mfma_f32_16x16x32_bf16 v[116:119], v[208:211], v[148:151], v[116:119]
	v_mfma_f32_16x16x32_bf16 v[108:111], v[216:219], v[148:151], v[108:111]
	v_mfma_f32_16x16x32_bf16 v[108:111], v[212:215], v[144:147], v[108:111]
	v_mfma_f32_16x16x32_bf16 v[96:99], v[212:215], v[152:155], v[96:99]
	v_mfma_f32_16x16x32_bf16 v[96:99], v[216:219], v[156:159], v[96:99]
	v_mfma_f32_16x16x32_bf16 v[100:103], v[208:211], v[156:159], v[100:103]
	v_mfma_f32_16x16x32_bf16 v[100:103], v[204:207], v[152:155], v[100:103]
	v_mfma_f32_16x16x32_bf16 v[84:87], v[204:207], v[176:179], v[84:87]
	v_mfma_f32_16x16x32_bf16 v[84:87], v[208:211], v[180:183], v[84:87]
	v_mfma_f32_16x16x32_bf16 v[80:83], v[216:219], v[180:183], v[80:83]
	v_mfma_f32_16x16x32_bf16 v[80:83], v[212:215], v[176:179], v[80:83]
	v_mfma_f32_16x16x32_bf16 v[64:67], v[212:215], v[196:199], v[64:67]
	v_mfma_f32_16x16x32_bf16 v[64:67], v[216:219], v[200:203], v[64:67]
	v_mfma_f32_16x16x32_bf16 v[68:71], v[208:211], v[200:203], v[68:71]
	v_mfma_f32_16x16x32_bf16 v[68:71], v[204:207], v[196:199], v[68:71]
	s_barrier
	s_mov_b32 m0, s17
	s_add_u32 s92, s24, 0x80
	s_addc_u32 s93, s25, 0
	ds_read_b128 v[144:147], v194 offset:16384
	ds_read_b128 v[148:151], v194 offset:17408
	ds_read_b128 v[152:155], v194 offset:18432
	ds_read_b128 v[156:159], v194 offset:19456
	ds_read_b128 v[176:179], v194 offset:20480
	ds_read_b128 v[180:183], v194 offset:21504
	ds_read_b128 v[196:199], v194 offset:22528
	ds_read_b128 v[200:203], v194 offset:23552
	global_load_lds_dwordx4 v160, s[24:25]
	s_mov_b32 m0, s19
	s_nop 0
	global_load_lds_dwordx4 v164, s[24:25]
	s_barrier
	s_waitcnt lgkmcnt(0)
	v_mfma_f32_16x16x32_bf16 v[60:63], v[128:131], v[144:147], v[60:63]
	v_mfma_f32_16x16x32_bf16 v[60:63], v[132:135], v[148:151], v[60:63]
	v_mfma_f32_16x16x32_bf16 v[56:59], v[140:143], v[148:151], v[56:59]
	v_mfma_f32_16x16x32_bf16 v[56:59], v[136:139], v[144:147], v[56:59]
	v_mfma_f32_16x16x32_bf16 v[40:43], v[136:139], v[152:155], v[40:43]
	v_mfma_f32_16x16x32_bf16 v[40:43], v[140:143], v[156:159], v[40:43]
	v_mfma_f32_16x16x32_bf16 v[48:51], v[132:135], v[156:159], v[48:51]
	v_mfma_f32_16x16x32_bf16 v[48:51], v[128:131], v[152:155], v[48:51]
	v_mfma_f32_16x16x32_bf16 v[32:35], v[128:131], v[176:179], v[32:35]
	v_mfma_f32_16x16x32_bf16 v[32:35], v[132:135], v[180:183], v[32:35]
	v_mfma_f32_16x16x32_bf16 v[24:27], v[140:143], v[180:183], v[24:27]
	v_mfma_f32_16x16x32_bf16 v[24:27], v[136:139], v[176:179], v[24:27]
	v_mfma_f32_16x16x32_bf16 v[8:11], v[136:139], v[196:199], v[8:11]
	v_mfma_f32_16x16x32_bf16 v[8:11], v[140:143], v[200:203], v[8:11]
	v_mfma_f32_16x16x32_bf16 v[16:19], v[132:135], v[200:203], v[16:19]
	v_mfma_f32_16x16x32_bf16 v[16:19], v[128:131], v[196:199], v[16:19]
	s_barrier
	s_add_u32 s48, s22, 0x100000
	s_addc_u32 s49, s23, 0
	s_add_i32 s47, s43, s34
	s_mov_b32 m0, s47
	s_nop 0
	global_load_lds_dwordx4 v162, s[48:49]
	s_add_i32 m0, s47, 0x2000
	s_nop 0
	global_load_lds_dwordx4 v166, s[48:49]
	s_waitcnt vmcnt(6)
	s_barrier
; #define PG8_STAGE(bufoff, gbase, voff) do { _Pragma("unroll") for (int _i = 0; _i < 2; ++_i) \
;         __builtin_amdgcn_global_load_lds((const unsigned*)((const char*)(gbase) + (voff)[_i]), (LAS unsigned*)(lds + (bufoff) + ldsw + _i * 8192), 16, 0, 0); } while (0)
; #define PG8_LDA(dst, b, h) do { _Pragma("unroll") for (int m = 0; m < 4; ++m) _Pragma("unroll") for (int k = 0; k < 2; ++k) dst[m][k] = *(const LAS bf16x8*)(lds + PG8_SA(b, h) + aoff + m * 2048 + k * 1024); } while (0)
; #define PG8_LDB(dst, b, h) do { _Pragma("unroll") for (int n = 0; n < 2; ++n) _Pragma("unroll") for (int k = 0; k < 2; ++k) dst[n][k] = *(const LAS bf16x8*)(lds + PG8_SB(b, h) + boff + n * 2048 + k * 1024); } while (0)
; #define PG8_MMA(ai, bj, At, Bt) do { __builtin_amdgcn_s_setprio(1); _Pragma("unroll") for (int m = 0; m < 4; ++m) _Pragma("unroll") for (int n = 0; n < 2; ++n) _Pragma("unroll") for (int k = 0; k < 2; ++k) \
;         acc[ai][bj][m][n] = __builtin_amdgcn_mfma_f32_16x16x32_bf16(Bt[n][k], At[m][k], acc[ai][bj][m][n], 0, 0, 0); __builtin_amdgcn_s_setprio(0); } while (0)
; #define PG8_WAIT_V(n) asm volatile("s_waitcnt vmcnt(" #n ")" ::: "memory")
; #define PG8_WAIT_L(n) asm volatile("s_waitcnt lgkmcnt(" #n ")" ::: "memory")
; #define PG8_BAR __builtin_amdgcn_s_barrier()
; #define PG8_SCHED __builtin_amdgcn_sched_barrier(0)
; template <class Epi, class Ptrs>
; __device__ __forceinline__ void gemm_phase(LAS unsigned char* lds, const int K, const StaticOrder& S, const Ptrs& P, const Epi& E) {
;     ...
;             PG8_WAIT_V(6); PG8_BAR; PG8_MMA(1, 1, At, B1); PG8_BAR;
;             PG8_LDB(B0, 1, 0); PG8_SCHED; PG8_LDA(At, 1, 0); PG8_STAGE(PG8_SA(0, 1), a2 + hstep, voffA);
;             PG8_WAIT_L(8); PG8_BAR; PG8_WAIT_L(0); PG8_MMA(0, 0, At, B0); PG8_BAR; PG8_SCHED;
;             PG8_LDB(B1, 1, 1); PG8_STAGE(PG8_SB(1, 0), b3, voffB);
;             PG8_BAR; PG8_WAIT_L(0); PG8_MMA(0, 1, At, B1); PG8_BAR;
;             PG8_LDA(At, 1, 1); PG8_STAGE(PG8_SA(1, 0), a3, voffA);
;             PG8_BAR; PG8_WAIT_L(0); PG8_MMA(1, 0, At, B0); PG8_BAR; PG8_SCHED;
;             PG8_STAGE(PG8_SB(1, 1), b3 + hstep, voffB);
	v_mfma_f32_16x16x32_bf16 v[52:55], v[204:207], v[144:147], v[52:55]
	v_mfma_f32_16x16x32_bf16 v[52:55], v[208:211], v[148:151], v[52:55]
	v_mfma_f32_16x16x32_bf16 v[44:47], v[216:219], v[148:151], v[44:47]
	v_mfma_f32_16x16x32_bf16 v[44:47], v[212:215], v[144:147], v[44:47]
	v_mfma_f32_16x16x32_bf16 v[28:31], v[212:215], v[152:155], v[28:31]
	v_mfma_f32_16x16x32_bf16 v[28:31], v[216:219], v[156:159], v[28:31]
	v_mfma_f32_16x16x32_bf16 v[36:39], v[208:211], v[156:159], v[36:39]
	v_mfma_f32_16x16x32_bf16 v[36:39], v[204:207], v[152:155], v[36:39]
	v_mfma_f32_16x16x32_bf16 v[20:23], v[204:207], v[176:179], v[20:23]
	v_mfma_f32_16x16x32_bf16 v[20:23], v[208:211], v[180:183], v[20:23]
	v_mfma_f32_16x16x32_bf16 v[12:15], v[216:219], v[180:183], v[12:15]
	v_mfma_f32_16x16x32_bf16 v[12:15], v[212:215], v[176:179], v[12:15]
	v_mfma_f32_16x16x32_bf16 v[0:3], v[212:215], v[196:199], v[0:3]
	v_mfma_f32_16x16x32_bf16 v[0:3], v[216:219], v[200:203], v[0:3]
	v_mfma_f32_16x16x32_bf16 v[4:7], v[208:211], v[200:203], v[4:7]
	v_mfma_f32_16x16x32_bf16 v[4:7], v[204:207], v[196:199], v[4:7]
	s_barrier
	s_add_i32 s47, 0, 0x18000
	ds_read_b128 v[128:131], v252
	ds_read_b128 v[132:135], v252 offset:1024
	ds_read_b128 v[136:139], v252 offset:2048
	ds_read_b128 v[140:143], v252 offset:3072
	s_add_u32 s24, s24, 0x100000
	s_addc_u32 s25, s25, 0
	s_mov_b32 m0, s40
	ds_read_b128 v[144:147], v194 offset:32768
	ds_read_b128 v[148:151], v194 offset:33792
	ds_read_b128 v[152:155], v194 offset:34816
	ds_read_b128 v[156:159], v194 offset:35840
	ds_read_b128 v[176:179], v194 offset:36864
	ds_read_b128 v[180:183], v194 offset:37888
	ds_read_b128 v[196:199], v194 offset:38912
	ds_read_b128 v[200:203], v194 offset:39936
	global_load_lds_dwordx4 v160, s[24:25]
	s_mov_b32 m0, s41
	s_nop 0
	global_load_lds_dwordx4 v164, s[24:25]
	s_waitcnt lgkmcnt(8)
	s_barrier
	s_waitcnt lgkmcnt(0)
	v_mfma_f32_16x16x32_bf16 v[124:127], v[128:131], v[144:147], v[124:127]
	v_mfma_f32_16x16x32_bf16 v[124:127], v[132:135], v[148:151], v[124:127]
	v_mfma_f32_16x16x32_bf16 v[120:123], v[140:143], v[148:151], v[120:123]
	v_mfma_f32_16x16x32_bf16 v[120:123], v[136:139], v[144:147], v[120:123]
	v_mfma_f32_16x16x32_bf16 v[104:107], v[136:139], v[152:155], v[104:107]
	v_mfma_f32_16x16x32_bf16 v[104:107], v[140:143], v[156:159], v[104:107]
	v_mfma_f32_16x16x32_bf16 v[112:115], v[132:135], v[156:159], v[112:115]
	v_mfma_f32_16x16x32_bf16 v[112:115], v[128:131], v[152:155], v[112:115]
	v_mfma_f32_16x16x32_bf16 v[92:95], v[128:131], v[176:179], v[92:95]
	v_mfma_f32_16x16x32_bf16 v[92:95], v[132:135], v[180:183], v[92:95]
	v_mfma_f32_16x16x32_bf16 v[88:91], v[140:143], v[180:183], v[88:91]
	v_mfma_f32_16x16x32_bf16 v[88:91], v[136:139], v[176:179], v[88:91]
	v_mfma_f32_16x16x32_bf16 v[72:75], v[136:139], v[196:199], v[72:75]
	v_mfma_f32_16x16x32_bf16 v[72:75], v[140:143], v[200:203], v[72:75]
	v_mfma_f32_16x16x32_bf16 v[76:79], v[132:135], v[200:203], v[76:79]
	v_mfma_f32_16x16x32_bf16 v[76:79], v[128:131], v[196:199], v[76:79]
	s_barrier
	s_add_i32 s24, 0, 0x1c000
	s_add_i32 s25, s47, s34
	s_mov_b32 m0, s25
	ds_read_b128 v[204:207], v253
	ds_read_b128 v[208:211], v253 offset:1024
	ds_read_b128 v[212:215], v253 offset:2048
	ds_read_b128 v[216:219], v253 offset:3072
	global_load_lds_dwordx4 v162, s[90:91]
	s_add_i32 m0, s25, 0x2000
	s_nop 0
	global_load_lds_dwordx4 v166, s[90:91]
	s_barrier
	s_waitcnt lgkmcnt(0)
	v_mfma_f32_16x16x32_bf16 v[116:119], v[204:207], v[144:147], v[116:119]
	v_mfma_f32_16x16x32_bf16 v[116:119], v[208:211], v[148:151], v[116:119]
	v_mfma_f32_16x16x32_bf16 v[108:111], v[216:219], v[148:151], v[108:111]
	v_mfma_f32_16x16x32_bf16 v[108:111], v[212:215], v[144:147], v[108:111]
	v_mfma_f32_16x16x32_bf16 v[96:99], v[212:215], v[152:155], v[96:99]
	v_mfma_f32_16x16x32_bf16 v[96:99], v[216:219], v[156:159], v[96:99]
	v_mfma_f32_16x16x32_bf16 v[100:103], v[208:211], v[156:159], v[100:103]
	v_mfma_f32_16x16x32_bf16 v[100:103], v[204:207], v[152:155], v[100:103]
	v_mfma_f32_16x16x32_bf16 v[84:87], v[204:207], v[176:179], v[84:87]
	v_mfma_f32_16x16x32_bf16 v[84:87], v[208:211], v[180:183], v[84:87]
	v_mfma_f32_16x16x32_bf16 v[80:83], v[216:219], v[180:183], v[80:83]
	v_mfma_f32_16x16x32_bf16 v[80:83], v[212:215], v[176:179], v[80:83]
	v_mfma_f32_16x16x32_bf16 v[64:67], v[212:215], v[196:199], v[64:67]
	v_mfma_f32_16x16x32_bf16 v[64:67], v[216:219], v[200:203], v[64:67]
	v_mfma_f32_16x16x32_bf16 v[68:71], v[208:211], v[200:203], v[68:71]
	v_mfma_f32_16x16x32_bf16 v[68:71], v[204:207], v[196:199], v[68:71]
	s_barrier
	s_mov_b32 m0, s28
	ds_read_b128 v[144:147], v194 offset:49152
	ds_read_b128 v[148:151], v194 offset:50176
	ds_read_b128 v[152:155], v194 offset:51200
	ds_read_b128 v[156:159], v194 offset:52224
	ds_read_b128 v[176:179], v194 offset:53248
	ds_read_b128 v[180:183], v194 offset:54272
	ds_read_b128 v[196:199], v194 offset:55296
	ds_read_b128 v[200:203], v194 offset:56320
	global_load_lds_dwordx4 v160, s[92:93]
	s_mov_b32 m0, s29
	s_nop 0
	global_load_lds_dwordx4 v164, s[92:93]
	s_barrier
	s_waitcnt lgkmcnt(0)
	v_mfma_f32_16x16x32_bf16 v[60:63], v[128:131], v[144:147], v[60:63]
	v_mfma_f32_16x16x32_bf16 v[60:63], v[132:135], v[148:151], v[60:63]
	v_mfma_f32_16x16x32_bf16 v[56:59], v[140:143], v[148:151], v[56:59]
	v_mfma_f32_16x16x32_bf16 v[56:59], v[136:139], v[144:147], v[56:59]
	v_mfma_f32_16x16x32_bf16 v[40:43], v[136:139], v[152:155], v[40:43]
	v_mfma_f32_16x16x32_bf16 v[40:43], v[140:143], v[156:159], v[40:43]
	v_mfma_f32_16x16x32_bf16 v[48:51], v[132:135], v[156:159], v[48:51]
	v_mfma_f32_16x16x32_bf16 v[48:51], v[128:131], v[152:155], v[48:51]
	v_mfma_f32_16x16x32_bf16 v[32:35], v[128:131], v[176:179], v[32:35]
	v_mfma_f32_16x16x32_bf16 v[32:35], v[132:135], v[180:183], v[32:35]
	v_mfma_f32_16x16x32_bf16 v[24:27], v[140:143], v[180:183], v[24:27]
	v_mfma_f32_16x16x32_bf16 v[24:27], v[136:139], v[176:179], v[24:27]
	v_mfma_f32_16x16x32_bf16 v[8:11], v[136:139], v[196:199], v[8:11]
	v_mfma_f32_16x16x32_bf16 v[8:11], v[140:143], v[200:203], v[8:11]
	v_mfma_f32_16x16x32_bf16 v[16:19], v[132:135], v[200:203], v[16:19]
	v_mfma_f32_16x16x32_bf16 v[16:19], v[128:131], v[196:199], v[16:19]
	s_barrier
; __device__ __forceinline__ float bf_lo(unsigned w) { return __uint_as_float(w << 16); }
; __device__ __forceinline__ float bf_hi(unsigned w) { return __uint_as_float(w & 0xffff0000u); }
; #define PG8_STAGE(bufoff, gbase, voff) do { _Pragma("unroll") for (int _i = 0; _i < 2; ++_i) \
;         __builtin_amdgcn_global_load_lds((const unsigned*)((const char*)(gbase) + (voff)[_i]), (LAS unsigned*)(lds + (bufoff) + ldsw + _i * 8192), 16, 0, 0); } while (0)
; #define PG8_MMA(ai, bj, At, Bt) do { __builtin_amdgcn_s_setprio(1); _Pragma("unroll") for (int m = 0; m < 4; ++m) _Pragma("unroll") for (int n = 0; n < 2; ++n) _Pragma("unroll") for (int k = 0; k < 2; ++k) \
;         acc[ai][bj][m][n] = __builtin_amdgcn_mfma_f32_16x16x32_bf16(Bt[n][k], At[m][k], acc[ai][bj][m][n], 0, 0, 0); __builtin_amdgcn_s_setprio(0); } while (0)
; #define PG8_BAR __builtin_amdgcn_s_barrier()
; template <class Epi, class Ptrs>
; __device__ __forceinline__ void gemm_phase(LAS unsigned char* lds, const int K, const StaticOrder& S, const Ptrs& P, const Epi& E) {
;     ...
;             PG8_STAGE(PG8_SB(1, 1), b3 + hstep, voffB);
;             PG8_WAIT_V(6); PG8_BAR; PG8_MMA(1, 1, At, B1); PG8_BAR;
;     __device__ __forceinline__ void operator()(const f32x4 (&acc)[2][2][4][2], const Unit& u, int ui, int wr, int wc, int fr, int fq) const {
;         const int rl0 = wr * 64 + fr, col0 = u.pn * 256 + wc * 32 + 8 * fq;
;         u32x4 xv[2][4][2];
; #pragma unroll
;         for (int ai = 0; ai < 2; ++ai)
; #pragma unroll
;             for (int m = 0; m < 4; ++m)
; #pragma unroll
;                 for (int bj = 0; bj < 2; ++bj) xv[ai][m][bj] = *(const u32x4*)(xb + (size_t)(u.pm * 256 + rl0 + ai * 128 + m * 16) * DM + col0 + bj * 128);
; #pragma unroll
;         for (int ai = 0; ai < 2; ++ai)
; #pragma unroll
;             for (int m = 0; m < 4; ++m) { const int rl = rl0 + ai * 128 + m * 16; float* rowp = out + (size_t)(u.pm * 256 + rl) * DM + col0;
;                 const float r2 = tab[ui * 256 + rl];
; #pragma unroll
;                 for (int bj = 0; bj < 2; ++bj) { const u32x4 x = xv[ai][m][bj];
;                     const f32x4 x0 = {bf_lo(x.x), bf_hi(x.x), bf_lo(x.y), bf_hi(x.y)}, x1 = {bf_lo(x.z), bf_hi(x.z), bf_lo(x.w), bf_hi(x.w)};
;                     *(f32x4*)(rowp + bj * 128) = acc[ai][bj][m][0] * r2 + x0; *(f32x4*)(rowp + bj * 128 + 4) = acc[ai][bj][m][1] * r2 + x1; } }
	s_add_u32 s22, s22, 0x100080
	s_addc_u32 s23, s23, 0
	s_add_i32 s24, s24, s34
	s_mov_b32 m0, s24
	s_nop 0
	global_load_lds_dwordx4 v162, s[22:23]
	s_add_i32 m0, s24, 0x2000
	s_nop 0
	global_load_lds_dwordx4 v166, s[22:23]
	s_waitcnt vmcnt(6)
	s_barrier
	v_mfma_f32_16x16x32_bf16 v[52:55], v[204:207], v[144:147], v[52:55]
	v_mfma_f32_16x16x32_bf16 v[52:55], v[208:211], v[148:151], v[52:55]
	v_mfma_f32_16x16x32_bf16 v[44:47], v[216:219], v[148:151], v[44:47]
	v_mfma_f32_16x16x32_bf16 v[44:47], v[212:215], v[144:147], v[44:47]
	v_mfma_f32_16x16x32_bf16 v[28:31], v[212:215], v[152:155], v[28:31]
	v_mfma_f32_16x16x32_bf16 v[28:31], v[216:219], v[156:159], v[28:31]
	v_mfma_f32_16x16x32_bf16 v[36:39], v[208:211], v[156:159], v[36:39]
	v_mfma_f32_16x16x32_bf16 v[36:39], v[204:207], v[152:155], v[36:39]
	v_mfma_f32_16x16x32_bf16 v[20:23], v[204:207], v[176:179], v[20:23]
	v_mfma_f32_16x16x32_bf16 v[20:23], v[208:211], v[180:183], v[20:23]
	v_mfma_f32_16x16x32_bf16 v[12:15], v[216:219], v[180:183], v[12:15]
	v_mfma_f32_16x16x32_bf16 v[12:15], v[212:215], v[176:179], v[12:15]
	v_mfma_f32_16x16x32_bf16 v[0:3], v[212:215], v[196:199], v[0:3]
	v_mfma_f32_16x16x32_bf16 v[0:3], v[216:219], v[200:203], v[0:3]
	v_mfma_f32_16x16x32_bf16 v[4:7], v[208:211], v[200:203], v[4:7]
	v_mfma_f32_16x16x32_bf16 v[4:7], v[204:207], v[196:199], v[4:7]
	s_barrier
	s_add_i32 s46, s46, 2
	s_add_u32 s20, s20, 0x100
	s_addc_u32 s21, s21, 0
	s_add_u32 s11, s11, 0x100
	s_addc_u32 s13, s13, 0
	s_cmp_gt_u32 s46, 61
	s_cbranch_scc0 .LBB0_522
	s_cmpk_lt_u32 s33, 0x100
	s_cbranch_scc0 .Ltsync_a3
	s_barrier
.Ltsync_a3:
	s_lshl_b32 s11, s18, 8
	v_lshl_or_b32 v128, s16, 8, v191
	v_add_u32_e32 v130, s11, v186
	v_ashrrev_i32_e32 v129, 31, v128
	v_ashrrev_i32_e32 v131, 31, v130
	v_lshl_add_u64 v[132:133], v[128:129], 1, s[6:7]
	v_lshlrev_b64 v[134:135], 11, v[130:131]
	v_lshl_add_u64 v[134:135], v[132:133], 0, v[134:135]
	global_load_dwordx4 v[198:201], v[134:135], off
	global_load_dwordx4 v[202:205], v[134:135], off offset:256
	v_or_b32_e32 v134, 16, v130
	v_ashrrev_i32_e32 v135, 31, v134
	v_lshlrev_b64 v[134:135], 11, v[134:135]
	v_lshl_add_u64 v[134:135], v[132:133], 0, v[134:135]
	global_load_dwordx4 v[206:209], v[134:135], off
	global_load_dwordx4 v[210:213], v[134:135], off offset:256
	v_or_b32_e32 v136, 32, v130
	v_ashrrev_i32_e32 v137, 31, v136
	v_or_b32_e32 v138, 48, v130
	v_add_u32_e32 v184, 0x80, v130
	v_add_u32_e32 v182, 0x90, v130
	v_add_u32_e32 v180, 0xa0, v130
	v_add_u32_e32 v178, 0xb0, v130
	v_lshlrev_b64 v[176:177], 2, v[128:129]
	v_lshlrev_b64 v[128:129], 12, v[130:131]
	v_lshlrev_b64 v[130:131], 11, v[136:137]
	v_lshl_add_u64 v[130:131], v[132:133], 0, v[130:131]
	global_load_dwordx4 v[214:217], v[130:131], off
	v_ashrrev_i32_e32 v139, 31, v138
	v_ashrrev_i32_e32 v185, 31, v184
	v_ashrrev_i32_e32 v183, 31, v182
	v_ashrrev_i32_e32 v181, 31, v180
	v_ashrrev_i32_e32 v179, 31, v178
	v_lshlrev_b64 v[134:135], 11, v[138:139]
	v_lshlrev_b64 v[136:137], 11, v[184:185]
	v_lshlrev_b64 v[138:139], 11, v[182:183]
	v_lshl_add_u32 v196, s45, 10, v192
	v_lshlrev_b64 v[140:141], 11, v[180:181]
	v_lshlrev_b64 v[142:143], 11, v[178:179]
	v_lshl_add_u64 v[128:129], s[26:27], 0, v[128:129]
	v_lshl_add_u64 v[134:135], v[132:133], 0, v[134:135]
	v_lshl_add_u64 v[136:137], v[132:133], 0, v[136:137]
	v_lshl_add_u64 v[138:139], v[132:133], 0, v[138:139]
	ds_read2_b32 v[230:231], v196 offset1:16
	v_lshl_add_u64 v[234:235], v[132:133], 0, v[140:141]
	v_lshl_add_u64 v[236:237], v[132:133], 0, v[142:143]
	v_lshl_add_u64 v[238:239], v[128:129], 0, v[176:177]
	global_load_dwordx4 v[218:221], v[130:131], off offset:256
	global_load_dwordx4 v[222:225], v[134:135], off
	global_load_dwordx4 v[226:229], v[134:135], off offset:256
	global_load_dwordx4 v[156:159], v[136:137], off
	global_load_dwordx4 v[152:155], v[136:137], off offset:256
	global_load_dwordx4 v[148:151], v[138:139], off
	global_load_dwordx4 v[144:147], v[138:139], off offset:256
	global_load_dwordx4 v[140:143], v[234:235], off
	s_nop 0
	global_load_dwordx4 v[136:139], v[234:235], off offset:256
	global_load_dwordx4 v[132:135], v[236:237], off
	global_load_dwordx4 v[128:131], v[236:237], off offset:256
	v_add_u32_e32 v232, s11, v188
	v_ashrrev_i32_e32 v233, 31, v232
	s_and_b64 vcc, exec, s[0:1]
	s_mov_b32 s16, s10
	s_mov_b32 s18, s12
	s_mov_b64 s[20:21], s[4:5]
	s_mov_b64 s[22:23], s[14:15]
	s_mov_b32 s45, s44
	s_waitcnt vmcnt(0)
	v_lshlrev_b32_e32 v234, 16, v198
	v_and_b32_e32 v235, 0xffff0000, v198
	v_lshlrev_b32_e32 v198, 16, v199
	v_and_b32_e32 v199, 0xffff0000, v199
	v_lshlrev_b32_e32 v242, 16, v204
	v_and_b32_e32 v243, 0xffff0000, v204
	v_lshlrev_b32_e32 v236, 16, v200
	v_and_b32_e32 v237, 0xffff0000, v200
	v_lshlrev_b32_e32 v200, 16, v201
	v_and_b32_e32 v201, 0xffff0000, v201
	v_lshlrev_b32_e32 v240, 16, v202
	v_and_b32_e32 v241, 0xffff0000, v202
	v_lshlrev_b32_e32 v202, 16, v203
	v_and_b32_e32 v203, 0xffff0000, v203
	v_lshlrev_b32_e32 v204, 16, v205
	v_and_b32_e32 v205, 0xffff0000, v205
	s_waitcnt lgkmcnt(0)
; __device__ __forceinline__ float bf_lo(unsigned w) { return __uint_as_float(w << 16); }
; __device__ __forceinline__ float bf_hi(unsigned w) { return __uint_as_float(w & 0xffff0000u); }
;     __device__ __forceinline__ void operator()(const f32x4 (&acc)[2][2][4][2], const Unit& u, int ui, int wr, int wc, int fr, int fq) const {
;     ...
;         for (int ai = 0; ai < 2; ++ai)
; #pragma unroll
;             for (int m = 0; m < 4; ++m) { const int rl = rl0 + ai * 128 + m * 16; float* rowp = out + (size_t)(u.pm * 256 + rl) * DM + col0;
;                 const float r2 = tab[ui * 256 + rl];
; #pragma unroll
;                 for (int bj = 0; bj < 2; ++bj) { const u32x4 x = xv[ai][m][bj];
;                     const f32x4 x0 = {bf_lo(x.x), bf_hi(x.x), bf_lo(x.y), bf_hi(x.y)}, x1 = {bf_lo(x.z), bf_hi(x.z), bf_lo(x.w), bf_hi(x.w)};
;                     *(f32x4*)(rowp + bj * 128) = acc[ai][bj][m][0] * r2 + x0; *(f32x4*)(rowp + bj * 128 + 4) = acc[ai][bj][m][1] * r2 + x1; } }
	v_pk_fma_f32 v[126:127], v[126:127], v[230:231], v[198:199] op_sel_hi:[1,0,1]
	v_pk_fma_f32 v[124:125], v[124:125], v[230:231], v[234:235] op_sel_hi:[1,0,1]
	v_pk_fma_f32 v[108:109], v[108:109], v[230:231], v[242:243] op_sel_hi:[1,0,1]
	v_pk_fma_f32 v[122:123], v[122:123], v[230:231], v[200:201] op_sel_hi:[1,0,1]
	v_pk_fma_f32 v[120:121], v[120:121], v[230:231], v[236:237] op_sel_hi:[1,0,1]
	v_pk_fma_f32 v[118:119], v[118:119], v[230:231], v[202:203] op_sel_hi:[1,0,1]
	v_pk_fma_f32 v[116:117], v[116:117], v[230:231], v[240:241] op_sel_hi:[1,0,1]
	v_pk_fma_f32 v[110:111], v[110:111], v[230:231], v[204:205] op_sel_hi:[1,0,1]
	global_store_dwordx4 v[238:239], v[124:127], off
	global_store_dwordx4 v[238:239], v[120:123], off offset:16
	global_store_dwordx4 v[238:239], v[116:119], off offset:512
	global_store_dwordx4 v[238:239], v[108:111], off offset:528
	v_mov_b32_e32 v122, v231
	v_lshlrev_b32_e32 v118, 16, v208
	v_lshlrev_b64 v[108:109], 12, v[232:233]
	v_lshl_add_u64 v[108:109], s[26:27], 0, v[108:109]
	v_lshl_add_u64 v[116:117], v[108:109], 0, v[176:177]
	v_lshlrev_b32_e32 v108, 16, v206
	v_and_b32_e32 v109, 0xffff0000, v206
	v_lshlrev_b32_e32 v110, 16, v207
	v_and_b32_e32 v111, 0xffff0000, v207
	v_pk_fma_f32 v[110:111], v[114:115], v[122:123], v[110:111] op_sel_hi:[1,0,1]
	v_pk_fma_f32 v[108:109], v[112:113], v[122:123], v[108:109] op_sel_hi:[1,0,1]
	global_store_dwordx4 v[116:117], v[108:111], off
	v_and_b32_e32 v119, 0xffff0000, v208
	v_lshlrev_b32_e32 v120, 16, v209
	v_lshlrev_b32_e32 v108, 16, v212
	v_and_b32_e32 v109, 0xffff0000, v212
	v_lshlrev_b32_e32 v110, 16, v213
	v_and_b32_e32 v111, 0xffff0000, v213
	v_pk_fma_f32 v[98:99], v[98:99], v[122:123], v[110:111] op_sel_hi:[1,0,1]
	v_pk_fma_f32 v[96:97], v[96:97], v[122:123], v[108:109] op_sel_hi:[1,0,1]
	v_and_b32_e32 v121, 0xffff0000, v209
	global_store_dwordx4 v[116:117], v[96:99], off offset:528
	ds_read2_b32 v[98:99], v196 offset0:32 offset1:48
	v_pk_fma_f32 v[106:107], v[106:107], v[122:123], v[120:121] op_sel_hi:[1,0,1]
	v_pk_fma_f32 v[104:105], v[104:105], v[122:123], v[118:119] op_sel_hi:[1,0,1]
	v_add_u32_e32 v96, s11, v189
	global_store_dwordx4 v[116:117], v[104:107], off offset:16
	v_ashrrev_i32_e32 v97, 31, v96
	v_lshlrev_b64 v[96:97], 12, v[96:97]
	v_lshlrev_b32_e32 v104, 16, v210
	v_and_b32_e32 v105, 0xffff0000, v210
	v_lshlrev_b32_e32 v106, 16, v211
	v_and_b32_e32 v107, 0xffff0000, v211
	v_pk_fma_f32 v[102:103], v[102:103], v[122:123], v[106:107] op_sel_hi:[1,0,1]
	v_pk_fma_f32 v[100:101], v[100:101], v[122:123], v[104:105] op_sel_hi:[1,0,1]
	global_store_dwordx4 v[116:117], v[100:103], off offset:512
	v_lshl_add_u64 v[96:97], s[26:27], 0, v[96:97]
	v_lshl_add_u64 v[96:97], v[96:97], 0, v[176:177]
	v_lshlrev_b32_e32 v100, 16, v214
	v_and_b32_e32 v101, 0xffff0000, v214
	v_lshlrev_b32_e32 v102, 16, v215
	v_and_b32_e32 v103, 0xffff0000, v215
	s_waitcnt lgkmcnt(0)
	v_pk_fma_f32 v[94:95], v[94:95], v[98:99], v[102:103] op_sel_hi:[1,0,1]
	v_pk_fma_f32 v[92:93], v[92:93], v[98:99], v[100:101] op_sel_hi:[1,0,1]
	global_store_dwordx4 v[96:97], v[92:95], off
	v_lshlrev_b32_e32 v104, 16, v216
	v_and_b32_e32 v105, 0xffff0000, v216
	v_lshlrev_b32_e32 v92, 16, v220
	v_and_b32_e32 v93, 0xffff0000, v220
	v_lshlrev_b32_e32 v94, 16, v221
	v_and_b32_e32 v95, 0xffff0000, v221
	v_lshlrev_b32_e32 v106, 16, v217
	v_and_b32_e32 v107, 0xffff0000, v217
	v_pk_fma_f32 v[82:83], v[82:83], v[98:99], v[94:95] op_sel_hi:[1,0,1]
	v_pk_fma_f32 v[80:81], v[80:81], v[98:99], v[92:93] op_sel_hi:[1,0,1]
	v_pk_fma_f32 v[90:91], v[90:91], v[98:99], v[106:107] op_sel_hi:[1,0,1]
	v_pk_fma_f32 v[88:89], v[88:89], v[98:99], v[104:105] op_sel_hi:[1,0,1]
	global_store_dwordx4 v[96:97], v[80:83], off offset:528
	global_store_dwordx4 v[96:97], v[88:91], off offset:16
	s_nop 0
	v_add_u32_e32 v80, s11, v190
	v_lshlrev_b32_e32 v88, 16, v218
	v_and_b32_e32 v89, 0xffff0000, v218
	v_lshlrev_b32_e32 v90, 16, v219
	v_and_b32_e32 v91, 0xffff0000, v219
	v_ashrrev_i32_e32 v81, 31, v80
	v_pk_fma_f32 v[86:87], v[86:87], v[98:99], v[90:91] op_sel_hi:[1,0,1]
	v_pk_fma_f32 v[84:85], v[84:85], v[98:99], v[88:89] op_sel_hi:[1,0,1]
	v_lshlrev_b64 v[80:81], 12, v[80:81]
	global_store_dwordx4 v[96:97], v[84:87], off offset:512
	v_lshl_add_u64 v[80:81], s[26:27], 0, v[80:81]
	v_lshlrev_b32_e32 v82, 16, v222
	v_and_b32_e32 v83, 0xffff0000, v222
	v_lshlrev_b32_e32 v84, 16, v223
	v_and_b32_e32 v85, 0xffff0000, v223
	v_mov_b32_e32 v90, v99
	v_lshl_add_u64 v[80:81], v[80:81], 0, v[176:177]
	v_pk_fma_f32 v[78:79], v[78:79], v[90:91], v[84:85] op_sel_hi:[1,0,1]
	v_pk_fma_f32 v[76:77], v[76:77], v[90:91], v[82:83] op_sel_hi:[1,0,1]
	global_store_dwordx4 v[80:81], v[76:79], off
	v_lshlrev_b32_e32 v86, 16, v224
	v_and_b32_e32 v87, 0xffff0000, v224
	v_lshlrev_b32_e32 v76, 16, v228
	v_and_b32_e32 v77, 0xffff0000, v228
	v_lshlrev_b32_e32 v78, 16, v229
	v_and_b32_e32 v79, 0xffff0000, v229
	v_pk_fma_f32 v[66:67], v[66:67], v[90:91], v[78:79] op_sel_hi:[1,0,1]
	v_pk_fma_f32 v[64:65], v[64:65], v[90:91], v[76:77] op_sel_hi:[1,0,1]
	v_lshlrev_b32_e32 v88, 16, v225
	v_and_b32_e32 v89, 0xffff0000, v225
	global_store_dwordx4 v[80:81], v[64:67], off offset:528
	ds_read2_b32 v[66:67], v196 offset0:128 offset1:144
	v_pk_fma_f32 v[74:75], v[74:75], v[90:91], v[88:89] op_sel_hi:[1,0,1]
	v_pk_fma_f32 v[72:73], v[72:73], v[90:91], v[86:87] op_sel_hi:[1,0,1]
	global_store_dwordx4 v[80:81], v[72:75], off offset:16
	v_lshlrev_b64 v[64:65], 12, v[184:185]
	v_lshl_add_u64 v[64:65], s[26:27], 0, v[64:65]
	v_lshlrev_b32_e32 v72, 16, v226
	v_and_b32_e32 v73, 0xffff0000, v226
	v_lshlrev_b32_e32 v74, 16, v227
	v_and_b32_e32 v75, 0xffff0000, v227
	v_pk_fma_f32 v[70:71], v[70:71], v[90:91], v[74:75] op_sel_hi:[1,0,1]
	v_pk_fma_f32 v[68:69], v[68:69], v[90:91], v[72:73] op_sel_hi:[1,0,1]
	global_store_dwordx4 v[80:81], v[68:71], off offset:512
	v_lshl_add_u64 v[64:65], v[64:65], 0, v[176:177]
	v_lshlrev_b32_e32 v72, 16, v158
	v_lshlrev_b32_e32 v68, 16, v156
	v_and_b32_e32 v69, 0xffff0000, v156
	v_lshlrev_b32_e32 v70, 16, v157
	v_and_b32_e32 v71, 0xffff0000, v157
	v_and_b32_e32 v73, 0xffff0000, v158
	v_lshlrev_b32_e32 v74, 16, v159
	v_and_b32_e32 v75, 0xffff0000, v159
	s_waitcnt lgkmcnt(0)
; __device__ __forceinline__ float bf_lo(unsigned w) { return __uint_as_float(w << 16); }
; __device__ __forceinline__ float bf_hi(unsigned w) { return __uint_as_float(w & 0xffff0000u); }
;     __device__ __forceinline__ void operator()(const f32x4 (&acc)[2][2][4][2], const Unit& u, int ui, int wr, int wc, int fr, int fq) const {
;     ...
;         for (int ai = 0; ai < 2; ++ai)
; #pragma unroll
;             for (int m = 0; m < 4; ++m) { const int rl = rl0 + ai * 128 + m * 16; float* rowp = out + (size_t)(u.pm * 256 + rl) * DM + col0;
;                 const float r2 = tab[ui * 256 + rl];
; #pragma unroll
;                 for (int bj = 0; bj < 2; ++bj) { const u32x4 x = xv[ai][m][bj];
;                     const f32x4 x0 = {bf_lo(x.x), bf_hi(x.x), bf_lo(x.y), bf_hi(x.y)}, x1 = {bf_lo(x.z), bf_hi(x.z), bf_lo(x.w), bf_hi(x.w)};
;                     *(f32x4*)(rowp + bj * 128) = acc[ai][bj][m][0] * r2 + x0; *(f32x4*)(rowp + bj * 128 + 4) = acc[ai][bj][m][1] * r2 + x1; } }
	v_pk_fma_f32 v[62:63], v[62:63], v[66:67], v[70:71] op_sel_hi:[1,0,1]
	v_pk_fma_f32 v[60:61], v[60:61], v[66:67], v[68:69] op_sel_hi:[1,0,1]
	global_store_dwordx4 v[64:65], v[60:63], off
	v_pk_fma_f32 v[58:59], v[58:59], v[66:67], v[74:75] op_sel_hi:[1,0,1]
	v_pk_fma_f32 v[56:57], v[56:57], v[66:67], v[72:73] op_sel_hi:[1,0,1]
	v_lshlrev_b32_e32 v60, 16, v154
	v_and_b32_e32 v61, 0xffff0000, v154
	v_lshlrev_b32_e32 v62, 16, v155
	v_and_b32_e32 v63, 0xffff0000, v155
	global_store_dwordx4 v[64:65], v[56:59], off offset:16
	v_pk_fma_f32 v[46:47], v[46:47], v[66:67], v[62:63] op_sel_hi:[1,0,1]
	v_pk_fma_f32 v[44:45], v[44:45], v[66:67], v[60:61] op_sel_hi:[1,0,1]
	v_lshlrev_b32_e32 v56, 16, v152
	v_and_b32_e32 v57, 0xffff0000, v152
	v_lshlrev_b32_e32 v58, 16, v153
	v_and_b32_e32 v59, 0xffff0000, v153
	v_pk_fma_f32 v[54:55], v[54:55], v[66:67], v[58:59] op_sel_hi:[1,0,1]
	v_pk_fma_f32 v[52:53], v[52:53], v[66:67], v[56:57] op_sel_hi:[1,0,1]
	global_store_dwordx4 v[64:65], v[44:47], off offset:528
	global_store_dwordx4 v[64:65], v[52:55], off offset:512
	v_lshlrev_b32_e32 v56, 16, v151
	v_lshlrev_b64 v[44:45], 12, v[182:183]
	v_lshl_add_u64 v[44:45], s[26:27], 0, v[44:45]
	v_lshlrev_b32_e32 v54, 16, v150
	v_and_b32_e32 v55, 0xffff0000, v150
	v_and_b32_e32 v57, 0xffff0000, v151
	v_mov_b32_e32 v58, v67
	v_lshl_add_u64 v[52:53], v[44:45], 0, v[176:177]
	v_pk_fma_f32 v[42:43], v[42:43], v[58:59], v[56:57] op_sel_hi:[1,0,1]
	v_pk_fma_f32 v[40:41], v[40:41], v[58:59], v[54:55] op_sel_hi:[1,0,1]
	v_lshlrev_b32_e32 v44, 16, v148
	v_and_b32_e32 v45, 0xffff0000, v148
	v_lshlrev_b32_e32 v46, 16, v149
	v_and_b32_e32 v47, 0xffff0000, v149
	global_store_dwordx4 v[52:53], v[40:43], off offset:16
	v_pk_fma_f32 v[46:47], v[50:51], v[58:59], v[46:47] op_sel_hi:[1,0,1]
	v_pk_fma_f32 v[44:45], v[48:49], v[58:59], v[44:45] op_sel_hi:[1,0,1]
	v_lshlrev_b32_e32 v40, 16, v144
	v_and_b32_e32 v41, 0xffff0000, v144
	v_lshlrev_b32_e32 v42, 16, v145
	v_and_b32_e32 v43, 0xffff0000, v145
	v_pk_fma_f32 v[38:39], v[38:39], v[58:59], v[42:43] op_sel_hi:[1,0,1]
	v_pk_fma_f32 v[36:37], v[36:37], v[58:59], v[40:41] op_sel_hi:[1,0,1]
	global_store_dwordx4 v[52:53], v[44:47], off
	global_store_dwordx4 v[52:53], v[36:39], off offset:512
	ds_read2_b32 v[38:39], v196 offset0:160 offset1:176
	v_lshlrev_b32_e32 v44, 16, v146
	v_and_b32_e32 v45, 0xffff0000, v146
	v_lshlrev_b32_e32 v46, 16, v147
	v_and_b32_e32 v47, 0xffff0000, v147
	v_pk_fma_f32 v[30:31], v[30:31], v[58:59], v[46:47] op_sel_hi:[1,0,1]
	v_pk_fma_f32 v[28:29], v[28:29], v[58:59], v[44:45] op_sel_hi:[1,0,1]
	global_store_dwordx4 v[52:53], v[28:31], off offset:528
	v_lshlrev_b32_e32 v40, 16, v142
	v_and_b32_e32 v41, 0xffff0000, v142
	v_lshlrev_b64 v[28:29], 12, v[180:181]
	v_lshl_add_u64 v[28:29], s[26:27], 0, v[28:29]
	v_lshl_add_u64 v[36:37], v[28:29], 0, v[176:177]
	v_lshlrev_b32_e32 v28, 16, v140
	v_and_b32_e32 v29, 0xffff0000, v140
	v_lshlrev_b32_e32 v30, 16, v141
	v_and_b32_e32 v31, 0xffff0000, v141
	s_waitcnt lgkmcnt(0)
	v_pk_fma_f32 v[30:31], v[34:35], v[38:39], v[30:31] op_sel_hi:[1,0,1]
	v_pk_fma_f32 v[28:29], v[32:33], v[38:39], v[28:29] op_sel_hi:[1,0,1]
	v_lshlrev_b32_e32 v42, 16, v143
	v_and_b32_e32 v43, 0xffff0000, v143
	global_store_dwordx4 v[36:37], v[28:31], off
	v_pk_fma_f32 v[26:27], v[26:27], v[38:39], v[42:43] op_sel_hi:[1,0,1]
	v_pk_fma_f32 v[24:25], v[24:25], v[38:39], v[40:41] op_sel_hi:[1,0,1]
	v_lshlrev_b32_e32 v28, 16, v138
	v_and_b32_e32 v29, 0xffff0000, v138
	v_lshlrev_b32_e32 v30, 16, v139
	v_and_b32_e32 v31, 0xffff0000, v139
	v_pk_fma_f32 v[14:15], v[14:15], v[38:39], v[30:31] op_sel_hi:[1,0,1]
	v_pk_fma_f32 v[12:13], v[12:13], v[38:39], v[28:29] op_sel_hi:[1,0,1]
	global_store_dwordx4 v[36:37], v[24:27], off offset:16
	global_store_dwordx4 v[36:37], v[12:15], off offset:528
	s_nop 0
	v_lshlrev_b32_e32 v24, 16, v136
	v_and_b32_e32 v25, 0xffff0000, v136
	v_lshlrev_b32_e32 v26, 16, v137
	v_and_b32_e32 v27, 0xffff0000, v137
	v_lshlrev_b64 v[12:13], 12, v[178:179]
	v_pk_fma_f32 v[22:23], v[22:23], v[38:39], v[26:27] op_sel_hi:[1,0,1]
	v_pk_fma_f32 v[20:21], v[20:21], v[38:39], v[24:25] op_sel_hi:[1,0,1]
	v_lshl_add_u64 v[12:13], s[26:27], 0, v[12:13]
	global_store_dwordx4 v[36:37], v[20:23], off offset:512
	v_lshlrev_b32_e32 v14, 16, v133
	v_and_b32_e32 v15, 0xffff0000, v133
	v_lshl_add_u64 v[20:21], v[12:13], 0, v[176:177]
	v_lshlrev_b32_e32 v12, 16, v132
	v_and_b32_e32 v13, 0xffff0000, v132
	v_lshlrev_b32_e32 v22, 16, v134
	v_and_b32_e32 v23, 0xffff0000, v134
	v_lshlrev_b32_e32 v24, 16, v135
	v_and_b32_e32 v25, 0xffff0000, v135
	v_mov_b32_e32 v26, v39
	v_pk_fma_f32 v[14:15], v[18:19], v[26:27], v[14:15] op_sel_hi:[1,0,1]
	v_pk_fma_f32 v[12:13], v[16:17], v[26:27], v[12:13] op_sel_hi:[1,0,1]
	v_pk_fma_f32 v[10:11], v[10:11], v[26:27], v[24:25] op_sel_hi:[1,0,1]
	v_pk_fma_f32 v[8:9], v[8:9], v[26:27], v[22:23] op_sel_hi:[1,0,1]
	global_store_dwordx4 v[20:21], v[12:15], off
	global_store_dwordx4 v[20:21], v[8:11], off offset:16
	s_nop 0
	v_lshlrev_b32_e32 v12, 16, v130
	v_lshlrev_b32_e32 v8, 16, v128
	v_and_b32_e32 v9, 0xffff0000, v128
	v_lshlrev_b32_e32 v10, 16, v129
	v_and_b32_e32 v11, 0xffff0000, v129
	v_and_b32_e32 v13, 0xffff0000, v130
	v_lshlrev_b32_e32 v14, 16, v131
	v_and_b32_e32 v15, 0xffff0000, v131
	v_pk_fma_f32 v[6:7], v[6:7], v[26:27], v[10:11] op_sel_hi:[1,0,1]
	v_pk_fma_f32 v[4:5], v[4:5], v[26:27], v[8:9] op_sel_hi:[1,0,1]
	v_pk_fma_f32 v[2:3], v[2:3], v[26:27], v[14:15] op_sel_hi:[1,0,1]
	v_pk_fma_f32 v[0:1], v[0:1], v[26:27], v[12:13] op_sel_hi:[1,0,1]
	global_store_dwordx4 v[20:21], v[4:7], off offset:512
	global_store_dwordx4 v[20:21], v[0:3], off offset:528
	s_cbranch_vccnz .Ltsync_x3
	s_cmpk_lt_u32 s33, 0x100
	s_cbranch_scc1 .LBB0_517
	s_barrier
	s_branch .LBB0_517
.Ltsync_x3:
	s_waitcnt vmcnt(0)
	s_setprio 0
	s_cmpk_gt_u32 s33, 0xff
	s_cbranch_scc1 .LBB0_526
